# gla_prep rewritten by hand: 16-byte tile loads into LDS, all 512 threads in logsig/cumsum (two token halves combined through LDS), coalesced dwordx4 stores for q~/k~/kdT/vT; rw_prep records stored [fi
# speedup vs baseline: 1.1976x; 1.0325x over previous
; DEVINL float bf2f(u16 h) { return __uint_as_float(((unsigned)h) << 16); }
; DEVINL int otid() { int t = threadIdx.x; asm volatile("" : "+v"(t)); return t; }
; DEVINL void gla_prep_unit(const Params& p, int unit) {
;   const int h = unit & 3, c = (unit >> 2) & 63, b = unit >> 8;
;   char* ws = p.ws;
;   const u16* cols = (const u16*)(ws + O_COLS);
;   const int tid = otid();
;   float* afab = (float*)dynsmem;
;   float* G = (float*)(dynsmem + 8192);
;   u16* KD = (u16*)(dynsmem + 8192 + 65536);
;   u16* VL = (u16*)dynsmem;
;   const long tok0 = (long)b * S_ + c * 64;
;   for (int i = tid; i < 64 * 32; i += 512) {
;     int r = i >> 5, cc = i & 31;
;     afab[i] = bf2f(cols[(tok0 + r) * NCP + C_AF + cc]);
;   }
;   __syncthreads();
;   if (tid < 256) {
;     const int dir = tid >> 7, kk = tid & 127;
;     const float* up = dir ? p.gla_a_up_b : p.gla_a_up_f;
;     const float bias = (dir ? p.gla_a_bias_b : p.gla_a_bias_f)[h * 128 + kk];
;     float u[16];
; #pragma unroll
;     for (int r = 0; r < 16; ++r) u[r] = up[r * 512 + h * 128 + kk];
.LBB0_283:
	s_or_b64 exec, exec, s[0:1]
	s_cmpk_lt_i32 s2, 0x200
	v_mov_b32_e32 v0, v189
	s_cselect_b64 s[68:69], -1, 0
	s_cmpk_gt_i32 s2, 0x1ff
	s_waitcnt lgkmcnt(0)
	s_barrier
	s_cbranch_scc1 .LBB0_334
	v_mov_b32_e32 v0, v189
	v_and_b32_e32 v1, 0x7f, v0
	v_lshlrev_b32_e32 v2, 4, v0
	v_lshrrev_b32_e32 v3, 6, v0
	s_nop 0
	v_readfirstlane_b32 s4, v3
	s_nop 3
	s_lshr_b32 s5, s4, 2
	s_bfe_u32 s6, s4, 0x10001
	v_lshrrev_b32_e32 v4, 3, v0
	v_mul_u32_u24_e32 v4, 0x5400, v4
	v_and_b32_e32 v5, 7, v0
	v_lshl_add_u32 v4, v5, 3, v4
	v_add_u32_e32 v4, 0x1800, v4
	v_lshrrev_b32_e32 v5, 4, v0
	v_mul_u32_u24_e32 v5, 0x5400, v5
	v_and_b32_e32 v6, 15, v0
	v_lshl_add_u32 v5, v6, 4, v5
	v_lshrrev_b32_e32 v6, 5, v0
	v_mul_u32_u24_e32 v6, 0x5400, v6
	v_and_b32_e32 v7, 31, v0
	v_lshl_add_u32 v6, v7, 4, v6
	v_lshlrev_b32_e32 v7, 2, v1
	v_and_b32_e32 v8, 0xff, v0
	v_lshrrev_b32_e32 v9, 8, v0
	v_lshlrev_b32_e32 v10, 1, v8
	v_lshl_add_u32 v10, v9, 14, v10
	v_add_u32_e32 v10, 0xa010, v10
	v_lshlrev_b32_e32 v11, 7, v8
	v_lshl_add_u32 v11, v9, 6, v11
	s_lshl_b32 s7, s5, 6
	s_lshl_b32 s8, s6, 12
	s_add_u32 s7, s7, s8
	s_add_u32 s7, s7, 16
	v_mov_b32_e32 v12, s7
	s_lshl_b32 s7, s6, 1
	s_add_u32 s7, s7, s5
	s_lshl_b32 s7, s7, 9
	s_add_u32 s7, s7, 106512
	v_add_u32_e32 v13, s7, v7
	s_xor_b32 s8, s6, 1
	s_lshl_b32 s8, s8, 1
	s_add_u32 s8, s8, s5
	s_lshl_b32 s8, s8, 9
	s_add_u32 s8, s8, 106512
	v_add_u32_e32 v14, s8, v7
	s_lshl_b32 s8, s5, 9
	s_add_u32 s8, s8, 108560
	v_add_u32_e32 v15, s8, v7
	s_lshl_b32 s8, s6, 13
	s_add_u32 s8, s8, 24592
	v_lshl_add_u32 v16, v1, 1, s8
	s_lshl_b32 s8, s5, 15
	s_lshl_b32 s9, s6, 14
	s_add_u32 s8, s8, s9
	s_add_u32 s8, s8, 40976
	v_add_u32_e32 v17, s8, v7
	v_lshlrev_b32_e32 v18, 7, v1
	s_lshl_b32 s8, s6, 6
	v_add_u32_e32 v18, s8, v18
	v_and_b32_e32 v19, 15, v0
	v_lshrrev_b32_e32 v20, 2, v19
	v_and_b32_e32 v21, 3, v19
	v_lshlrev_b32_e32 v20, 5, v20
	v_lshl_add_u32 v20, v21, 2, v20
	v_lshrrev_b32_e32 v21, 4, v0
	v_lshlrev_b32_e32 v22, 9, v21
	v_lshl_add_u32 v22, v20, 2, v22
	v_add_u32_e32 v22, 0xa010, v22
	v_lshlrev_b32_e32 v23, 8, v21
	v_lshl_add_u32 v23, v20, 1, v23
	v_add_u32_e32 v23, 0x2010, v23
	s_cmp_eq_u32 s5, 0
	s_cselect_b32 s36, s80, s84
	s_cselect_b32 s37, s81, s85
	s_cselect_b32 s38, s82, s86
	s_cselect_b32 s39, s83, s87
	s_xor_b32 s40, s5, s6
	s_mov_b32 s3, s2
.Lgl_unit:
	s_cmp_ge_u32 s3, 0x200
	s_cbranch_scc1 .Lgl_done
	s_and_b32 s41, s3, 3
	s_bfe_u32 s42, s3, 0x60002
	s_lshr_b32 s43, s3, 8
	s_lshl_b32 s44, s43, 12
	s_lshl_b32 s45, s42, 6
	s_add_u32 s44, s44, s45
	s_mul_i32 s44, s44, 0x5400
	s_add_u32 s46, s92, s44
	s_addc_u32 s47, s93, 0
	s_add_u32 s46, s46, 0x4c00000
	s_addc_u32 s47, s47, 0
	global_load_dwordx2 v[82:83], v4, s[46:47]
	s_lshl_b32 s48, s41, 8
	s_add_u32 s48, s46, s48
	s_addc_u32 s49, s47, 0
	global_load_dwordx4 v[84:87], v5, s[48:49]
	global_load_dwordx4 v[92:95], v5, s[48:49] offset:1024
	s_add_u32 s50, s48, 0xa8000
	s_addc_u32 s51, s49, 0
	global_load_dwordx4 v[88:91], v5, s[50:51]
	global_load_dwordx4 v[96:99], v5, s[50:51] offset:1024
	s_lshl_b32 s48, s41, 9
	s_add_u32 s48, s46, s48
	s_addc_u32 s49, s47, 0
	global_load_dwordx4 v[100:103], v6, s[48:49] offset:2048
	s_add_u32 s48, s48, 0x54000
	s_addc_u32 s49, s49, 0
	global_load_dwordx4 v[104:107], v6, s[48:49] offset:2048
	s_add_u32 s48, s48, 0x54000
	s_addc_u32 s49, s49, 0
	global_load_dwordx4 v[108:111], v6, s[48:49] offset:2048
	s_add_u32 s48, s48, 0x54000
	s_addc_u32 s49, s49, 0
	global_load_dwordx4 v[112:115], v6, s[48:49] offset:2048
	s_lshl_b32 s48, s41, 9
	v_add_u32_e32 v24, s48, v7
	global_load_dword v64, v24, s[36:37] offset:0
	global_load_dword v65, v24, s[36:37] offset:2048
	v_add_u32_e32 v24, 0x1000, v24
	global_load_dword v66, v24, s[36:37] offset:0
	global_load_dword v67, v24, s[36:37] offset:2048
	v_add_u32_e32 v24, 0x1000, v24
	global_load_dword v68, v24, s[36:37] offset:0
	global_load_dword v69, v24, s[36:37] offset:2048
	v_add_u32_e32 v24, 0x1000, v24
	global_load_dword v70, v24, s[36:37] offset:0
	global_load_dword v71, v24, s[36:37] offset:2048
	v_add_u32_e32 v24, 0x1000, v24
	global_load_dword v72, v24, s[36:37] offset:0
	global_load_dword v73, v24, s[36:37] offset:2048
	v_add_u32_e32 v24, 0x1000, v24
	global_load_dword v74, v24, s[36:37] offset:0
	global_load_dword v75, v24, s[36:37] offset:2048
	v_add_u32_e32 v24, 0x1000, v24
	global_load_dword v76, v24, s[36:37] offset:0
	global_load_dword v77, v24, s[36:37] offset:2048
	v_add_u32_e32 v24, 0x1000, v24
	global_load_dword v78, v24, s[36:37] offset:0
	global_load_dword v79, v24, s[36:37] offset:2048
	v_add_u32_e32 v25, s48, v7
	global_load_dword v80, v25, s[38:39]
	s_waitcnt vmcnt(25)
	v_lshlrev_b32_e32 v116, 16, v82
	v_and_b32_e32 v117, 0xffff0000, v82
	v_lshlrev_b32_e32 v118, 16, v83
	v_and_b32_e32 v119, 0xffff0000, v83
	ds_write_b128 v2, v[116:119] offset:16
	s_waitcnt vmcnt(21)
	ds_write_b128 v2, v[84:87] offset:8208
	ds_write_b128 v2, v[92:95] offset:24592
	ds_write_b128 v2, v[88:91] offset:16400
	ds_write_b128 v2, v[96:99] offset:32784
	s_waitcnt vmcnt(17)
	v_add_u32_e32 v26, 0x8000, v2
	ds_write_b128 v2, v[100:103] offset:40976
	ds_write_b128 v2, v[104:107] offset:49168
	ds_write_b128 v26, v[108:111] offset:24592
	ds_write_b128 v26, v[112:115] offset:32784
	s_waitcnt lgkmcnt(0)
	s_barrier
; DEVINL float logsig(float z) { return fminf(z, 0.f) - __logf(1.f + __expf(-fabsf(z))); }
; DEVINL int fragpos(int idx) { const int w = idx & 31; return (idx & ~31) + (((w & 15) >> 2) << 3) + (w & 3) + ((w >> 4) << 2); }
; DEVINL void gla_prep_unit(const Params& p, int unit) {
;     ...
;     for (int i = 0; i < 64; ++i) {
;       float z = bias;
; #pragma unroll
;       for (int r = 0; r < 16; ++r) z += afab[i * 32 + dir * 16 + r] * u[r];
;       Gc[i * 128] = logsig(z) * (1.f / 16.f);
;     }
;     ...
; #pragma unroll 8
;   for (int idx = tid; idx < 64 * 256; idx += 512) {
;     int i = idx >> 8, vc = idx & 255;
;     VL[vc * 72 + fragpos(i)] = cols[(tok0 + i) * NCP + C_V + h * 256 + vc];
;   }
;   __syncthreads();
;   for (int pc = tid; pc < 4096; pc += 512) {
;     int row = pc >> 3, ch = pc & 7;
;     if (row < 256) {
;       int dir = row >> 7, kk = row & 127;
;       uint4 v = *(const uint4*)(KD + row * 72 + ch * 8);
;       long hb = ((long)(dir * 2 + b) * 4 + h);
;       *(uint4*)((u16*)(ws + O_KDT) + ((hb * 64 + c) * 128 + kk) * 64 + ch * 8) = v;
;     } else {
;       int vc = row - 256;
;       uint4 v = *(const uint4*)(VL + vc * 72 + ch * 8);
;       long hb = ((long)b * 4 + h);
;       *(uint4*)((u16*)(ws + O_VT) + ((hb * 64 + c) * 256 + vc) * 64 + ch * 8) = v;
	ds_read_u16 v192, v10 offset:0
	ds_read_u16 v193, v10 offset:512
	ds_read_u16 v194, v10 offset:1024
	ds_read_u16 v195, v10 offset:1536
	ds_read_u16 v196, v10 offset:2048
	ds_read_u16 v197, v10 offset:2560
	ds_read_u16 v198, v10 offset:3072
	ds_read_u16 v199, v10 offset:3584
	ds_read_u16 v200, v10 offset:4096
	ds_read_u16 v201, v10 offset:4608
	ds_read_u16 v202, v10 offset:5120
	ds_read_u16 v203, v10 offset:5632
	ds_read_u16 v204, v10 offset:6144
	ds_read_u16 v205, v10 offset:6656
	ds_read_u16 v206, v10 offset:7168
	ds_read_u16 v207, v10 offset:7680
	ds_read_u16 v208, v10 offset:8192
	ds_read_u16 v209, v10 offset:8704
	ds_read_u16 v210, v10 offset:9216
	ds_read_u16 v211, v10 offset:9728
	ds_read_u16 v212, v10 offset:10240
	ds_read_u16 v213, v10 offset:10752
	ds_read_u16 v214, v10 offset:11264
	ds_read_u16 v215, v10 offset:11776
	ds_read_u16 v216, v10 offset:12288
	ds_read_u16 v217, v10 offset:12800
	ds_read_u16 v218, v10 offset:13312
	ds_read_u16 v219, v10 offset:13824
	ds_read_u16 v220, v10 offset:14336
	ds_read_u16 v221, v10 offset:14848
	ds_read_u16 v222, v10 offset:15360
	ds_read_u16 v223, v10 offset:15872
	s_lshl_b32 s48, s43, 2
	s_add_u32 s48, s48, s41
	s_lshl_b32 s48, s48, 6
	s_add_u32 s48, s48, s42
	s_lshl_b32 s48, s48, 15
	s_add_u32 s48, s92, s48
	s_addc_u32 s49, s93, 0
	s_add_u32 s48, s48, 0x1a400000
	s_addc_u32 s49, s49, 0
	s_waitcnt lgkmcnt(0)
	v_lshl_or_b32 v144, v193, 16, v192
	v_lshl_or_b32 v145, v195, 16, v194
	v_lshl_or_b32 v146, v209, 16, v208
	v_lshl_or_b32 v147, v211, 16, v210
	v_lshl_or_b32 v148, v197, 16, v196
	v_lshl_or_b32 v149, v199, 16, v198
	v_lshl_or_b32 v150, v213, 16, v212
	v_lshl_or_b32 v151, v215, 16, v214
	v_lshl_or_b32 v152, v201, 16, v200
	v_lshl_or_b32 v153, v203, 16, v202
	v_lshl_or_b32 v154, v217, 16, v216
	v_lshl_or_b32 v155, v219, 16, v218
	v_lshl_or_b32 v156, v205, 16, v204
	v_lshl_or_b32 v157, v207, 16, v206
	v_lshl_or_b32 v158, v221, 16, v220
	v_lshl_or_b32 v159, v223, 16, v222
	global_store_dwordx4 v11, v[144:147], s[48:49] offset:0
	global_store_dwordx4 v11, v[148:151], s[48:49] offset:16
	global_store_dwordx4 v11, v[152:155], s[48:49] offset:32
	global_store_dwordx4 v11, v[156:159], s[48:49] offset:48
	s_waitcnt vmcnt(4)
	s_mov_b32 s52, 0xbfb8aa3b
	s_mov_b32 s53, 0x3f317217
	ds_read_b128 v[116:119], v12 offset:0
	ds_read_b128 v[120:123], v12 offset:16
	ds_read_b128 v[124:127], v12 offset:32
	ds_read_b128 v[128:131], v12 offset:48
	v_mov_b32_e32 v32, v80
	s_waitcnt lgkmcnt(3)
	v_fmac_f32_e32 v32, v116, v64
	v_fmac_f32_e32 v32, v117, v65
	v_fmac_f32_e32 v32, v118, v66
	v_fmac_f32_e32 v32, v119, v67
	s_waitcnt lgkmcnt(2)
	v_fmac_f32_e32 v32, v120, v68
	v_fmac_f32_e32 v32, v121, v69
	v_fmac_f32_e32 v32, v122, v70
	v_fmac_f32_e32 v32, v123, v71
	s_waitcnt lgkmcnt(1)
	v_fmac_f32_e32 v32, v124, v72
	v_fmac_f32_e32 v32, v125, v73
	v_fmac_f32_e32 v32, v126, v74
	v_fmac_f32_e32 v32, v127, v75
	s_waitcnt lgkmcnt(0)
	v_fmac_f32_e32 v32, v128, v76
	v_fmac_f32_e32 v32, v129, v77
	v_fmac_f32_e32 v32, v130, v78
	v_fmac_f32_e32 v32, v131, v79
	v_min_f32_e32 v132, 0, v32
	v_mul_f32_e64 v32, |v32|, s52
	v_exp_f32_e32 v32, v32
	s_nop 0
	v_add_f32_e32 v32, 1.0, v32
	v_log_f32_e32 v32, v32
	s_nop 0
	v_mul_f32_e32 v133, 0x3f317217, v32
	v_fma_f32 v133, v32, s53, -v133
	v_fmac_f32_e32 v133, 0x3377d1cf, v32
	v_fmac_f32_e32 v133, 0x3f317217, v32
	v_sub_f32_e32 v32, v132, v133
	v_mul_f32_e32 v32, 0x3d800000, v32
	ds_read_b128 v[116:119], v12 offset:128
	ds_read_b128 v[120:123], v12 offset:144
	ds_read_b128 v[124:127], v12 offset:160
	ds_read_b128 v[128:131], v12 offset:176
	v_mov_b32_e32 v33, v80
	s_waitcnt lgkmcnt(3)
	v_fmac_f32_e32 v33, v116, v64
	v_fmac_f32_e32 v33, v117, v65
	v_fmac_f32_e32 v33, v118, v66
	v_fmac_f32_e32 v33, v119, v67
	s_waitcnt lgkmcnt(2)
	v_fmac_f32_e32 v33, v120, v68
	v_fmac_f32_e32 v33, v121, v69
	v_fmac_f32_e32 v33, v122, v70
	v_fmac_f32_e32 v33, v123, v71
	s_waitcnt lgkmcnt(1)
	v_fmac_f32_e32 v33, v124, v72
	v_fmac_f32_e32 v33, v125, v73
	v_fmac_f32_e32 v33, v126, v74
	v_fmac_f32_e32 v33, v127, v75
	s_waitcnt lgkmcnt(0)
	v_fmac_f32_e32 v33, v128, v76
	v_fmac_f32_e32 v33, v129, v77
	v_fmac_f32_e32 v33, v130, v78
	v_fmac_f32_e32 v33, v131, v79
	v_min_f32_e32 v132, 0, v33
	v_mul_f32_e64 v33, |v33|, s52
	v_exp_f32_e32 v33, v33
	s_nop 0
	v_add_f32_e32 v33, 1.0, v33
	v_log_f32_e32 v33, v33
	s_nop 0
	v_mul_f32_e32 v133, 0x3f317217, v33
	v_fma_f32 v133, v33, s53, -v133
	v_fmac_f32_e32 v133, 0x3377d1cf, v33
	v_fmac_f32_e32 v133, 0x3f317217, v33
	v_sub_f32_e32 v33, v132, v133
	v_mul_f32_e32 v33, 0x3d800000, v33
	ds_read_b128 v[116:119], v12 offset:256
	ds_read_b128 v[120:123], v12 offset:272
	ds_read_b128 v[124:127], v12 offset:288
	ds_read_b128 v[128:131], v12 offset:304
	v_mov_b32_e32 v34, v80
	s_waitcnt lgkmcnt(3)
	v_fmac_f32_e32 v34, v116, v64
	v_fmac_f32_e32 v34, v117, v65
	v_fmac_f32_e32 v34, v118, v66
	v_fmac_f32_e32 v34, v119, v67
	s_waitcnt lgkmcnt(2)
	v_fmac_f32_e32 v34, v120, v68
	v_fmac_f32_e32 v34, v121, v69
	v_fmac_f32_e32 v34, v122, v70
	v_fmac_f32_e32 v34, v123, v71
	s_waitcnt lgkmcnt(1)
	v_fmac_f32_e32 v34, v124, v72
	v_fmac_f32_e32 v34, v125, v73
	v_fmac_f32_e32 v34, v126, v74
	v_fmac_f32_e32 v34, v127, v75
	s_waitcnt lgkmcnt(0)
	v_fmac_f32_e32 v34, v128, v76
	v_fmac_f32_e32 v34, v129, v77
	v_fmac_f32_e32 v34, v130, v78
	v_fmac_f32_e32 v34, v131, v79
	v_min_f32_e32 v132, 0, v34
	v_mul_f32_e64 v34, |v34|, s52
	v_exp_f32_e32 v34, v34
	s_nop 0
	v_add_f32_e32 v34, 1.0, v34
	v_log_f32_e32 v34, v34
	s_nop 0
	v_mul_f32_e32 v133, 0x3f317217, v34
	v_fma_f32 v133, v34, s53, -v133
	v_fmac_f32_e32 v133, 0x3377d1cf, v34
	v_fmac_f32_e32 v133, 0x3f317217, v34
	v_sub_f32_e32 v34, v132, v133
	v_mul_f32_e32 v34, 0x3d800000, v34
	ds_read_b128 v[116:119], v12 offset:384
	ds_read_b128 v[120:123], v12 offset:400
	ds_read_b128 v[124:127], v12 offset:416
	ds_read_b128 v[128:131], v12 offset:432
	v_mov_b32_e32 v35, v80
	s_waitcnt lgkmcnt(3)
; DEVINL float logsig(float z) { return fminf(z, 0.f) - __logf(1.f + __expf(-fabsf(z))); }
; DEVINL void gla_prep_unit(const Params& p, int unit) {
;     ...
;     for (int i = 0; i < 64; ++i) {
;       float z = bias;
; #pragma unroll
;       for (int r = 0; r < 16; ++r) z += afab[i * 32 + dir * 16 + r] * u[r];
;       Gc[i * 128] = logsig(z) * (1.f / 16.f);
;     }
	v_fmac_f32_e32 v35, v116, v64
	v_fmac_f32_e32 v35, v117, v65
	v_fmac_f32_e32 v35, v118, v66
	v_fmac_f32_e32 v35, v119, v67
	s_waitcnt lgkmcnt(2)
	v_fmac_f32_e32 v35, v120, v68
	v_fmac_f32_e32 v35, v121, v69
	v_fmac_f32_e32 v35, v122, v70
	v_fmac_f32_e32 v35, v123, v71
	s_waitcnt lgkmcnt(1)
	v_fmac_f32_e32 v35, v124, v72
	v_fmac_f32_e32 v35, v125, v73
	v_fmac_f32_e32 v35, v126, v74
	v_fmac_f32_e32 v35, v127, v75
	s_waitcnt lgkmcnt(0)
	v_fmac_f32_e32 v35, v128, v76
	v_fmac_f32_e32 v35, v129, v77
	v_fmac_f32_e32 v35, v130, v78
	v_fmac_f32_e32 v35, v131, v79
	v_min_f32_e32 v132, 0, v35
	v_mul_f32_e64 v35, |v35|, s52
	v_exp_f32_e32 v35, v35
	s_nop 0
	v_add_f32_e32 v35, 1.0, v35
	v_log_f32_e32 v35, v35
	s_nop 0
	v_mul_f32_e32 v133, 0x3f317217, v35
	v_fma_f32 v133, v35, s53, -v133
	v_fmac_f32_e32 v133, 0x3377d1cf, v35
	v_fmac_f32_e32 v133, 0x3f317217, v35
	v_sub_f32_e32 v35, v132, v133
	v_mul_f32_e32 v35, 0x3d800000, v35
	ds_read_b128 v[116:119], v12 offset:512
	ds_read_b128 v[120:123], v12 offset:528
	ds_read_b128 v[124:127], v12 offset:544
	ds_read_b128 v[128:131], v12 offset:560
	v_mov_b32_e32 v36, v80
	s_waitcnt lgkmcnt(3)
	v_fmac_f32_e32 v36, v116, v64
	v_fmac_f32_e32 v36, v117, v65
	v_fmac_f32_e32 v36, v118, v66
	v_fmac_f32_e32 v36, v119, v67
	s_waitcnt lgkmcnt(2)
	v_fmac_f32_e32 v36, v120, v68
	v_fmac_f32_e32 v36, v121, v69
	v_fmac_f32_e32 v36, v122, v70
	v_fmac_f32_e32 v36, v123, v71
	s_waitcnt lgkmcnt(1)
	v_fmac_f32_e32 v36, v124, v72
	v_fmac_f32_e32 v36, v125, v73
	v_fmac_f32_e32 v36, v126, v74
	v_fmac_f32_e32 v36, v127, v75
	s_waitcnt lgkmcnt(0)
	v_fmac_f32_e32 v36, v128, v76
	v_fmac_f32_e32 v36, v129, v77
	v_fmac_f32_e32 v36, v130, v78
	v_fmac_f32_e32 v36, v131, v79
	v_min_f32_e32 v132, 0, v36
	v_mul_f32_e64 v36, |v36|, s52
	v_exp_f32_e32 v36, v36
	s_nop 0
	v_add_f32_e32 v36, 1.0, v36
	v_log_f32_e32 v36, v36
	s_nop 0
	v_mul_f32_e32 v133, 0x3f317217, v36
	v_fma_f32 v133, v36, s53, -v133
	v_fmac_f32_e32 v133, 0x3377d1cf, v36
	v_fmac_f32_e32 v133, 0x3f317217, v36
	v_sub_f32_e32 v36, v132, v133
	v_mul_f32_e32 v36, 0x3d800000, v36
	ds_read_b128 v[116:119], v12 offset:640
	ds_read_b128 v[120:123], v12 offset:656
	ds_read_b128 v[124:127], v12 offset:672
	ds_read_b128 v[128:131], v12 offset:688
	v_mov_b32_e32 v37, v80
	s_waitcnt lgkmcnt(3)
	v_fmac_f32_e32 v37, v116, v64
	v_fmac_f32_e32 v37, v117, v65
	v_fmac_f32_e32 v37, v118, v66
	v_fmac_f32_e32 v37, v119, v67
	s_waitcnt lgkmcnt(2)
	v_fmac_f32_e32 v37, v120, v68
	v_fmac_f32_e32 v37, v121, v69
	v_fmac_f32_e32 v37, v122, v70
	v_fmac_f32_e32 v37, v123, v71
	s_waitcnt lgkmcnt(1)
	v_fmac_f32_e32 v37, v124, v72
	v_fmac_f32_e32 v37, v125, v73
	v_fmac_f32_e32 v37, v126, v74
	v_fmac_f32_e32 v37, v127, v75
	s_waitcnt lgkmcnt(0)
	v_fmac_f32_e32 v37, v128, v76
	v_fmac_f32_e32 v37, v129, v77
	v_fmac_f32_e32 v37, v130, v78
	v_fmac_f32_e32 v37, v131, v79
	v_min_f32_e32 v132, 0, v37
	v_mul_f32_e64 v37, |v37|, s52
	v_exp_f32_e32 v37, v37
	s_nop 0
	v_add_f32_e32 v37, 1.0, v37
	v_log_f32_e32 v37, v37
	s_nop 0
	v_mul_f32_e32 v133, 0x3f317217, v37
	v_fma_f32 v133, v37, s53, -v133
	v_fmac_f32_e32 v133, 0x3377d1cf, v37
	v_fmac_f32_e32 v133, 0x3f317217, v37
	v_sub_f32_e32 v37, v132, v133
	v_mul_f32_e32 v37, 0x3d800000, v37
	ds_read_b128 v[116:119], v12 offset:768
	ds_read_b128 v[120:123], v12 offset:784
	ds_read_b128 v[124:127], v12 offset:800
	ds_read_b128 v[128:131], v12 offset:816
	v_mov_b32_e32 v38, v80
	s_waitcnt lgkmcnt(3)
	v_fmac_f32_e32 v38, v116, v64
	v_fmac_f32_e32 v38, v117, v65
	v_fmac_f32_e32 v38, v118, v66
	v_fmac_f32_e32 v38, v119, v67
	s_waitcnt lgkmcnt(2)
	v_fmac_f32_e32 v38, v120, v68
	v_fmac_f32_e32 v38, v121, v69
	v_fmac_f32_e32 v38, v122, v70
	v_fmac_f32_e32 v38, v123, v71
	s_waitcnt lgkmcnt(1)
	v_fmac_f32_e32 v38, v124, v72
	v_fmac_f32_e32 v38, v125, v73
	v_fmac_f32_e32 v38, v126, v74
	v_fmac_f32_e32 v38, v127, v75
	s_waitcnt lgkmcnt(0)
	v_fmac_f32_e32 v38, v128, v76
	v_fmac_f32_e32 v38, v129, v77
	v_fmac_f32_e32 v38, v130, v78
	v_fmac_f32_e32 v38, v131, v79
	v_min_f32_e32 v132, 0, v38
	v_mul_f32_e64 v38, |v38|, s52
	v_exp_f32_e32 v38, v38
	s_nop 0
	v_add_f32_e32 v38, 1.0, v38
	v_log_f32_e32 v38, v38
	s_nop 0
	v_mul_f32_e32 v133, 0x3f317217, v38
	v_fma_f32 v133, v38, s53, -v133
	v_fmac_f32_e32 v133, 0x3377d1cf, v38
	v_fmac_f32_e32 v133, 0x3f317217, v38
	v_sub_f32_e32 v38, v132, v133
	v_mul_f32_e32 v38, 0x3d800000, v38
	ds_read_b128 v[116:119], v12 offset:896
	ds_read_b128 v[120:123], v12 offset:912
	ds_read_b128 v[124:127], v12 offset:928
	ds_read_b128 v[128:131], v12 offset:944
	v_mov_b32_e32 v39, v80
	s_waitcnt lgkmcnt(3)
	v_fmac_f32_e32 v39, v116, v64
	v_fmac_f32_e32 v39, v117, v65
	v_fmac_f32_e32 v39, v118, v66
	v_fmac_f32_e32 v39, v119, v67
	s_waitcnt lgkmcnt(2)
	v_fmac_f32_e32 v39, v120, v68
	v_fmac_f32_e32 v39, v121, v69
	v_fmac_f32_e32 v39, v122, v70
	v_fmac_f32_e32 v39, v123, v71
	s_waitcnt lgkmcnt(1)
	v_fmac_f32_e32 v39, v124, v72
	v_fmac_f32_e32 v39, v125, v73
	v_fmac_f32_e32 v39, v126, v74
	v_fmac_f32_e32 v39, v127, v75
	s_waitcnt lgkmcnt(0)
	v_fmac_f32_e32 v39, v128, v76
	v_fmac_f32_e32 v39, v129, v77
	v_fmac_f32_e32 v39, v130, v78
	v_fmac_f32_e32 v39, v131, v79
	v_min_f32_e32 v132, 0, v39
	v_mul_f32_e64 v39, |v39|, s52
	v_exp_f32_e32 v39, v39
	s_nop 0
	v_add_f32_e32 v39, 1.0, v39
	v_log_f32_e32 v39, v39
	s_nop 0
	v_mul_f32_e32 v133, 0x3f317217, v39
	v_fma_f32 v133, v39, s53, -v133
	v_fmac_f32_e32 v133, 0x3377d1cf, v39
	v_fmac_f32_e32 v133, 0x3f317217, v39
	v_sub_f32_e32 v39, v132, v133
	v_mul_f32_e32 v39, 0x3d800000, v39
	ds_read_b128 v[116:119], v12 offset:1024
	ds_read_b128 v[120:123], v12 offset:1040
	ds_read_b128 v[124:127], v12 offset:1056
	ds_read_b128 v[128:131], v12 offset:1072
	v_mov_b32_e32 v40, v80
	s_waitcnt lgkmcnt(3)
; DEVINL float logsig(float z) { return fminf(z, 0.f) - __logf(1.f + __expf(-fabsf(z))); }
; DEVINL void gla_prep_unit(const Params& p, int unit) {
;     ...
;     for (int i = 0; i < 64; ++i) {
;       float z = bias;
; #pragma unroll
;       for (int r = 0; r < 16; ++r) z += afab[i * 32 + dir * 16 + r] * u[r];
;       Gc[i * 128] = logsig(z) * (1.f / 16.f);
;     }
	v_fmac_f32_e32 v40, v116, v64
	v_fmac_f32_e32 v40, v117, v65
	v_fmac_f32_e32 v40, v118, v66
	v_fmac_f32_e32 v40, v119, v67
	s_waitcnt lgkmcnt(2)
	v_fmac_f32_e32 v40, v120, v68
	v_fmac_f32_e32 v40, v121, v69
	v_fmac_f32_e32 v40, v122, v70
	v_fmac_f32_e32 v40, v123, v71
	s_waitcnt lgkmcnt(1)
	v_fmac_f32_e32 v40, v124, v72
	v_fmac_f32_e32 v40, v125, v73
	v_fmac_f32_e32 v40, v126, v74
	v_fmac_f32_e32 v40, v127, v75
	s_waitcnt lgkmcnt(0)
	v_fmac_f32_e32 v40, v128, v76
	v_fmac_f32_e32 v40, v129, v77
	v_fmac_f32_e32 v40, v130, v78
	v_fmac_f32_e32 v40, v131, v79
	v_min_f32_e32 v132, 0, v40
	v_mul_f32_e64 v40, |v40|, s52
	v_exp_f32_e32 v40, v40
	s_nop 0
	v_add_f32_e32 v40, 1.0, v40
	v_log_f32_e32 v40, v40
	s_nop 0
	v_mul_f32_e32 v133, 0x3f317217, v40
	v_fma_f32 v133, v40, s53, -v133
	v_fmac_f32_e32 v133, 0x3377d1cf, v40
	v_fmac_f32_e32 v133, 0x3f317217, v40
	v_sub_f32_e32 v40, v132, v133
	v_mul_f32_e32 v40, 0x3d800000, v40
	ds_read_b128 v[116:119], v12 offset:1152
	ds_read_b128 v[120:123], v12 offset:1168
	ds_read_b128 v[124:127], v12 offset:1184
	ds_read_b128 v[128:131], v12 offset:1200
	v_mov_b32_e32 v41, v80
	s_waitcnt lgkmcnt(3)
	v_fmac_f32_e32 v41, v116, v64
	v_fmac_f32_e32 v41, v117, v65
	v_fmac_f32_e32 v41, v118, v66
	v_fmac_f32_e32 v41, v119, v67
	s_waitcnt lgkmcnt(2)
	v_fmac_f32_e32 v41, v120, v68
	v_fmac_f32_e32 v41, v121, v69
	v_fmac_f32_e32 v41, v122, v70
	v_fmac_f32_e32 v41, v123, v71
	s_waitcnt lgkmcnt(1)
	v_fmac_f32_e32 v41, v124, v72
	v_fmac_f32_e32 v41, v125, v73
	v_fmac_f32_e32 v41, v126, v74
	v_fmac_f32_e32 v41, v127, v75
	s_waitcnt lgkmcnt(0)
	v_fmac_f32_e32 v41, v128, v76
	v_fmac_f32_e32 v41, v129, v77
	v_fmac_f32_e32 v41, v130, v78
	v_fmac_f32_e32 v41, v131, v79
	v_min_f32_e32 v132, 0, v41
	v_mul_f32_e64 v41, |v41|, s52
	v_exp_f32_e32 v41, v41
	s_nop 0
	v_add_f32_e32 v41, 1.0, v41
	v_log_f32_e32 v41, v41
	s_nop 0
	v_mul_f32_e32 v133, 0x3f317217, v41
	v_fma_f32 v133, v41, s53, -v133
	v_fmac_f32_e32 v133, 0x3377d1cf, v41
	v_fmac_f32_e32 v133, 0x3f317217, v41
	v_sub_f32_e32 v41, v132, v133
	v_mul_f32_e32 v41, 0x3d800000, v41
	ds_read_b128 v[116:119], v12 offset:1280
	ds_read_b128 v[120:123], v12 offset:1296
	ds_read_b128 v[124:127], v12 offset:1312
	ds_read_b128 v[128:131], v12 offset:1328
	v_mov_b32_e32 v42, v80
	s_waitcnt lgkmcnt(3)
	v_fmac_f32_e32 v42, v116, v64
	v_fmac_f32_e32 v42, v117, v65
	v_fmac_f32_e32 v42, v118, v66
	v_fmac_f32_e32 v42, v119, v67
	s_waitcnt lgkmcnt(2)
	v_fmac_f32_e32 v42, v120, v68
	v_fmac_f32_e32 v42, v121, v69
	v_fmac_f32_e32 v42, v122, v70
	v_fmac_f32_e32 v42, v123, v71
	s_waitcnt lgkmcnt(1)
	v_fmac_f32_e32 v42, v124, v72
	v_fmac_f32_e32 v42, v125, v73
	v_fmac_f32_e32 v42, v126, v74
	v_fmac_f32_e32 v42, v127, v75
	s_waitcnt lgkmcnt(0)
	v_fmac_f32_e32 v42, v128, v76
	v_fmac_f32_e32 v42, v129, v77
	v_fmac_f32_e32 v42, v130, v78
	v_fmac_f32_e32 v42, v131, v79
	v_min_f32_e32 v132, 0, v42
	v_mul_f32_e64 v42, |v42|, s52
	v_exp_f32_e32 v42, v42
	s_nop 0
	v_add_f32_e32 v42, 1.0, v42
	v_log_f32_e32 v42, v42
	s_nop 0
	v_mul_f32_e32 v133, 0x3f317217, v42
	v_fma_f32 v133, v42, s53, -v133
	v_fmac_f32_e32 v133, 0x3377d1cf, v42
	v_fmac_f32_e32 v133, 0x3f317217, v42
	v_sub_f32_e32 v42, v132, v133
	v_mul_f32_e32 v42, 0x3d800000, v42
	ds_read_b128 v[116:119], v12 offset:1408
	ds_read_b128 v[120:123], v12 offset:1424
	ds_read_b128 v[124:127], v12 offset:1440
	ds_read_b128 v[128:131], v12 offset:1456
	v_mov_b32_e32 v43, v80
	s_waitcnt lgkmcnt(3)
	v_fmac_f32_e32 v43, v116, v64
	v_fmac_f32_e32 v43, v117, v65
	v_fmac_f32_e32 v43, v118, v66
	v_fmac_f32_e32 v43, v119, v67
	s_waitcnt lgkmcnt(2)
	v_fmac_f32_e32 v43, v120, v68
	v_fmac_f32_e32 v43, v121, v69
	v_fmac_f32_e32 v43, v122, v70
	v_fmac_f32_e32 v43, v123, v71
	s_waitcnt lgkmcnt(1)
	v_fmac_f32_e32 v43, v124, v72
	v_fmac_f32_e32 v43, v125, v73
	v_fmac_f32_e32 v43, v126, v74
	v_fmac_f32_e32 v43, v127, v75
	s_waitcnt lgkmcnt(0)
	v_fmac_f32_e32 v43, v128, v76
	v_fmac_f32_e32 v43, v129, v77
	v_fmac_f32_e32 v43, v130, v78
	v_fmac_f32_e32 v43, v131, v79
	v_min_f32_e32 v132, 0, v43
	v_mul_f32_e64 v43, |v43|, s52
	v_exp_f32_e32 v43, v43
	s_nop 0
	v_add_f32_e32 v43, 1.0, v43
	v_log_f32_e32 v43, v43
	s_nop 0
	v_mul_f32_e32 v133, 0x3f317217, v43
	v_fma_f32 v133, v43, s53, -v133
	v_fmac_f32_e32 v133, 0x3377d1cf, v43
	v_fmac_f32_e32 v133, 0x3f317217, v43
	v_sub_f32_e32 v43, v132, v133
	v_mul_f32_e32 v43, 0x3d800000, v43
	ds_read_b128 v[116:119], v12 offset:1536
	ds_read_b128 v[120:123], v12 offset:1552
	ds_read_b128 v[124:127], v12 offset:1568
	ds_read_b128 v[128:131], v12 offset:1584
	v_mov_b32_e32 v44, v80
	s_waitcnt lgkmcnt(3)
	v_fmac_f32_e32 v44, v116, v64
	v_fmac_f32_e32 v44, v117, v65
	v_fmac_f32_e32 v44, v118, v66
	v_fmac_f32_e32 v44, v119, v67
	s_waitcnt lgkmcnt(2)
	v_fmac_f32_e32 v44, v120, v68
	v_fmac_f32_e32 v44, v121, v69
	v_fmac_f32_e32 v44, v122, v70
	v_fmac_f32_e32 v44, v123, v71
	s_waitcnt lgkmcnt(1)
	v_fmac_f32_e32 v44, v124, v72
	v_fmac_f32_e32 v44, v125, v73
	v_fmac_f32_e32 v44, v126, v74
	v_fmac_f32_e32 v44, v127, v75
	s_waitcnt lgkmcnt(0)
	v_fmac_f32_e32 v44, v128, v76
	v_fmac_f32_e32 v44, v129, v77
	v_fmac_f32_e32 v44, v130, v78
	v_fmac_f32_e32 v44, v131, v79
	v_min_f32_e32 v132, 0, v44
	v_mul_f32_e64 v44, |v44|, s52
	v_exp_f32_e32 v44, v44
	s_nop 0
	v_add_f32_e32 v44, 1.0, v44
	v_log_f32_e32 v44, v44
	s_nop 0
	v_mul_f32_e32 v133, 0x3f317217, v44
	v_fma_f32 v133, v44, s53, -v133
	v_fmac_f32_e32 v133, 0x3377d1cf, v44
	v_fmac_f32_e32 v133, 0x3f317217, v44
	v_sub_f32_e32 v44, v132, v133
	v_mul_f32_e32 v44, 0x3d800000, v44
	ds_read_b128 v[116:119], v12 offset:1664
	ds_read_b128 v[120:123], v12 offset:1680
	ds_read_b128 v[124:127], v12 offset:1696
	ds_read_b128 v[128:131], v12 offset:1712
	v_mov_b32_e32 v45, v80
	s_waitcnt lgkmcnt(3)
; DEVINL float logsig(float z) { return fminf(z, 0.f) - __logf(1.f + __expf(-fabsf(z))); }
; DEVINL void gla_prep_unit(const Params& p, int unit) {
;     ...
;     for (int i = 0; i < 64; ++i) {
;       float z = bias;
; #pragma unroll
;       for (int r = 0; r < 16; ++r) z += afab[i * 32 + dir * 16 + r] * u[r];
;       Gc[i * 128] = logsig(z) * (1.f / 16.f);
;     }
	v_fmac_f32_e32 v45, v116, v64
	v_fmac_f32_e32 v45, v117, v65
	v_fmac_f32_e32 v45, v118, v66
	v_fmac_f32_e32 v45, v119, v67
	s_waitcnt lgkmcnt(2)
	v_fmac_f32_e32 v45, v120, v68
	v_fmac_f32_e32 v45, v121, v69
	v_fmac_f32_e32 v45, v122, v70
	v_fmac_f32_e32 v45, v123, v71
	s_waitcnt lgkmcnt(1)
	v_fmac_f32_e32 v45, v124, v72
	v_fmac_f32_e32 v45, v125, v73
	v_fmac_f32_e32 v45, v126, v74
	v_fmac_f32_e32 v45, v127, v75
	s_waitcnt lgkmcnt(0)
	v_fmac_f32_e32 v45, v128, v76
	v_fmac_f32_e32 v45, v129, v77
	v_fmac_f32_e32 v45, v130, v78
	v_fmac_f32_e32 v45, v131, v79
	v_min_f32_e32 v132, 0, v45
	v_mul_f32_e64 v45, |v45|, s52
	v_exp_f32_e32 v45, v45
	s_nop 0
	v_add_f32_e32 v45, 1.0, v45
	v_log_f32_e32 v45, v45
	s_nop 0
	v_mul_f32_e32 v133, 0x3f317217, v45
	v_fma_f32 v133, v45, s53, -v133
	v_fmac_f32_e32 v133, 0x3377d1cf, v45
	v_fmac_f32_e32 v133, 0x3f317217, v45
	v_sub_f32_e32 v45, v132, v133
	v_mul_f32_e32 v45, 0x3d800000, v45
	ds_read_b128 v[116:119], v12 offset:1792
	ds_read_b128 v[120:123], v12 offset:1808
	ds_read_b128 v[124:127], v12 offset:1824
	ds_read_b128 v[128:131], v12 offset:1840
	v_mov_b32_e32 v46, v80
	s_waitcnt lgkmcnt(3)
	v_fmac_f32_e32 v46, v116, v64
	v_fmac_f32_e32 v46, v117, v65
	v_fmac_f32_e32 v46, v118, v66
	v_fmac_f32_e32 v46, v119, v67
	s_waitcnt lgkmcnt(2)
	v_fmac_f32_e32 v46, v120, v68
	v_fmac_f32_e32 v46, v121, v69
	v_fmac_f32_e32 v46, v122, v70
	v_fmac_f32_e32 v46, v123, v71
	s_waitcnt lgkmcnt(1)
	v_fmac_f32_e32 v46, v124, v72
	v_fmac_f32_e32 v46, v125, v73
	v_fmac_f32_e32 v46, v126, v74
	v_fmac_f32_e32 v46, v127, v75
	s_waitcnt lgkmcnt(0)
	v_fmac_f32_e32 v46, v128, v76
	v_fmac_f32_e32 v46, v129, v77
	v_fmac_f32_e32 v46, v130, v78
	v_fmac_f32_e32 v46, v131, v79
	v_min_f32_e32 v132, 0, v46
	v_mul_f32_e64 v46, |v46|, s52
	v_exp_f32_e32 v46, v46
	s_nop 0
	v_add_f32_e32 v46, 1.0, v46
	v_log_f32_e32 v46, v46
	s_nop 0
	v_mul_f32_e32 v133, 0x3f317217, v46
	v_fma_f32 v133, v46, s53, -v133
	v_fmac_f32_e32 v133, 0x3377d1cf, v46
	v_fmac_f32_e32 v133, 0x3f317217, v46
	v_sub_f32_e32 v46, v132, v133
	v_mul_f32_e32 v46, 0x3d800000, v46
	ds_read_b128 v[116:119], v12 offset:1920
	ds_read_b128 v[120:123], v12 offset:1936
	ds_read_b128 v[124:127], v12 offset:1952
	ds_read_b128 v[128:131], v12 offset:1968
	v_mov_b32_e32 v47, v80
	s_waitcnt lgkmcnt(3)
	v_fmac_f32_e32 v47, v116, v64
	v_fmac_f32_e32 v47, v117, v65
	v_fmac_f32_e32 v47, v118, v66
	v_fmac_f32_e32 v47, v119, v67
	s_waitcnt lgkmcnt(2)
	v_fmac_f32_e32 v47, v120, v68
	v_fmac_f32_e32 v47, v121, v69
	v_fmac_f32_e32 v47, v122, v70
	v_fmac_f32_e32 v47, v123, v71
	s_waitcnt lgkmcnt(1)
	v_fmac_f32_e32 v47, v124, v72
	v_fmac_f32_e32 v47, v125, v73
	v_fmac_f32_e32 v47, v126, v74
	v_fmac_f32_e32 v47, v127, v75
	s_waitcnt lgkmcnt(0)
	v_fmac_f32_e32 v47, v128, v76
	v_fmac_f32_e32 v47, v129, v77
	v_fmac_f32_e32 v47, v130, v78
	v_fmac_f32_e32 v47, v131, v79
	v_min_f32_e32 v132, 0, v47
	v_mul_f32_e64 v47, |v47|, s52
	v_exp_f32_e32 v47, v47
	s_nop 0
	v_add_f32_e32 v47, 1.0, v47
	v_log_f32_e32 v47, v47
	s_nop 0
	v_mul_f32_e32 v133, 0x3f317217, v47
	v_fma_f32 v133, v47, s53, -v133
	v_fmac_f32_e32 v133, 0x3377d1cf, v47
	v_fmac_f32_e32 v133, 0x3f317217, v47
	v_sub_f32_e32 v47, v132, v133
	v_mul_f32_e32 v47, 0x3d800000, v47
	ds_read_b128 v[116:119], v12 offset:2048
	ds_read_b128 v[120:123], v12 offset:2064
	ds_read_b128 v[124:127], v12 offset:2080
	ds_read_b128 v[128:131], v12 offset:2096
	v_mov_b32_e32 v48, v80
	s_waitcnt lgkmcnt(3)
	v_fmac_f32_e32 v48, v116, v64
	v_fmac_f32_e32 v48, v117, v65
	v_fmac_f32_e32 v48, v118, v66
	v_fmac_f32_e32 v48, v119, v67
	s_waitcnt lgkmcnt(2)
	v_fmac_f32_e32 v48, v120, v68
	v_fmac_f32_e32 v48, v121, v69
	v_fmac_f32_e32 v48, v122, v70
	v_fmac_f32_e32 v48, v123, v71
	s_waitcnt lgkmcnt(1)
	v_fmac_f32_e32 v48, v124, v72
	v_fmac_f32_e32 v48, v125, v73
	v_fmac_f32_e32 v48, v126, v74
	v_fmac_f32_e32 v48, v127, v75
	s_waitcnt lgkmcnt(0)
	v_fmac_f32_e32 v48, v128, v76
	v_fmac_f32_e32 v48, v129, v77
	v_fmac_f32_e32 v48, v130, v78
	v_fmac_f32_e32 v48, v131, v79
	v_min_f32_e32 v132, 0, v48
	v_mul_f32_e64 v48, |v48|, s52
	v_exp_f32_e32 v48, v48
	s_nop 0
	v_add_f32_e32 v48, 1.0, v48
	v_log_f32_e32 v48, v48
	s_nop 0
	v_mul_f32_e32 v133, 0x3f317217, v48
	v_fma_f32 v133, v48, s53, -v133
	v_fmac_f32_e32 v133, 0x3377d1cf, v48
	v_fmac_f32_e32 v133, 0x3f317217, v48
	v_sub_f32_e32 v48, v132, v133
	v_mul_f32_e32 v48, 0x3d800000, v48
	ds_read_b128 v[116:119], v12 offset:2176
	ds_read_b128 v[120:123], v12 offset:2192
	ds_read_b128 v[124:127], v12 offset:2208
	ds_read_b128 v[128:131], v12 offset:2224
	v_mov_b32_e32 v49, v80
	s_waitcnt lgkmcnt(3)
	v_fmac_f32_e32 v49, v116, v64
	v_fmac_f32_e32 v49, v117, v65
	v_fmac_f32_e32 v49, v118, v66
	v_fmac_f32_e32 v49, v119, v67
	s_waitcnt lgkmcnt(2)
	v_fmac_f32_e32 v49, v120, v68
	v_fmac_f32_e32 v49, v121, v69
	v_fmac_f32_e32 v49, v122, v70
	v_fmac_f32_e32 v49, v123, v71
	s_waitcnt lgkmcnt(1)
	v_fmac_f32_e32 v49, v124, v72
	v_fmac_f32_e32 v49, v125, v73
	v_fmac_f32_e32 v49, v126, v74
	v_fmac_f32_e32 v49, v127, v75
	s_waitcnt lgkmcnt(0)
	v_fmac_f32_e32 v49, v128, v76
	v_fmac_f32_e32 v49, v129, v77
	v_fmac_f32_e32 v49, v130, v78
	v_fmac_f32_e32 v49, v131, v79
	v_min_f32_e32 v132, 0, v49
	v_mul_f32_e64 v49, |v49|, s52
	v_exp_f32_e32 v49, v49
	s_nop 0
	v_add_f32_e32 v49, 1.0, v49
	v_log_f32_e32 v49, v49
	s_nop 0
	v_mul_f32_e32 v133, 0x3f317217, v49
	v_fma_f32 v133, v49, s53, -v133
	v_fmac_f32_e32 v133, 0x3377d1cf, v49
	v_fmac_f32_e32 v133, 0x3f317217, v49
	v_sub_f32_e32 v49, v132, v133
	v_mul_f32_e32 v49, 0x3d800000, v49
	ds_read_b128 v[116:119], v12 offset:2304
	ds_read_b128 v[120:123], v12 offset:2320
	ds_read_b128 v[124:127], v12 offset:2336
	ds_read_b128 v[128:131], v12 offset:2352
	v_mov_b32_e32 v50, v80
	s_waitcnt lgkmcnt(3)
; DEVINL float logsig(float z) { return fminf(z, 0.f) - __logf(1.f + __expf(-fabsf(z))); }
; DEVINL void gla_prep_unit(const Params& p, int unit) {
;     ...
;     for (int i = 0; i < 64; ++i) {
;       float z = bias;
; #pragma unroll
;       for (int r = 0; r < 16; ++r) z += afab[i * 32 + dir * 16 + r] * u[r];
;       Gc[i * 128] = logsig(z) * (1.f / 16.f);
;     }
	v_fmac_f32_e32 v50, v116, v64
	v_fmac_f32_e32 v50, v117, v65
	v_fmac_f32_e32 v50, v118, v66
	v_fmac_f32_e32 v50, v119, v67
	s_waitcnt lgkmcnt(2)
	v_fmac_f32_e32 v50, v120, v68
	v_fmac_f32_e32 v50, v121, v69
	v_fmac_f32_e32 v50, v122, v70
	v_fmac_f32_e32 v50, v123, v71
	s_waitcnt lgkmcnt(1)
	v_fmac_f32_e32 v50, v124, v72
	v_fmac_f32_e32 v50, v125, v73
	v_fmac_f32_e32 v50, v126, v74
	v_fmac_f32_e32 v50, v127, v75
	s_waitcnt lgkmcnt(0)
	v_fmac_f32_e32 v50, v128, v76
	v_fmac_f32_e32 v50, v129, v77
	v_fmac_f32_e32 v50, v130, v78
	v_fmac_f32_e32 v50, v131, v79
	v_min_f32_e32 v132, 0, v50
	v_mul_f32_e64 v50, |v50|, s52
	v_exp_f32_e32 v50, v50
	s_nop 0
	v_add_f32_e32 v50, 1.0, v50
	v_log_f32_e32 v50, v50
	s_nop 0
	v_mul_f32_e32 v133, 0x3f317217, v50
	v_fma_f32 v133, v50, s53, -v133
	v_fmac_f32_e32 v133, 0x3377d1cf, v50
	v_fmac_f32_e32 v133, 0x3f317217, v50
	v_sub_f32_e32 v50, v132, v133
	v_mul_f32_e32 v50, 0x3d800000, v50
	ds_read_b128 v[116:119], v12 offset:2432
	ds_read_b128 v[120:123], v12 offset:2448
	ds_read_b128 v[124:127], v12 offset:2464
	ds_read_b128 v[128:131], v12 offset:2480
	v_mov_b32_e32 v51, v80
	s_waitcnt lgkmcnt(3)
	v_fmac_f32_e32 v51, v116, v64
	v_fmac_f32_e32 v51, v117, v65
	v_fmac_f32_e32 v51, v118, v66
	v_fmac_f32_e32 v51, v119, v67
	s_waitcnt lgkmcnt(2)
	v_fmac_f32_e32 v51, v120, v68
	v_fmac_f32_e32 v51, v121, v69
	v_fmac_f32_e32 v51, v122, v70
	v_fmac_f32_e32 v51, v123, v71
	s_waitcnt lgkmcnt(1)
	v_fmac_f32_e32 v51, v124, v72
	v_fmac_f32_e32 v51, v125, v73
	v_fmac_f32_e32 v51, v126, v74
	v_fmac_f32_e32 v51, v127, v75
	s_waitcnt lgkmcnt(0)
	v_fmac_f32_e32 v51, v128, v76
	v_fmac_f32_e32 v51, v129, v77
	v_fmac_f32_e32 v51, v130, v78
	v_fmac_f32_e32 v51, v131, v79
	v_min_f32_e32 v132, 0, v51
	v_mul_f32_e64 v51, |v51|, s52
	v_exp_f32_e32 v51, v51
	s_nop 0
	v_add_f32_e32 v51, 1.0, v51
	v_log_f32_e32 v51, v51
	s_nop 0
	v_mul_f32_e32 v133, 0x3f317217, v51
	v_fma_f32 v133, v51, s53, -v133
	v_fmac_f32_e32 v133, 0x3377d1cf, v51
	v_fmac_f32_e32 v133, 0x3f317217, v51
	v_sub_f32_e32 v51, v132, v133
	v_mul_f32_e32 v51, 0x3d800000, v51
	ds_read_b128 v[116:119], v12 offset:2560
	ds_read_b128 v[120:123], v12 offset:2576
	ds_read_b128 v[124:127], v12 offset:2592
	ds_read_b128 v[128:131], v12 offset:2608
	v_mov_b32_e32 v52, v80
	s_waitcnt lgkmcnt(3)
	v_fmac_f32_e32 v52, v116, v64
	v_fmac_f32_e32 v52, v117, v65
	v_fmac_f32_e32 v52, v118, v66
	v_fmac_f32_e32 v52, v119, v67
	s_waitcnt lgkmcnt(2)
	v_fmac_f32_e32 v52, v120, v68
	v_fmac_f32_e32 v52, v121, v69
	v_fmac_f32_e32 v52, v122, v70
	v_fmac_f32_e32 v52, v123, v71
	s_waitcnt lgkmcnt(1)
	v_fmac_f32_e32 v52, v124, v72
	v_fmac_f32_e32 v52, v125, v73
	v_fmac_f32_e32 v52, v126, v74
	v_fmac_f32_e32 v52, v127, v75
	s_waitcnt lgkmcnt(0)
	v_fmac_f32_e32 v52, v128, v76
	v_fmac_f32_e32 v52, v129, v77
	v_fmac_f32_e32 v52, v130, v78
	v_fmac_f32_e32 v52, v131, v79
	v_min_f32_e32 v132, 0, v52
	v_mul_f32_e64 v52, |v52|, s52
	v_exp_f32_e32 v52, v52
	s_nop 0
	v_add_f32_e32 v52, 1.0, v52
	v_log_f32_e32 v52, v52
	s_nop 0
	v_mul_f32_e32 v133, 0x3f317217, v52
	v_fma_f32 v133, v52, s53, -v133
	v_fmac_f32_e32 v133, 0x3377d1cf, v52
	v_fmac_f32_e32 v133, 0x3f317217, v52
	v_sub_f32_e32 v52, v132, v133
	v_mul_f32_e32 v52, 0x3d800000, v52
	ds_read_b128 v[116:119], v12 offset:2688
	ds_read_b128 v[120:123], v12 offset:2704
	ds_read_b128 v[124:127], v12 offset:2720
	ds_read_b128 v[128:131], v12 offset:2736
	v_mov_b32_e32 v53, v80
	s_waitcnt lgkmcnt(3)
	v_fmac_f32_e32 v53, v116, v64
	v_fmac_f32_e32 v53, v117, v65
	v_fmac_f32_e32 v53, v118, v66
	v_fmac_f32_e32 v53, v119, v67
	s_waitcnt lgkmcnt(2)
	v_fmac_f32_e32 v53, v120, v68
	v_fmac_f32_e32 v53, v121, v69
	v_fmac_f32_e32 v53, v122, v70
	v_fmac_f32_e32 v53, v123, v71
	s_waitcnt lgkmcnt(1)
	v_fmac_f32_e32 v53, v124, v72
	v_fmac_f32_e32 v53, v125, v73
	v_fmac_f32_e32 v53, v126, v74
	v_fmac_f32_e32 v53, v127, v75
	s_waitcnt lgkmcnt(0)
	v_fmac_f32_e32 v53, v128, v76
	v_fmac_f32_e32 v53, v129, v77
	v_fmac_f32_e32 v53, v130, v78
	v_fmac_f32_e32 v53, v131, v79
	v_min_f32_e32 v132, 0, v53
	v_mul_f32_e64 v53, |v53|, s52
	v_exp_f32_e32 v53, v53
	s_nop 0
	v_add_f32_e32 v53, 1.0, v53
	v_log_f32_e32 v53, v53
	s_nop 0
	v_mul_f32_e32 v133, 0x3f317217, v53
	v_fma_f32 v133, v53, s53, -v133
	v_fmac_f32_e32 v133, 0x3377d1cf, v53
	v_fmac_f32_e32 v133, 0x3f317217, v53
	v_sub_f32_e32 v53, v132, v133
	v_mul_f32_e32 v53, 0x3d800000, v53
	ds_read_b128 v[116:119], v12 offset:2816
	ds_read_b128 v[120:123], v12 offset:2832
	ds_read_b128 v[124:127], v12 offset:2848
	ds_read_b128 v[128:131], v12 offset:2864
	v_mov_b32_e32 v54, v80
	s_waitcnt lgkmcnt(3)
	v_fmac_f32_e32 v54, v116, v64
	v_fmac_f32_e32 v54, v117, v65
	v_fmac_f32_e32 v54, v118, v66
	v_fmac_f32_e32 v54, v119, v67
	s_waitcnt lgkmcnt(2)
	v_fmac_f32_e32 v54, v120, v68
	v_fmac_f32_e32 v54, v121, v69
	v_fmac_f32_e32 v54, v122, v70
	v_fmac_f32_e32 v54, v123, v71
	s_waitcnt lgkmcnt(1)
	v_fmac_f32_e32 v54, v124, v72
	v_fmac_f32_e32 v54, v125, v73
	v_fmac_f32_e32 v54, v126, v74
	v_fmac_f32_e32 v54, v127, v75
	s_waitcnt lgkmcnt(0)
	v_fmac_f32_e32 v54, v128, v76
	v_fmac_f32_e32 v54, v129, v77
	v_fmac_f32_e32 v54, v130, v78
	v_fmac_f32_e32 v54, v131, v79
	v_min_f32_e32 v132, 0, v54
	v_mul_f32_e64 v54, |v54|, s52
	v_exp_f32_e32 v54, v54
	s_nop 0
	v_add_f32_e32 v54, 1.0, v54
	v_log_f32_e32 v54, v54
	s_nop 0
	v_mul_f32_e32 v133, 0x3f317217, v54
	v_fma_f32 v133, v54, s53, -v133
	v_fmac_f32_e32 v133, 0x3377d1cf, v54
	v_fmac_f32_e32 v133, 0x3f317217, v54
	v_sub_f32_e32 v54, v132, v133
	v_mul_f32_e32 v54, 0x3d800000, v54
	ds_read_b128 v[116:119], v12 offset:2944
	ds_read_b128 v[120:123], v12 offset:2960
	ds_read_b128 v[124:127], v12 offset:2976
	ds_read_b128 v[128:131], v12 offset:2992
	v_mov_b32_e32 v55, v80
	s_waitcnt lgkmcnt(3)
; DEVINL float logsig(float z) { return fminf(z, 0.f) - __logf(1.f + __expf(-fabsf(z))); }
; DEVINL void gla_prep_unit(const Params& p, int unit) {
;     ...
;     for (int i = 0; i < 64; ++i) {
;       float z = bias;
; #pragma unroll
;       for (int r = 0; r < 16; ++r) z += afab[i * 32 + dir * 16 + r] * u[r];
;       Gc[i * 128] = logsig(z) * (1.f / 16.f);
;     }
	v_fmac_f32_e32 v55, v116, v64
	v_fmac_f32_e32 v55, v117, v65
	v_fmac_f32_e32 v55, v118, v66
	v_fmac_f32_e32 v55, v119, v67
	s_waitcnt lgkmcnt(2)
	v_fmac_f32_e32 v55, v120, v68
	v_fmac_f32_e32 v55, v121, v69
	v_fmac_f32_e32 v55, v122, v70
	v_fmac_f32_e32 v55, v123, v71
	s_waitcnt lgkmcnt(1)
	v_fmac_f32_e32 v55, v124, v72
	v_fmac_f32_e32 v55, v125, v73
	v_fmac_f32_e32 v55, v126, v74
	v_fmac_f32_e32 v55, v127, v75
	s_waitcnt lgkmcnt(0)
	v_fmac_f32_e32 v55, v128, v76
	v_fmac_f32_e32 v55, v129, v77
	v_fmac_f32_e32 v55, v130, v78
	v_fmac_f32_e32 v55, v131, v79
	v_min_f32_e32 v132, 0, v55
	v_mul_f32_e64 v55, |v55|, s52
	v_exp_f32_e32 v55, v55
	s_nop 0
	v_add_f32_e32 v55, 1.0, v55
	v_log_f32_e32 v55, v55
	s_nop 0
	v_mul_f32_e32 v133, 0x3f317217, v55
	v_fma_f32 v133, v55, s53, -v133
	v_fmac_f32_e32 v133, 0x3377d1cf, v55
	v_fmac_f32_e32 v133, 0x3f317217, v55
	v_sub_f32_e32 v55, v132, v133
	v_mul_f32_e32 v55, 0x3d800000, v55
	ds_read_b128 v[116:119], v12 offset:3072
	ds_read_b128 v[120:123], v12 offset:3088
	ds_read_b128 v[124:127], v12 offset:3104
	ds_read_b128 v[128:131], v12 offset:3120
	v_mov_b32_e32 v56, v80
	s_waitcnt lgkmcnt(3)
	v_fmac_f32_e32 v56, v116, v64
	v_fmac_f32_e32 v56, v117, v65
	v_fmac_f32_e32 v56, v118, v66
	v_fmac_f32_e32 v56, v119, v67
	s_waitcnt lgkmcnt(2)
	v_fmac_f32_e32 v56, v120, v68
	v_fmac_f32_e32 v56, v121, v69
	v_fmac_f32_e32 v56, v122, v70
	v_fmac_f32_e32 v56, v123, v71
	s_waitcnt lgkmcnt(1)
	v_fmac_f32_e32 v56, v124, v72
	v_fmac_f32_e32 v56, v125, v73
	v_fmac_f32_e32 v56, v126, v74
	v_fmac_f32_e32 v56, v127, v75
	s_waitcnt lgkmcnt(0)
	v_fmac_f32_e32 v56, v128, v76
	v_fmac_f32_e32 v56, v129, v77
	v_fmac_f32_e32 v56, v130, v78
	v_fmac_f32_e32 v56, v131, v79
	v_min_f32_e32 v132, 0, v56
	v_mul_f32_e64 v56, |v56|, s52
	v_exp_f32_e32 v56, v56
	s_nop 0
	v_add_f32_e32 v56, 1.0, v56
	v_log_f32_e32 v56, v56
	s_nop 0
	v_mul_f32_e32 v133, 0x3f317217, v56
	v_fma_f32 v133, v56, s53, -v133
	v_fmac_f32_e32 v133, 0x3377d1cf, v56
	v_fmac_f32_e32 v133, 0x3f317217, v56
	v_sub_f32_e32 v56, v132, v133
	v_mul_f32_e32 v56, 0x3d800000, v56
	ds_read_b128 v[116:119], v12 offset:3200
	ds_read_b128 v[120:123], v12 offset:3216
	ds_read_b128 v[124:127], v12 offset:3232
	ds_read_b128 v[128:131], v12 offset:3248
	v_mov_b32_e32 v57, v80
	s_waitcnt lgkmcnt(3)
	v_fmac_f32_e32 v57, v116, v64
	v_fmac_f32_e32 v57, v117, v65
	v_fmac_f32_e32 v57, v118, v66
	v_fmac_f32_e32 v57, v119, v67
	s_waitcnt lgkmcnt(2)
	v_fmac_f32_e32 v57, v120, v68
	v_fmac_f32_e32 v57, v121, v69
	v_fmac_f32_e32 v57, v122, v70
	v_fmac_f32_e32 v57, v123, v71
	s_waitcnt lgkmcnt(1)
	v_fmac_f32_e32 v57, v124, v72
	v_fmac_f32_e32 v57, v125, v73
	v_fmac_f32_e32 v57, v126, v74
	v_fmac_f32_e32 v57, v127, v75
	s_waitcnt lgkmcnt(0)
	v_fmac_f32_e32 v57, v128, v76
	v_fmac_f32_e32 v57, v129, v77
	v_fmac_f32_e32 v57, v130, v78
	v_fmac_f32_e32 v57, v131, v79
	v_min_f32_e32 v132, 0, v57
	v_mul_f32_e64 v57, |v57|, s52
	v_exp_f32_e32 v57, v57
	s_nop 0
	v_add_f32_e32 v57, 1.0, v57
	v_log_f32_e32 v57, v57
	s_nop 0
	v_mul_f32_e32 v133, 0x3f317217, v57
	v_fma_f32 v133, v57, s53, -v133
	v_fmac_f32_e32 v133, 0x3377d1cf, v57
	v_fmac_f32_e32 v133, 0x3f317217, v57
	v_sub_f32_e32 v57, v132, v133
	v_mul_f32_e32 v57, 0x3d800000, v57
	ds_read_b128 v[116:119], v12 offset:3328
	ds_read_b128 v[120:123], v12 offset:3344
	ds_read_b128 v[124:127], v12 offset:3360
	ds_read_b128 v[128:131], v12 offset:3376
	v_mov_b32_e32 v58, v80
	s_waitcnt lgkmcnt(3)
	v_fmac_f32_e32 v58, v116, v64
	v_fmac_f32_e32 v58, v117, v65
	v_fmac_f32_e32 v58, v118, v66
	v_fmac_f32_e32 v58, v119, v67
	s_waitcnt lgkmcnt(2)
	v_fmac_f32_e32 v58, v120, v68
	v_fmac_f32_e32 v58, v121, v69
	v_fmac_f32_e32 v58, v122, v70
	v_fmac_f32_e32 v58, v123, v71
	s_waitcnt lgkmcnt(1)
	v_fmac_f32_e32 v58, v124, v72
	v_fmac_f32_e32 v58, v125, v73
	v_fmac_f32_e32 v58, v126, v74
	v_fmac_f32_e32 v58, v127, v75
	s_waitcnt lgkmcnt(0)
	v_fmac_f32_e32 v58, v128, v76
	v_fmac_f32_e32 v58, v129, v77
	v_fmac_f32_e32 v58, v130, v78
	v_fmac_f32_e32 v58, v131, v79
	v_min_f32_e32 v132, 0, v58
	v_mul_f32_e64 v58, |v58|, s52
	v_exp_f32_e32 v58, v58
	s_nop 0
	v_add_f32_e32 v58, 1.0, v58
	v_log_f32_e32 v58, v58
	s_nop 0
	v_mul_f32_e32 v133, 0x3f317217, v58
	v_fma_f32 v133, v58, s53, -v133
	v_fmac_f32_e32 v133, 0x3377d1cf, v58
	v_fmac_f32_e32 v133, 0x3f317217, v58
	v_sub_f32_e32 v58, v132, v133
	v_mul_f32_e32 v58, 0x3d800000, v58
	ds_read_b128 v[116:119], v12 offset:3456
	ds_read_b128 v[120:123], v12 offset:3472
	ds_read_b128 v[124:127], v12 offset:3488
	ds_read_b128 v[128:131], v12 offset:3504
	v_mov_b32_e32 v59, v80
	s_waitcnt lgkmcnt(3)
	v_fmac_f32_e32 v59, v116, v64
	v_fmac_f32_e32 v59, v117, v65
	v_fmac_f32_e32 v59, v118, v66
	v_fmac_f32_e32 v59, v119, v67
	s_waitcnt lgkmcnt(2)
	v_fmac_f32_e32 v59, v120, v68
	v_fmac_f32_e32 v59, v121, v69
	v_fmac_f32_e32 v59, v122, v70
	v_fmac_f32_e32 v59, v123, v71
	s_waitcnt lgkmcnt(1)
	v_fmac_f32_e32 v59, v124, v72
	v_fmac_f32_e32 v59, v125, v73
	v_fmac_f32_e32 v59, v126, v74
	v_fmac_f32_e32 v59, v127, v75
	s_waitcnt lgkmcnt(0)
	v_fmac_f32_e32 v59, v128, v76
	v_fmac_f32_e32 v59, v129, v77
	v_fmac_f32_e32 v59, v130, v78
	v_fmac_f32_e32 v59, v131, v79
	v_min_f32_e32 v132, 0, v59
	v_mul_f32_e64 v59, |v59|, s52
	v_exp_f32_e32 v59, v59
	s_nop 0
	v_add_f32_e32 v59, 1.0, v59
	v_log_f32_e32 v59, v59
	s_nop 0
	v_mul_f32_e32 v133, 0x3f317217, v59
	v_fma_f32 v133, v59, s53, -v133
	v_fmac_f32_e32 v133, 0x3377d1cf, v59
	v_fmac_f32_e32 v133, 0x3f317217, v59
	v_sub_f32_e32 v59, v132, v133
	v_mul_f32_e32 v59, 0x3d800000, v59
	ds_read_b128 v[116:119], v12 offset:3584
	ds_read_b128 v[120:123], v12 offset:3600
	ds_read_b128 v[124:127], v12 offset:3616
	ds_read_b128 v[128:131], v12 offset:3632
	v_mov_b32_e32 v60, v80
	s_waitcnt lgkmcnt(3)
; DEVINL float logsig(float z) { return fminf(z, 0.f) - __logf(1.f + __expf(-fabsf(z))); }
; DEVINL void gla_prep_unit(const Params& p, int unit) {
;     ...
;     for (int i = 0; i < 64; ++i) {
;       float z = bias;
; #pragma unroll
;       for (int r = 0; r < 16; ++r) z += afab[i * 32 + dir * 16 + r] * u[r];
;       Gc[i * 128] = logsig(z) * (1.f / 16.f);
;     }
;     float run = 0.f;
;     if (dir == 0) { for (int i = 0; i < 64; ++i) { run += Gc[i * 128]; Gc[i * 128] = run; } }
;     else { for (int i = 63; i >= 0; --i) { run += Gc[i * 128]; Gc[i * 128] = run; } }
;     const float bedge = run;
	v_fmac_f32_e32 v60, v116, v64
	v_fmac_f32_e32 v60, v117, v65
	v_fmac_f32_e32 v60, v118, v66
	v_fmac_f32_e32 v60, v119, v67
	s_waitcnt lgkmcnt(2)
	v_fmac_f32_e32 v60, v120, v68
	v_fmac_f32_e32 v60, v121, v69
	v_fmac_f32_e32 v60, v122, v70
	v_fmac_f32_e32 v60, v123, v71
	s_waitcnt lgkmcnt(1)
	v_fmac_f32_e32 v60, v124, v72
	v_fmac_f32_e32 v60, v125, v73
	v_fmac_f32_e32 v60, v126, v74
	v_fmac_f32_e32 v60, v127, v75
	s_waitcnt lgkmcnt(0)
	v_fmac_f32_e32 v60, v128, v76
	v_fmac_f32_e32 v60, v129, v77
	v_fmac_f32_e32 v60, v130, v78
	v_fmac_f32_e32 v60, v131, v79
	v_min_f32_e32 v132, 0, v60
	v_mul_f32_e64 v60, |v60|, s52
	v_exp_f32_e32 v60, v60
	s_nop 0
	v_add_f32_e32 v60, 1.0, v60
	v_log_f32_e32 v60, v60
	s_nop 0
	v_mul_f32_e32 v133, 0x3f317217, v60
	v_fma_f32 v133, v60, s53, -v133
	v_fmac_f32_e32 v133, 0x3377d1cf, v60
	v_fmac_f32_e32 v133, 0x3f317217, v60
	v_sub_f32_e32 v60, v132, v133
	v_mul_f32_e32 v60, 0x3d800000, v60
	ds_read_b128 v[116:119], v12 offset:3712
	ds_read_b128 v[120:123], v12 offset:3728
	ds_read_b128 v[124:127], v12 offset:3744
	ds_read_b128 v[128:131], v12 offset:3760
	v_mov_b32_e32 v61, v80
	s_waitcnt lgkmcnt(3)
	v_fmac_f32_e32 v61, v116, v64
	v_fmac_f32_e32 v61, v117, v65
	v_fmac_f32_e32 v61, v118, v66
	v_fmac_f32_e32 v61, v119, v67
	s_waitcnt lgkmcnt(2)
	v_fmac_f32_e32 v61, v120, v68
	v_fmac_f32_e32 v61, v121, v69
	v_fmac_f32_e32 v61, v122, v70
	v_fmac_f32_e32 v61, v123, v71
	s_waitcnt lgkmcnt(1)
	v_fmac_f32_e32 v61, v124, v72
	v_fmac_f32_e32 v61, v125, v73
	v_fmac_f32_e32 v61, v126, v74
	v_fmac_f32_e32 v61, v127, v75
	s_waitcnt lgkmcnt(0)
	v_fmac_f32_e32 v61, v128, v76
	v_fmac_f32_e32 v61, v129, v77
	v_fmac_f32_e32 v61, v130, v78
	v_fmac_f32_e32 v61, v131, v79
	v_min_f32_e32 v132, 0, v61
	v_mul_f32_e64 v61, |v61|, s52
	v_exp_f32_e32 v61, v61
	s_nop 0
	v_add_f32_e32 v61, 1.0, v61
	v_log_f32_e32 v61, v61
	s_nop 0
	v_mul_f32_e32 v133, 0x3f317217, v61
	v_fma_f32 v133, v61, s53, -v133
	v_fmac_f32_e32 v133, 0x3377d1cf, v61
	v_fmac_f32_e32 v133, 0x3f317217, v61
	v_sub_f32_e32 v61, v132, v133
	v_mul_f32_e32 v61, 0x3d800000, v61
	ds_read_b128 v[116:119], v12 offset:3840
	ds_read_b128 v[120:123], v12 offset:3856
	ds_read_b128 v[124:127], v12 offset:3872
	ds_read_b128 v[128:131], v12 offset:3888
	v_mov_b32_e32 v62, v80
	s_waitcnt lgkmcnt(3)
	v_fmac_f32_e32 v62, v116, v64
	v_fmac_f32_e32 v62, v117, v65
	v_fmac_f32_e32 v62, v118, v66
	v_fmac_f32_e32 v62, v119, v67
	s_waitcnt lgkmcnt(2)
	v_fmac_f32_e32 v62, v120, v68
	v_fmac_f32_e32 v62, v121, v69
	v_fmac_f32_e32 v62, v122, v70
	v_fmac_f32_e32 v62, v123, v71
	s_waitcnt lgkmcnt(1)
	v_fmac_f32_e32 v62, v124, v72
	v_fmac_f32_e32 v62, v125, v73
	v_fmac_f32_e32 v62, v126, v74
	v_fmac_f32_e32 v62, v127, v75
	s_waitcnt lgkmcnt(0)
	v_fmac_f32_e32 v62, v128, v76
	v_fmac_f32_e32 v62, v129, v77
	v_fmac_f32_e32 v62, v130, v78
	v_fmac_f32_e32 v62, v131, v79
	v_min_f32_e32 v132, 0, v62
	v_mul_f32_e64 v62, |v62|, s52
	v_exp_f32_e32 v62, v62
	s_nop 0
	v_add_f32_e32 v62, 1.0, v62
	v_log_f32_e32 v62, v62
	s_nop 0
	v_mul_f32_e32 v133, 0x3f317217, v62
	v_fma_f32 v133, v62, s53, -v133
	v_fmac_f32_e32 v133, 0x3377d1cf, v62
	v_fmac_f32_e32 v133, 0x3f317217, v62
	v_sub_f32_e32 v62, v132, v133
	v_mul_f32_e32 v62, 0x3d800000, v62
	ds_read_b128 v[116:119], v12 offset:3968
	ds_read_b128 v[120:123], v12 offset:3984
	ds_read_b128 v[124:127], v12 offset:4000
	ds_read_b128 v[128:131], v12 offset:4016
	v_mov_b32_e32 v63, v80
	s_waitcnt lgkmcnt(3)
	v_fmac_f32_e32 v63, v116, v64
	v_fmac_f32_e32 v63, v117, v65
	v_fmac_f32_e32 v63, v118, v66
	v_fmac_f32_e32 v63, v119, v67
	s_waitcnt lgkmcnt(2)
	v_fmac_f32_e32 v63, v120, v68
	v_fmac_f32_e32 v63, v121, v69
	v_fmac_f32_e32 v63, v122, v70
	v_fmac_f32_e32 v63, v123, v71
	s_waitcnt lgkmcnt(1)
	v_fmac_f32_e32 v63, v124, v72
	v_fmac_f32_e32 v63, v125, v73
	v_fmac_f32_e32 v63, v126, v74
	v_fmac_f32_e32 v63, v127, v75
	s_waitcnt lgkmcnt(0)
	v_fmac_f32_e32 v63, v128, v76
	v_fmac_f32_e32 v63, v129, v77
	v_fmac_f32_e32 v63, v130, v78
	v_fmac_f32_e32 v63, v131, v79
	v_min_f32_e32 v132, 0, v63
	v_mul_f32_e64 v63, |v63|, s52
	v_exp_f32_e32 v63, v63
	s_nop 0
	v_add_f32_e32 v63, 1.0, v63
	v_log_f32_e32 v63, v63
	s_nop 0
	v_mul_f32_e32 v133, 0x3f317217, v63
	v_fma_f32 v133, v63, s53, -v133
	v_fmac_f32_e32 v133, 0x3377d1cf, v63
	v_fmac_f32_e32 v133, 0x3f317217, v63
	v_sub_f32_e32 v63, v132, v133
	v_mul_f32_e32 v63, 0x3d800000, v63
	s_cmp_eq_u32 s5, 0
	s_cbranch_scc0 .Lgl_tot_b
	v_mov_b32_e32 v134, v32
	v_add_f32_e32 v134, v134, v33
	v_add_f32_e32 v134, v134, v34
	v_add_f32_e32 v134, v134, v35
	v_add_f32_e32 v134, v134, v36
	v_add_f32_e32 v134, v134, v37
	v_add_f32_e32 v134, v134, v38
	v_add_f32_e32 v134, v134, v39
	v_add_f32_e32 v134, v134, v40
	v_add_f32_e32 v134, v134, v41
	v_add_f32_e32 v134, v134, v42
	v_add_f32_e32 v134, v134, v43
	v_add_f32_e32 v134, v134, v44
	v_add_f32_e32 v134, v134, v45
	v_add_f32_e32 v134, v134, v46
	v_add_f32_e32 v134, v134, v47
	v_add_f32_e32 v134, v134, v48
	v_add_f32_e32 v134, v134, v49
	v_add_f32_e32 v134, v134, v50
	v_add_f32_e32 v134, v134, v51
	v_add_f32_e32 v134, v134, v52
	v_add_f32_e32 v134, v134, v53
	v_add_f32_e32 v134, v134, v54
	v_add_f32_e32 v134, v134, v55
	v_add_f32_e32 v134, v134, v56
	v_add_f32_e32 v134, v134, v57
	v_add_f32_e32 v134, v134, v58
	v_add_f32_e32 v134, v134, v59
	v_add_f32_e32 v134, v134, v60
	v_add_f32_e32 v134, v134, v61
	v_add_f32_e32 v134, v134, v62
	v_add_f32_e32 v134, v134, v63
	s_branch .Lgl_tot_e
; DEVINL void gla_prep_unit(const Params& p, int unit) {
;     ...
;     float run = 0.f;
;     if (dir == 0) { for (int i = 0; i < 64; ++i) { run += Gc[i * 128]; Gc[i * 128] = run; } }
;     else { for (int i = 63; i >= 0; --i) { run += Gc[i * 128]; Gc[i * 128] = run; } }
;     const float bedge = run;
;     const long hb = ((long)(dir * 2 + b) * 4 + h);
.Lgl_tot_b:
	v_mov_b32_e32 v134, v63
	v_add_f32_e32 v134, v134, v62
	v_add_f32_e32 v134, v134, v61
	v_add_f32_e32 v134, v134, v60
	v_add_f32_e32 v134, v134, v59
	v_add_f32_e32 v134, v134, v58
	v_add_f32_e32 v134, v134, v57
	v_add_f32_e32 v134, v134, v56
	v_add_f32_e32 v134, v134, v55
	v_add_f32_e32 v134, v134, v54
	v_add_f32_e32 v134, v134, v53
	v_add_f32_e32 v134, v134, v52
	v_add_f32_e32 v134, v134, v51
	v_add_f32_e32 v134, v134, v50
	v_add_f32_e32 v134, v134, v49
	v_add_f32_e32 v134, v134, v48
	v_add_f32_e32 v134, v134, v47
	v_add_f32_e32 v134, v134, v46
	v_add_f32_e32 v134, v134, v45
	v_add_f32_e32 v134, v134, v44
	v_add_f32_e32 v134, v134, v43
	v_add_f32_e32 v134, v134, v42
	v_add_f32_e32 v134, v134, v41
	v_add_f32_e32 v134, v134, v40
	v_add_f32_e32 v134, v134, v39
	v_add_f32_e32 v134, v134, v38
	v_add_f32_e32 v134, v134, v37
	v_add_f32_e32 v134, v134, v36
	v_add_f32_e32 v134, v134, v35
	v_add_f32_e32 v134, v134, v34
	v_add_f32_e32 v134, v134, v33
	v_add_f32_e32 v134, v134, v32
.Lgl_tot_e:
	ds_write_b32 v13, v134
	s_waitcnt lgkmcnt(0)
	s_barrier
	ds_read_b32 v135, v14
	s_waitcnt lgkmcnt(0)
	s_cmp_eq_u32 s40, 0
	s_cbranch_scc0 .Lgl_carry
	v_mov_b32_e32 v135, 0
.Lgl_carry:
	s_cmp_eq_u32 s5, 0
	s_cbranch_scc0 .Lgl_scan_b
	v_add_f32_e32 v135, v135, v32
	v_mov_b32_e32 v32, v135
	v_add_f32_e32 v135, v135, v33
	v_mov_b32_e32 v33, v135
	v_add_f32_e32 v135, v135, v34
	v_mov_b32_e32 v34, v135
	v_add_f32_e32 v135, v135, v35
	v_mov_b32_e32 v35, v135
	v_add_f32_e32 v135, v135, v36
	v_mov_b32_e32 v36, v135
	v_add_f32_e32 v135, v135, v37
	v_mov_b32_e32 v37, v135
	v_add_f32_e32 v135, v135, v38
	v_mov_b32_e32 v38, v135
	v_add_f32_e32 v135, v135, v39
	v_mov_b32_e32 v39, v135
	v_add_f32_e32 v135, v135, v40
	v_mov_b32_e32 v40, v135
	v_add_f32_e32 v135, v135, v41
	v_mov_b32_e32 v41, v135
	v_add_f32_e32 v135, v135, v42
	v_mov_b32_e32 v42, v135
	v_add_f32_e32 v135, v135, v43
	v_mov_b32_e32 v43, v135
	v_add_f32_e32 v135, v135, v44
	v_mov_b32_e32 v44, v135
	v_add_f32_e32 v135, v135, v45
	v_mov_b32_e32 v45, v135
	v_add_f32_e32 v135, v135, v46
	v_mov_b32_e32 v46, v135
	v_add_f32_e32 v135, v135, v47
	v_mov_b32_e32 v47, v135
	v_add_f32_e32 v135, v135, v48
	v_mov_b32_e32 v48, v135
	v_add_f32_e32 v135, v135, v49
	v_mov_b32_e32 v49, v135
	v_add_f32_e32 v135, v135, v50
	v_mov_b32_e32 v50, v135
	v_add_f32_e32 v135, v135, v51
	v_mov_b32_e32 v51, v135
	v_add_f32_e32 v135, v135, v52
	v_mov_b32_e32 v52, v135
	v_add_f32_e32 v135, v135, v53
	v_mov_b32_e32 v53, v135
	v_add_f32_e32 v135, v135, v54
	v_mov_b32_e32 v54, v135
	v_add_f32_e32 v135, v135, v55
	v_mov_b32_e32 v55, v135
	v_add_f32_e32 v135, v135, v56
	v_mov_b32_e32 v56, v135
	v_add_f32_e32 v135, v135, v57
	v_mov_b32_e32 v57, v135
	v_add_f32_e32 v135, v135, v58
	v_mov_b32_e32 v58, v135
	v_add_f32_e32 v135, v135, v59
	v_mov_b32_e32 v59, v135
	v_add_f32_e32 v135, v135, v60
	v_mov_b32_e32 v60, v135
	v_add_f32_e32 v135, v135, v61
	v_mov_b32_e32 v61, v135
	v_add_f32_e32 v135, v135, v62
	v_mov_b32_e32 v62, v135
	v_add_f32_e32 v135, v135, v63
	v_mov_b32_e32 v63, v135
	s_branch .Lgl_scan_e
.Lgl_scan_b:
	v_add_f32_e32 v135, v135, v63
	v_mov_b32_e32 v63, v135
	v_add_f32_e32 v135, v135, v62
	v_mov_b32_e32 v62, v135
	v_add_f32_e32 v135, v135, v61
	v_mov_b32_e32 v61, v135
	v_add_f32_e32 v135, v135, v60
	v_mov_b32_e32 v60, v135
	v_add_f32_e32 v135, v135, v59
	v_mov_b32_e32 v59, v135
	v_add_f32_e32 v135, v135, v58
	v_mov_b32_e32 v58, v135
	v_add_f32_e32 v135, v135, v57
	v_mov_b32_e32 v57, v135
	v_add_f32_e32 v135, v135, v56
	v_mov_b32_e32 v56, v135
	v_add_f32_e32 v135, v135, v55
	v_mov_b32_e32 v55, v135
	v_add_f32_e32 v135, v135, v54
	v_mov_b32_e32 v54, v135
	v_add_f32_e32 v135, v135, v53
	v_mov_b32_e32 v53, v135
	v_add_f32_e32 v135, v135, v52
	v_mov_b32_e32 v52, v135
	v_add_f32_e32 v135, v135, v51
	v_mov_b32_e32 v51, v135
	v_add_f32_e32 v135, v135, v50
	v_mov_b32_e32 v50, v135
	v_add_f32_e32 v135, v135, v49
	v_mov_b32_e32 v49, v135
	v_add_f32_e32 v135, v135, v48
	v_mov_b32_e32 v48, v135
	v_add_f32_e32 v135, v135, v47
	v_mov_b32_e32 v47, v135
	v_add_f32_e32 v135, v135, v46
	v_mov_b32_e32 v46, v135
	v_add_f32_e32 v135, v135, v45
	v_mov_b32_e32 v45, v135
	v_add_f32_e32 v135, v135, v44
	v_mov_b32_e32 v44, v135
	v_add_f32_e32 v135, v135, v43
	v_mov_b32_e32 v43, v135
	v_add_f32_e32 v135, v135, v42
	v_mov_b32_e32 v42, v135
	v_add_f32_e32 v135, v135, v41
	v_mov_b32_e32 v41, v135
	v_add_f32_e32 v135, v135, v40
	v_mov_b32_e32 v40, v135
	v_add_f32_e32 v135, v135, v39
	v_mov_b32_e32 v39, v135
	v_add_f32_e32 v135, v135, v38
	v_mov_b32_e32 v38, v135
	v_add_f32_e32 v135, v135, v37
	v_mov_b32_e32 v37, v135
	v_add_f32_e32 v135, v135, v36
	v_mov_b32_e32 v36, v135
	v_add_f32_e32 v135, v135, v35
	v_mov_b32_e32 v35, v135
	v_add_f32_e32 v135, v135, v34
	v_mov_b32_e32 v34, v135
	v_add_f32_e32 v135, v135, v33
	v_mov_b32_e32 v33, v135
	v_add_f32_e32 v135, v135, v32
	v_mov_b32_e32 v32, v135
.Lgl_scan_e:
	s_cmp_eq_u32 s40, 0
	s_cbranch_scc1 .Lgl_noedge
	ds_write_b32 v15, v135
; DEVINL u16 f2bf(float a) { return (u16)(pk2(a, 0.f) & 0xffffu); }
; DEVINL float bf2f(u16 h) { return __uint_as_float(((unsigned)h) << 16); }
; DEVINL int fragpos(int idx) { const int w = idx & 31; return (idx & ~31) + (((w & 15) >> 2) << 3) + (w & 3) + ((w >> 4) << 2); }
; DEVINL void gla_prep_unit(const Params& p, int unit) {
;     ...
;     ((float*)(ws + O_DEC))[(hb * 64 + c) * 128 + kk] = __expf(bedge);
;     u16* KDr = KD + (dir * 128 + kk) * 72;
;     const unsigned short* qsrc = cols + tok0 * NCP + C_Q + h * 128 + kk;
;     const unsigned short* ksrc = cols + tok0 * NCP + C_K + h * 128 + kk;
; #pragma unroll 1
;     for (int i0 = 0; i0 < 64; i0 += 8) {
;       u16 qv[8], kv[8];
; #pragma unroll
;       for (int j = 0; j < 8; ++j) { qv[j] = qsrc[(long)(i0 + j) * NCP]; kv[j] = ksrc[(long)(i0 + j) * NCP]; }
; #pragma unroll
;       for (int j = 0; j < 8; ++j) {
;         const int i = i0 + j;
;         float bb = Gc[i * 128];
;         float q = bf2f(qv[j]);
;         float k = bf2f(kv[j]);
;         qt[i * 128] = f2bf(q * 0.08838834764831845f * __expf(bb));
;         kt[i * 128] = f2bf(k * __expf(-bb));
;         KDr[fragpos(i)] = f2bf(k * __expf(bedge - bb));
;       }
;     }
.Lgl_noedge:
	s_waitcnt lgkmcnt(0)
	s_barrier
	ds_read_b32 v136, v15
	ds_read_u16 v192, v16 offset:0
	ds_read_u16 v193, v16 offset:256
	ds_read_u16 v194, v16 offset:512
	ds_read_u16 v195, v16 offset:768
	ds_read_u16 v196, v16 offset:1024
	ds_read_u16 v197, v16 offset:1280
	ds_read_u16 v198, v16 offset:1536
	ds_read_u16 v199, v16 offset:1792
	ds_read_u16 v200, v16 offset:2048
	ds_read_u16 v201, v16 offset:2304
	ds_read_u16 v202, v16 offset:2560
	ds_read_u16 v203, v16 offset:2816
	ds_read_u16 v204, v16 offset:3072
	ds_read_u16 v205, v16 offset:3328
	ds_read_u16 v206, v16 offset:3584
	ds_read_u16 v207, v16 offset:3840
	ds_read_u16 v208, v16 offset:4096
	ds_read_u16 v209, v16 offset:4352
	ds_read_u16 v210, v16 offset:4608
	ds_read_u16 v211, v16 offset:4864
	ds_read_u16 v212, v16 offset:5120
	ds_read_u16 v213, v16 offset:5376
	ds_read_u16 v214, v16 offset:5632
	ds_read_u16 v215, v16 offset:5888
	ds_read_u16 v216, v16 offset:6144
	ds_read_u16 v217, v16 offset:6400
	ds_read_u16 v218, v16 offset:6656
	ds_read_u16 v219, v16 offset:6912
	ds_read_u16 v220, v16 offset:7168
	ds_read_u16 v221, v16 offset:7424
	ds_read_u16 v222, v16 offset:7680
	ds_read_u16 v223, v16 offset:7936
	ds_write_b32 v17, v32 offset:0
	ds_write_b32 v17, v33 offset:512
	ds_write_b32 v17, v34 offset:1024
	ds_write_b32 v17, v35 offset:1536
	ds_write_b32 v17, v36 offset:2048
	ds_write_b32 v17, v37 offset:2560
	ds_write_b32 v17, v38 offset:3072
	ds_write_b32 v17, v39 offset:3584
	ds_write_b32 v17, v40 offset:4096
	ds_write_b32 v17, v41 offset:4608
	ds_write_b32 v17, v42 offset:5120
	ds_write_b32 v17, v43 offset:5632
	ds_write_b32 v17, v44 offset:6144
	ds_write_b32 v17, v45 offset:6656
	ds_write_b32 v17, v46 offset:7168
	ds_write_b32 v17, v47 offset:7680
	ds_write_b32 v17, v48 offset:8192
	ds_write_b32 v17, v49 offset:8704
	ds_write_b32 v17, v50 offset:9216
	ds_write_b32 v17, v51 offset:9728
	ds_write_b32 v17, v52 offset:10240
	ds_write_b32 v17, v53 offset:10752
	ds_write_b32 v17, v54 offset:11264
	ds_write_b32 v17, v55 offset:11776
	ds_write_b32 v17, v56 offset:12288
	ds_write_b32 v17, v57 offset:12800
	ds_write_b32 v17, v58 offset:13312
	ds_write_b32 v17, v59 offset:13824
	ds_write_b32 v17, v60 offset:14336
	ds_write_b32 v17, v61 offset:14848
	ds_write_b32 v17, v62 offset:15360
	ds_write_b32 v17, v63 offset:15872
	s_waitcnt lgkmcnt(15)
	s_waitcnt lgkmcnt(0)
	v_sub_f32_e32 v116, v136, v32
	v_mul_f32_e32 v116, 0x3fb8aa3b, v116
	v_exp_f32_e32 v116, v116
	v_lshlrev_b32_e32 v192, 16, v192
	v_mul_f32_e32 v192, v116, v192
	v_sub_f32_e32 v116, v136, v33
	v_mul_f32_e32 v116, 0x3fb8aa3b, v116
	v_exp_f32_e32 v116, v116
	v_lshlrev_b32_e32 v193, 16, v193
	v_mul_f32_e32 v193, v116, v193
	v_sub_f32_e32 v116, v136, v34
	v_mul_f32_e32 v116, 0x3fb8aa3b, v116
	v_exp_f32_e32 v116, v116
	v_lshlrev_b32_e32 v194, 16, v194
	v_mul_f32_e32 v194, v116, v194
	v_sub_f32_e32 v116, v136, v35
	v_mul_f32_e32 v116, 0x3fb8aa3b, v116
	v_exp_f32_e32 v116, v116
	v_lshlrev_b32_e32 v195, 16, v195
	v_mul_f32_e32 v195, v116, v195
	v_sub_f32_e32 v116, v136, v36
	v_mul_f32_e32 v116, 0x3fb8aa3b, v116
	v_exp_f32_e32 v116, v116
	v_lshlrev_b32_e32 v196, 16, v196
	v_mul_f32_e32 v196, v116, v196
	v_sub_f32_e32 v116, v136, v37
	v_mul_f32_e32 v116, 0x3fb8aa3b, v116
	v_exp_f32_e32 v116, v116
	v_lshlrev_b32_e32 v197, 16, v197
	v_mul_f32_e32 v197, v116, v197
	v_sub_f32_e32 v116, v136, v38
	v_mul_f32_e32 v116, 0x3fb8aa3b, v116
	v_exp_f32_e32 v116, v116
	v_lshlrev_b32_e32 v198, 16, v198
	v_mul_f32_e32 v198, v116, v198
	v_sub_f32_e32 v116, v136, v39
	v_mul_f32_e32 v116, 0x3fb8aa3b, v116
	v_exp_f32_e32 v116, v116
	v_lshlrev_b32_e32 v199, 16, v199
	v_mul_f32_e32 v199, v116, v199
	v_sub_f32_e32 v116, v136, v40
	v_mul_f32_e32 v116, 0x3fb8aa3b, v116
	v_exp_f32_e32 v116, v116
	v_lshlrev_b32_e32 v200, 16, v200
	v_mul_f32_e32 v200, v116, v200
	v_sub_f32_e32 v116, v136, v41
	v_mul_f32_e32 v116, 0x3fb8aa3b, v116
	v_exp_f32_e32 v116, v116
	v_lshlrev_b32_e32 v201, 16, v201
	v_mul_f32_e32 v201, v116, v201
	v_sub_f32_e32 v116, v136, v42
	v_mul_f32_e32 v116, 0x3fb8aa3b, v116
	v_exp_f32_e32 v116, v116
	v_lshlrev_b32_e32 v202, 16, v202
	v_mul_f32_e32 v202, v116, v202
	v_sub_f32_e32 v116, v136, v43
	v_mul_f32_e32 v116, 0x3fb8aa3b, v116
	v_exp_f32_e32 v116, v116
	v_lshlrev_b32_e32 v203, 16, v203
	v_mul_f32_e32 v203, v116, v203
	v_sub_f32_e32 v116, v136, v44
	v_mul_f32_e32 v116, 0x3fb8aa3b, v116
	v_exp_f32_e32 v116, v116
	v_lshlrev_b32_e32 v204, 16, v204
	v_mul_f32_e32 v204, v116, v204
	v_sub_f32_e32 v116, v136, v45
	v_mul_f32_e32 v116, 0x3fb8aa3b, v116
	v_exp_f32_e32 v116, v116
	v_lshlrev_b32_e32 v205, 16, v205
	v_mul_f32_e32 v205, v116, v205
	v_sub_f32_e32 v116, v136, v46
	v_mul_f32_e32 v116, 0x3fb8aa3b, v116
	v_exp_f32_e32 v116, v116
	v_lshlrev_b32_e32 v206, 16, v206
	v_mul_f32_e32 v206, v116, v206
	v_sub_f32_e32 v116, v136, v47
	v_mul_f32_e32 v116, 0x3fb8aa3b, v116
	v_exp_f32_e32 v116, v116
	v_lshlrev_b32_e32 v207, 16, v207
	v_mul_f32_e32 v207, v116, v207
	v_sub_f32_e32 v116, v136, v48
	v_mul_f32_e32 v116, 0x3fb8aa3b, v116
	v_exp_f32_e32 v116, v116
	v_lshlrev_b32_e32 v208, 16, v208
	v_mul_f32_e32 v208, v116, v208
	v_sub_f32_e32 v116, v136, v49
	v_mul_f32_e32 v116, 0x3fb8aa3b, v116
	v_exp_f32_e32 v116, v116
	v_lshlrev_b32_e32 v209, 16, v209
	v_mul_f32_e32 v209, v116, v209
	v_sub_f32_e32 v116, v136, v50
	v_mul_f32_e32 v116, 0x3fb8aa3b, v116
	v_exp_f32_e32 v116, v116
	v_lshlrev_b32_e32 v210, 16, v210
	v_mul_f32_e32 v210, v116, v210
	v_sub_f32_e32 v116, v136, v51
	v_mul_f32_e32 v116, 0x3fb8aa3b, v116
	v_exp_f32_e32 v116, v116
	v_lshlrev_b32_e32 v211, 16, v211
	v_mul_f32_e32 v211, v116, v211
	v_sub_f32_e32 v116, v136, v52
	v_mul_f32_e32 v116, 0x3fb8aa3b, v116
; DEVINL u16 f2bf(float a) { return (u16)(pk2(a, 0.f) & 0xffffu); }
; DEVINL float bf2f(u16 h) { return __uint_as_float(((unsigned)h) << 16); }
; DEVINL int fragpos(int idx) { const int w = idx & 31; return (idx & ~31) + (((w & 15) >> 2) << 3) + (w & 3) + ((w >> 4) << 2); }
; DEVINL void gla_prep_unit(const Params& p, int unit) {
;     ...
;     ((float*)(ws + O_DEC))[(hb * 64 + c) * 128 + kk] = __expf(bedge);
;     u16* KDr = KD + (dir * 128 + kk) * 72;
;     const unsigned short* qsrc = cols + tok0 * NCP + C_Q + h * 128 + kk;
;     const unsigned short* ksrc = cols + tok0 * NCP + C_K + h * 128 + kk;
; #pragma unroll 1
;     for (int i0 = 0; i0 < 64; i0 += 8) {
;       u16 qv[8], kv[8];
; #pragma unroll
;       for (int j = 0; j < 8; ++j) { qv[j] = qsrc[(long)(i0 + j) * NCP]; kv[j] = ksrc[(long)(i0 + j) * NCP]; }
; #pragma unroll
;       for (int j = 0; j < 8; ++j) {
;         const int i = i0 + j;
;         float bb = Gc[i * 128];
;         float q = bf2f(qv[j]);
;         float k = bf2f(kv[j]);
;         qt[i * 128] = f2bf(q * 0.08838834764831845f * __expf(bb));
;         kt[i * 128] = f2bf(k * __expf(-bb));
;         KDr[fragpos(i)] = f2bf(k * __expf(bedge - bb));
;       }
;     }
;     ...
;   for (int pc = tid; pc < 4096; pc += 512) {
;     int row = pc >> 3, ch = pc & 7;
;     if (row < 256) {
;       int dir = row >> 7, kk = row & 127;
;       uint4 v = *(const uint4*)(KD + row * 72 + ch * 8);
;       long hb = ((long)(dir * 2 + b) * 4 + h);
;       *(uint4*)((u16*)(ws + O_KDT) + ((hb * 64 + c) * 128 + kk) * 64 + ch * 8) = v;
;     } else {
	v_exp_f32_e32 v116, v116
	v_lshlrev_b32_e32 v212, 16, v212
	v_mul_f32_e32 v212, v116, v212
	v_sub_f32_e32 v116, v136, v53
	v_mul_f32_e32 v116, 0x3fb8aa3b, v116
	v_exp_f32_e32 v116, v116
	v_lshlrev_b32_e32 v213, 16, v213
	v_mul_f32_e32 v213, v116, v213
	v_sub_f32_e32 v116, v136, v54
	v_mul_f32_e32 v116, 0x3fb8aa3b, v116
	v_exp_f32_e32 v116, v116
	v_lshlrev_b32_e32 v214, 16, v214
	v_mul_f32_e32 v214, v116, v214
	v_sub_f32_e32 v116, v136, v55
	v_mul_f32_e32 v116, 0x3fb8aa3b, v116
	v_exp_f32_e32 v116, v116
	v_lshlrev_b32_e32 v215, 16, v215
	v_mul_f32_e32 v215, v116, v215
	v_sub_f32_e32 v116, v136, v56
	v_mul_f32_e32 v116, 0x3fb8aa3b, v116
	v_exp_f32_e32 v116, v116
	v_lshlrev_b32_e32 v216, 16, v216
	v_mul_f32_e32 v216, v116, v216
	v_sub_f32_e32 v116, v136, v57
	v_mul_f32_e32 v116, 0x3fb8aa3b, v116
	v_exp_f32_e32 v116, v116
	v_lshlrev_b32_e32 v217, 16, v217
	v_mul_f32_e32 v217, v116, v217
	v_sub_f32_e32 v116, v136, v58
	v_mul_f32_e32 v116, 0x3fb8aa3b, v116
	v_exp_f32_e32 v116, v116
	v_lshlrev_b32_e32 v218, 16, v218
	v_mul_f32_e32 v218, v116, v218
	v_sub_f32_e32 v116, v136, v59
	v_mul_f32_e32 v116, 0x3fb8aa3b, v116
	v_exp_f32_e32 v116, v116
	v_lshlrev_b32_e32 v219, 16, v219
	v_mul_f32_e32 v219, v116, v219
	v_sub_f32_e32 v116, v136, v60
	v_mul_f32_e32 v116, 0x3fb8aa3b, v116
	v_exp_f32_e32 v116, v116
	v_lshlrev_b32_e32 v220, 16, v220
	v_mul_f32_e32 v220, v116, v220
	v_sub_f32_e32 v116, v136, v61
	v_mul_f32_e32 v116, 0x3fb8aa3b, v116
	v_exp_f32_e32 v116, v116
	v_lshlrev_b32_e32 v221, 16, v221
	v_mul_f32_e32 v221, v116, v221
	v_sub_f32_e32 v116, v136, v62
	v_mul_f32_e32 v116, 0x3fb8aa3b, v116
	v_exp_f32_e32 v116, v116
	v_lshlrev_b32_e32 v222, 16, v222
	v_mul_f32_e32 v222, v116, v222
	v_sub_f32_e32 v116, v136, v63
	v_mul_f32_e32 v116, 0x3fb8aa3b, v116
	v_exp_f32_e32 v116, v116
	v_lshlrev_b32_e32 v223, 16, v223
	v_mul_f32_e32 v223, v116, v223
	v_cvt_pk_bf16_f32 v144, v192, v193
	v_cvt_pk_bf16_f32 v145, v194, v195
	v_cvt_pk_bf16_f32 v146, v208, v209
	v_cvt_pk_bf16_f32 v147, v210, v211
	v_cvt_pk_bf16_f32 v148, v196, v197
	v_cvt_pk_bf16_f32 v149, v198, v199
	v_cvt_pk_bf16_f32 v150, v212, v213
	v_cvt_pk_bf16_f32 v151, v214, v215
	v_cvt_pk_bf16_f32 v152, v200, v201
	v_cvt_pk_bf16_f32 v153, v202, v203
	v_cvt_pk_bf16_f32 v154, v216, v217
	v_cvt_pk_bf16_f32 v155, v218, v219
	v_cvt_pk_bf16_f32 v156, v204, v205
	v_cvt_pk_bf16_f32 v157, v206, v207
	v_cvt_pk_bf16_f32 v158, v220, v221
	v_cvt_pk_bf16_f32 v159, v222, v223
	s_lshl_b32 s48, s5, 1
	s_add_u32 s48, s48, s43
	s_lshl_b32 s48, s48, 2
	s_add_u32 s48, s48, s41
	s_lshl_b32 s56, s48, 6
	s_add_u32 s56, s56, s42
	s_lshl_b32 s57, s56, 14
	s_add_u32 s58, s92, s57
	s_addc_u32 s59, s93, 0
	s_add_u32 s58, s58, 0x19400000
	s_addc_u32 s59, s59, 0
	global_store_dwordx4 v18, v[144:147], s[58:59] offset:0
	global_store_dwordx4 v18, v[148:151], s[58:59] offset:16
	global_store_dwordx4 v18, v[152:155], s[58:59] offset:32
	global_store_dwordx4 v18, v[156:159], s[58:59] offset:48
	s_cmp_eq_u32 s6, 0
	s_cbranch_scc0 .Lgl_nodec
	v_mul_f32_e32 v116, 0x3fb8aa3b, v136
	v_exp_f32_e32 v116, v116
	s_lshl_b32 s57, s56, 9
	s_add_u32 s58, s92, s57
	s_addc_u32 s59, s93, 0
	s_add_u32 s58, s58, 0x1b400000
	s_addc_u32 s59, s59, 0
	global_store_dword v7, v116, s[58:59]
.Lgl_nodec:
	s_waitcnt lgkmcnt(0)
	s_barrier
	s_mov_b32 s56, 0x3db504f3
	ds_read_b128 v[116:119], v22 offset:0
	ds_read_b128 v[120:123], v22 offset:64
	ds_read_b64 v[124:125], v23 offset:0
	ds_read_b64 v[126:127], v23 offset:32
	s_waitcnt lgkmcnt(0)
	v_lshlrev_b32_e32 v128, 16, v124
	v_and_b32_e32 v129, 0xffff0000, v124
	v_lshlrev_b32_e32 v130, 16, v125
	v_and_b32_e32 v131, 0xffff0000, v125
	v_lshlrev_b32_e32 v132, 16, v126
	v_and_b32_e32 v133, 0xffff0000, v126
	v_lshlrev_b32_e32 v134, 16, v127
	v_and_b32_e32 v135, 0xffff0000, v127
	v_mul_f32_e32 v116, 0x3fb8aa3b, v116
	v_exp_f32_e32 v116, v116
	v_mul_f32_e32 v128, s56, v128
	v_mul_f32_e32 v128, v128, v116
	v_mul_f32_e32 v117, 0x3fb8aa3b, v117
	v_exp_f32_e32 v117, v117
	v_mul_f32_e32 v129, s56, v129
	v_mul_f32_e32 v129, v129, v117
	v_mul_f32_e32 v118, 0x3fb8aa3b, v118
	v_exp_f32_e32 v118, v118
	v_mul_f32_e32 v130, s56, v130
	v_mul_f32_e32 v130, v130, v118
	v_mul_f32_e32 v119, 0x3fb8aa3b, v119
	v_exp_f32_e32 v119, v119
	v_mul_f32_e32 v131, s56, v131
	v_mul_f32_e32 v131, v131, v119
	v_mul_f32_e32 v120, 0x3fb8aa3b, v120
	v_exp_f32_e32 v120, v120
	v_mul_f32_e32 v132, s56, v132
	v_mul_f32_e32 v132, v132, v120
	v_mul_f32_e32 v121, 0x3fb8aa3b, v121
	v_exp_f32_e32 v121, v121
	v_mul_f32_e32 v133, s56, v133
	v_mul_f32_e32 v133, v133, v121
	v_mul_f32_e32 v122, 0x3fb8aa3b, v122
	v_exp_f32_e32 v122, v122
	v_mul_f32_e32 v134, s56, v134
	v_mul_f32_e32 v134, v134, v122
	v_mul_f32_e32 v123, 0x3fb8aa3b, v123
	v_exp_f32_e32 v123, v123
	v_mul_f32_e32 v135, s56, v135
	v_mul_f32_e32 v135, v135, v123
	v_cvt_pk_bf16_f32 v140, v128, v129
	v_cvt_pk_bf16_f32 v141, v130, v131
	v_cvt_pk_bf16_f32 v142, v132, v133
	v_cvt_pk_bf16_f32 v143, v134, v135
	s_lshl_b32 s48, s43, 2
	s_add_u32 s48, s48, 0
	s_add_u32 s48, s48, s41
	s_lshl_b32 s48, s48, 20
	s_lshl_b32 s57, s42, 14
	s_add_u32 s48, s48, s57
	s_add_u32 s48, s48, 0
	s_add_u32 s58, s92, s48
	s_addc_u32 s59, s93, 0
	s_add_u32 s58, s58, 0x17400000
	s_addc_u32 s59, s59, 0
	global_store_dwordx4 v2, v[140:143], s[58:59]
	ds_read_b128 v[116:119], v22 offset:16384
	ds_read_b128 v[120:123], v22 offset:16448
	ds_read_b64 v[124:125], v23 offset:8192
	ds_read_b64 v[126:127], v23 offset:8224
	s_waitcnt lgkmcnt(0)
; DEVINL u16 f2bf(float a) { return (u16)(pk2(a, 0.f) & 0xffffu); }
; DEVINL float bf2f(u16 h) { return __uint_as_float(((unsigned)h) << 16); }
; DEVINL int fragpos(int idx) { const int w = idx & 31; return (idx & ~31) + (((w & 15) >> 2) << 3) + (w & 3) + ((w >> 4) << 2); }
; DEVINL void gla_prep_unit(const Params& p, int unit) {
;     ...
;     const long hb = ((long)(dir * 2 + b) * 4 + h);
;     const int pk = fragpos(kk);
;     u16* qt = (u16*)(ws + O_QT) + (hb * 4096 + c * 64) * 128 + pk;
;     u16* kt = (u16*)(ws + O_KT) + (hb * 4096 + c * 64) * 128 + pk;
;     ((float*)(ws + O_DEC))[(hb * 64 + c) * 128 + kk] = __expf(bedge);
;     u16* KDr = KD + (dir * 128 + kk) * 72;
;     const unsigned short* qsrc = cols + tok0 * NCP + C_Q + h * 128 + kk;
;     const unsigned short* ksrc = cols + tok0 * NCP + C_K + h * 128 + kk;
; #pragma unroll 1
;     for (int i0 = 0; i0 < 64; i0 += 8) {
;       u16 qv[8], kv[8];
; #pragma unroll
;       for (int j = 0; j < 8; ++j) { qv[j] = qsrc[(long)(i0 + j) * NCP]; kv[j] = ksrc[(long)(i0 + j) * NCP]; }
; #pragma unroll
;       for (int j = 0; j < 8; ++j) {
;         const int i = i0 + j;
;         float bb = Gc[i * 128];
;         float q = bf2f(qv[j]);
;         float k = bf2f(kv[j]);
;         qt[i * 128] = f2bf(q * 0.08838834764831845f * __expf(bb));
;         kt[i * 128] = f2bf(k * __expf(-bb));
	v_lshlrev_b32_e32 v128, 16, v124
	v_and_b32_e32 v129, 0xffff0000, v124
	v_lshlrev_b32_e32 v130, 16, v125
	v_and_b32_e32 v131, 0xffff0000, v125
	v_lshlrev_b32_e32 v132, 16, v126
	v_and_b32_e32 v133, 0xffff0000, v126
	v_lshlrev_b32_e32 v134, 16, v127
	v_and_b32_e32 v135, 0xffff0000, v127
	v_mul_f32_e32 v116, 0x3fb8aa3b, v116
	v_exp_f32_e32 v116, v116
	v_mul_f32_e32 v128, s56, v128
	v_mul_f32_e32 v128, v128, v116
	v_mul_f32_e32 v117, 0x3fb8aa3b, v117
	v_exp_f32_e32 v117, v117
	v_mul_f32_e32 v129, s56, v129
	v_mul_f32_e32 v129, v129, v117
	v_mul_f32_e32 v118, 0x3fb8aa3b, v118
	v_exp_f32_e32 v118, v118
	v_mul_f32_e32 v130, s56, v130
	v_mul_f32_e32 v130, v130, v118
	v_mul_f32_e32 v119, 0x3fb8aa3b, v119
	v_exp_f32_e32 v119, v119
	v_mul_f32_e32 v131, s56, v131
	v_mul_f32_e32 v131, v131, v119
	v_mul_f32_e32 v120, 0x3fb8aa3b, v120
	v_exp_f32_e32 v120, v120
	v_mul_f32_e32 v132, s56, v132
	v_mul_f32_e32 v132, v132, v120
	v_mul_f32_e32 v121, 0x3fb8aa3b, v121
	v_exp_f32_e32 v121, v121
	v_mul_f32_e32 v133, s56, v133
	v_mul_f32_e32 v133, v133, v121
	v_mul_f32_e32 v122, 0x3fb8aa3b, v122
	v_exp_f32_e32 v122, v122
	v_mul_f32_e32 v134, s56, v134
	v_mul_f32_e32 v134, v134, v122
	v_mul_f32_e32 v123, 0x3fb8aa3b, v123
	v_exp_f32_e32 v123, v123
	v_mul_f32_e32 v135, s56, v135
	v_mul_f32_e32 v135, v135, v123
	v_cvt_pk_bf16_f32 v140, v128, v129
	v_cvt_pk_bf16_f32 v141, v130, v131
	v_cvt_pk_bf16_f32 v142, v132, v133
	v_cvt_pk_bf16_f32 v143, v134, v135
	s_lshl_b32 s48, s43, 2
	s_add_u32 s48, s48, 0
	s_add_u32 s48, s48, s41
	s_lshl_b32 s48, s48, 20
	s_lshl_b32 s57, s42, 14
	s_add_u32 s48, s48, s57
	s_add_u32 s48, s48, 8192
	s_add_u32 s58, s92, s48
	s_addc_u32 s59, s93, 0
	s_add_u32 s58, s58, 0x17400000
	s_addc_u32 s59, s59, 0
	global_store_dwordx4 v2, v[140:143], s[58:59]
	ds_read_b128 v[116:119], v22 offset:0
	ds_read_b128 v[120:123], v22 offset:64
	ds_read_b64 v[124:125], v23 offset:16384
	ds_read_b64 v[126:127], v23 offset:16416
	s_waitcnt lgkmcnt(0)
	v_lshlrev_b32_e32 v128, 16, v124
	v_and_b32_e32 v129, 0xffff0000, v124
	v_lshlrev_b32_e32 v130, 16, v125
	v_and_b32_e32 v131, 0xffff0000, v125
	v_lshlrev_b32_e32 v132, 16, v126
	v_and_b32_e32 v133, 0xffff0000, v126
	v_lshlrev_b32_e32 v134, 16, v127
	v_and_b32_e32 v135, 0xffff0000, v127
	v_mul_f32_e32 v116, 0xbfb8aa3b, v116
	v_exp_f32_e32 v116, v116
	s_nop 0
	v_mul_f32_e32 v128, v116, v128
	v_mul_f32_e32 v117, 0xbfb8aa3b, v117
	v_exp_f32_e32 v117, v117
	s_nop 0
	v_mul_f32_e32 v129, v117, v129
	v_mul_f32_e32 v118, 0xbfb8aa3b, v118
	v_exp_f32_e32 v118, v118
	s_nop 0
	v_mul_f32_e32 v130, v118, v130
	v_mul_f32_e32 v119, 0xbfb8aa3b, v119
	v_exp_f32_e32 v119, v119
	s_nop 0
	v_mul_f32_e32 v131, v119, v131
	v_mul_f32_e32 v120, 0xbfb8aa3b, v120
	v_exp_f32_e32 v120, v120
	s_nop 0
	v_mul_f32_e32 v132, v120, v132
	v_mul_f32_e32 v121, 0xbfb8aa3b, v121
	v_exp_f32_e32 v121, v121
	s_nop 0
	v_mul_f32_e32 v133, v121, v133
	v_mul_f32_e32 v122, 0xbfb8aa3b, v122
	v_exp_f32_e32 v122, v122
	s_nop 0
	v_mul_f32_e32 v134, v122, v134
	v_mul_f32_e32 v123, 0xbfb8aa3b, v123
	v_exp_f32_e32 v123, v123
	s_nop 0
	v_mul_f32_e32 v135, v123, v135
	v_cvt_pk_bf16_f32 v140, v128, v129
	v_cvt_pk_bf16_f32 v141, v130, v131
	v_cvt_pk_bf16_f32 v142, v132, v133
	v_cvt_pk_bf16_f32 v143, v134, v135
	s_lshl_b32 s48, s43, 2
	s_add_u32 s48, s48, 0
	s_add_u32 s48, s48, s41
	s_lshl_b32 s48, s48, 20
	s_lshl_b32 s57, s42, 14
	s_add_u32 s48, s48, s57
	s_add_u32 s48, s48, 0
	s_add_u32 s58, s92, s48
	s_addc_u32 s59, s93, 0
	s_add_u32 s58, s58, 0x18400000
	s_addc_u32 s59, s59, 0
	global_store_dwordx4 v2, v[140:143], s[58:59]
	ds_read_b128 v[116:119], v22 offset:16384
	ds_read_b128 v[120:123], v22 offset:16448
	ds_read_b64 v[124:125], v23 offset:24576
	ds_read_b64 v[126:127], v23 offset:24608
	s_waitcnt lgkmcnt(0)
	v_lshlrev_b32_e32 v128, 16, v124
	v_and_b32_e32 v129, 0xffff0000, v124
	v_lshlrev_b32_e32 v130, 16, v125
	v_and_b32_e32 v131, 0xffff0000, v125
	v_lshlrev_b32_e32 v132, 16, v126
	v_and_b32_e32 v133, 0xffff0000, v126
	v_lshlrev_b32_e32 v134, 16, v127
	v_and_b32_e32 v135, 0xffff0000, v127
	v_mul_f32_e32 v116, 0xbfb8aa3b, v116
	v_exp_f32_e32 v116, v116
	s_nop 0
	v_mul_f32_e32 v128, v116, v128
	v_mul_f32_e32 v117, 0xbfb8aa3b, v117
	v_exp_f32_e32 v117, v117
	s_nop 0
	v_mul_f32_e32 v129, v117, v129
	v_mul_f32_e32 v118, 0xbfb8aa3b, v118
	v_exp_f32_e32 v118, v118
	s_nop 0
	v_mul_f32_e32 v130, v118, v130
	v_mul_f32_e32 v119, 0xbfb8aa3b, v119
	v_exp_f32_e32 v119, v119
	s_nop 0
	v_mul_f32_e32 v131, v119, v131
	v_mul_f32_e32 v120, 0xbfb8aa3b, v120
	v_exp_f32_e32 v120, v120
	s_nop 0
	v_mul_f32_e32 v132, v120, v132
	v_mul_f32_e32 v121, 0xbfb8aa3b, v121
	v_exp_f32_e32 v121, v121
	s_nop 0
	v_mul_f32_e32 v133, v121, v133
	v_mul_f32_e32 v122, 0xbfb8aa3b, v122
	v_exp_f32_e32 v122, v122
	s_nop 0
	v_mul_f32_e32 v134, v122, v134
	v_mul_f32_e32 v123, 0xbfb8aa3b, v123
	v_exp_f32_e32 v123, v123
	s_nop 0
	v_mul_f32_e32 v135, v123, v135
	v_cvt_pk_bf16_f32 v140, v128, v129
	v_cvt_pk_bf16_f32 v141, v130, v131
	v_cvt_pk_bf16_f32 v142, v132, v133
	v_cvt_pk_bf16_f32 v143, v134, v135
	s_lshl_b32 s48, s43, 2
	s_add_u32 s48, s48, 0
	s_add_u32 s48, s48, s41
	s_lshl_b32 s48, s48, 20
	s_lshl_b32 s57, s42, 14
	s_add_u32 s48, s48, s57
	s_add_u32 s48, s48, 8192
	s_add_u32 s58, s92, s48
	s_addc_u32 s59, s93, 0
	s_add_u32 s58, s58, 0x18400000
	s_addc_u32 s59, s59, 0
	global_store_dwordx4 v2, v[140:143], s[58:59]
	ds_read_b128 v[116:119], v22 offset:32768
	ds_read_b128 v[120:123], v22 offset:32832
	ds_read_b64 v[124:125], v23 offset:0
	ds_read_b64 v[126:127], v23 offset:32
	s_waitcnt lgkmcnt(0)
; DEVINL u16 f2bf(float a) { return (u16)(pk2(a, 0.f) & 0xffffu); }
; DEVINL float bf2f(u16 h) { return __uint_as_float(((unsigned)h) << 16); }
; DEVINL int fragpos(int idx) { const int w = idx & 31; return (idx & ~31) + (((w & 15) >> 2) << 3) + (w & 3) + ((w >> 4) << 2); }
; DEVINL void gla_prep_unit(const Params& p, int unit) {
;     ...
;     const long hb = ((long)(dir * 2 + b) * 4 + h);
;     const int pk = fragpos(kk);
;     u16* qt = (u16*)(ws + O_QT) + (hb * 4096 + c * 64) * 128 + pk;
;     u16* kt = (u16*)(ws + O_KT) + (hb * 4096 + c * 64) * 128 + pk;
;     ((float*)(ws + O_DEC))[(hb * 64 + c) * 128 + kk] = __expf(bedge);
;     u16* KDr = KD + (dir * 128 + kk) * 72;
;     const unsigned short* qsrc = cols + tok0 * NCP + C_Q + h * 128 + kk;
;     const unsigned short* ksrc = cols + tok0 * NCP + C_K + h * 128 + kk;
; #pragma unroll 1
;     for (int i0 = 0; i0 < 64; i0 += 8) {
;       u16 qv[8], kv[8];
; #pragma unroll
;       for (int j = 0; j < 8; ++j) { qv[j] = qsrc[(long)(i0 + j) * NCP]; kv[j] = ksrc[(long)(i0 + j) * NCP]; }
; #pragma unroll
;       for (int j = 0; j < 8; ++j) {
;         const int i = i0 + j;
;         float bb = Gc[i * 128];
;         float q = bf2f(qv[j]);
;         float k = bf2f(kv[j]);
;         qt[i * 128] = f2bf(q * 0.08838834764831845f * __expf(bb));
;         kt[i * 128] = f2bf(k * __expf(-bb));
	v_lshlrev_b32_e32 v128, 16, v124
	v_and_b32_e32 v129, 0xffff0000, v124
	v_lshlrev_b32_e32 v130, 16, v125
	v_and_b32_e32 v131, 0xffff0000, v125
	v_lshlrev_b32_e32 v132, 16, v126
	v_and_b32_e32 v133, 0xffff0000, v126
	v_lshlrev_b32_e32 v134, 16, v127
	v_and_b32_e32 v135, 0xffff0000, v127
	v_mul_f32_e32 v116, 0x3fb8aa3b, v116
	v_exp_f32_e32 v116, v116
	v_mul_f32_e32 v128, s56, v128
	v_mul_f32_e32 v128, v128, v116
	v_mul_f32_e32 v117, 0x3fb8aa3b, v117
	v_exp_f32_e32 v117, v117
	v_mul_f32_e32 v129, s56, v129
	v_mul_f32_e32 v129, v129, v117
	v_mul_f32_e32 v118, 0x3fb8aa3b, v118
	v_exp_f32_e32 v118, v118
	v_mul_f32_e32 v130, s56, v130
	v_mul_f32_e32 v130, v130, v118
	v_mul_f32_e32 v119, 0x3fb8aa3b, v119
	v_exp_f32_e32 v119, v119
	v_mul_f32_e32 v131, s56, v131
	v_mul_f32_e32 v131, v131, v119
	v_mul_f32_e32 v120, 0x3fb8aa3b, v120
	v_exp_f32_e32 v120, v120
	v_mul_f32_e32 v132, s56, v132
	v_mul_f32_e32 v132, v132, v120
	v_mul_f32_e32 v121, 0x3fb8aa3b, v121
	v_exp_f32_e32 v121, v121
	v_mul_f32_e32 v133, s56, v133
	v_mul_f32_e32 v133, v133, v121
	v_mul_f32_e32 v122, 0x3fb8aa3b, v122
	v_exp_f32_e32 v122, v122
	v_mul_f32_e32 v134, s56, v134
	v_mul_f32_e32 v134, v134, v122
	v_mul_f32_e32 v123, 0x3fb8aa3b, v123
	v_exp_f32_e32 v123, v123
	v_mul_f32_e32 v135, s56, v135
	v_mul_f32_e32 v135, v135, v123
	v_cvt_pk_bf16_f32 v140, v128, v129
	v_cvt_pk_bf16_f32 v141, v130, v131
	v_cvt_pk_bf16_f32 v142, v132, v133
	v_cvt_pk_bf16_f32 v143, v134, v135
	s_lshl_b32 s48, s43, 2
	s_add_u32 s48, s48, 8
	s_add_u32 s48, s48, s41
	s_lshl_b32 s48, s48, 20
	s_lshl_b32 s57, s42, 14
	s_add_u32 s48, s48, s57
	s_add_u32 s48, s48, 0
	s_add_u32 s58, s92, s48
	s_addc_u32 s59, s93, 0
	s_add_u32 s58, s58, 0x17400000
	s_addc_u32 s59, s59, 0
	global_store_dwordx4 v2, v[140:143], s[58:59]
	ds_read_b128 v[116:119], v22 offset:49152
	ds_read_b128 v[120:123], v22 offset:49216
	ds_read_b64 v[124:125], v23 offset:8192
	ds_read_b64 v[126:127], v23 offset:8224
	s_waitcnt lgkmcnt(0)
	v_lshlrev_b32_e32 v128, 16, v124
	v_and_b32_e32 v129, 0xffff0000, v124
	v_lshlrev_b32_e32 v130, 16, v125
	v_and_b32_e32 v131, 0xffff0000, v125
	v_lshlrev_b32_e32 v132, 16, v126
	v_and_b32_e32 v133, 0xffff0000, v126
	v_lshlrev_b32_e32 v134, 16, v127
	v_and_b32_e32 v135, 0xffff0000, v127
	v_mul_f32_e32 v116, 0x3fb8aa3b, v116
	v_exp_f32_e32 v116, v116
	v_mul_f32_e32 v128, s56, v128
	v_mul_f32_e32 v128, v128, v116
	v_mul_f32_e32 v117, 0x3fb8aa3b, v117
	v_exp_f32_e32 v117, v117
	v_mul_f32_e32 v129, s56, v129
	v_mul_f32_e32 v129, v129, v117
	v_mul_f32_e32 v118, 0x3fb8aa3b, v118
	v_exp_f32_e32 v118, v118
	v_mul_f32_e32 v130, s56, v130
	v_mul_f32_e32 v130, v130, v118
	v_mul_f32_e32 v119, 0x3fb8aa3b, v119
	v_exp_f32_e32 v119, v119
	v_mul_f32_e32 v131, s56, v131
	v_mul_f32_e32 v131, v131, v119
	v_mul_f32_e32 v120, 0x3fb8aa3b, v120
	v_exp_f32_e32 v120, v120
	v_mul_f32_e32 v132, s56, v132
	v_mul_f32_e32 v132, v132, v120
	v_mul_f32_e32 v121, 0x3fb8aa3b, v121
	v_exp_f32_e32 v121, v121
	v_mul_f32_e32 v133, s56, v133
	v_mul_f32_e32 v133, v133, v121
	v_mul_f32_e32 v122, 0x3fb8aa3b, v122
	v_exp_f32_e32 v122, v122
	v_mul_f32_e32 v134, s56, v134
	v_mul_f32_e32 v134, v134, v122
	v_mul_f32_e32 v123, 0x3fb8aa3b, v123
	v_exp_f32_e32 v123, v123
	v_mul_f32_e32 v135, s56, v135
	v_mul_f32_e32 v135, v135, v123
	v_cvt_pk_bf16_f32 v140, v128, v129
	v_cvt_pk_bf16_f32 v141, v130, v131
	v_cvt_pk_bf16_f32 v142, v132, v133
	v_cvt_pk_bf16_f32 v143, v134, v135
	s_lshl_b32 s48, s43, 2
	s_add_u32 s48, s48, 8
	s_add_u32 s48, s48, s41
	s_lshl_b32 s48, s48, 20
	s_lshl_b32 s57, s42, 14
	s_add_u32 s48, s48, s57
	s_add_u32 s48, s48, 8192
	s_add_u32 s58, s92, s48
	s_addc_u32 s59, s93, 0
	s_add_u32 s58, s58, 0x17400000
	s_addc_u32 s59, s59, 0
	global_store_dwordx4 v2, v[140:143], s[58:59]
	ds_read_b128 v[116:119], v22 offset:32768
	ds_read_b128 v[120:123], v22 offset:32832
	ds_read_b64 v[124:125], v23 offset:16384
	ds_read_b64 v[126:127], v23 offset:16416
	s_waitcnt lgkmcnt(0)
; DEVINL u16 f2bf(float a) { return (u16)(pk2(a, 0.f) & 0xffffu); }
; DEVINL float bf2f(u16 h) { return __uint_as_float(((unsigned)h) << 16); }
; DEVINL int otid() { int t = threadIdx.x; asm volatile("" : "+v"(t)); return t; }
; DEVINL void gla_prep_unit(const Params& p, int unit) {
;     ...
;         float bb = Gc[i * 128];
;         float q = bf2f(qv[j]);
;         float k = bf2f(kv[j]);
;         qt[i * 128] = f2bf(q * 0.08838834764831845f * __expf(bb));
;         kt[i * 128] = f2bf(k * __expf(-bb));
; DEVINL void phase2(const Params& p) {
;   const int bid = blockIdx.x, nb = gridDim.x, tid = otid();
;   for (int u = bid; u < 512; u += nb) gla_prep_unit(p, u);
;   for (int u = bid; u < 256; u += nb) rw_prep_unit(p, u);
; }
	v_lshlrev_b32_e32 v128, 16, v124
	v_and_b32_e32 v129, 0xffff0000, v124
	v_lshlrev_b32_e32 v130, 16, v125
	v_and_b32_e32 v131, 0xffff0000, v125
	v_lshlrev_b32_e32 v132, 16, v126
	v_and_b32_e32 v133, 0xffff0000, v126
	v_lshlrev_b32_e32 v134, 16, v127
	v_and_b32_e32 v135, 0xffff0000, v127
	v_mul_f32_e32 v116, 0xbfb8aa3b, v116
	v_exp_f32_e32 v116, v116
	s_nop 0
	v_mul_f32_e32 v128, v116, v128
	v_mul_f32_e32 v117, 0xbfb8aa3b, v117
	v_exp_f32_e32 v117, v117
	s_nop 0
	v_mul_f32_e32 v129, v117, v129
	v_mul_f32_e32 v118, 0xbfb8aa3b, v118
	v_exp_f32_e32 v118, v118
	s_nop 0
	v_mul_f32_e32 v130, v118, v130
	v_mul_f32_e32 v119, 0xbfb8aa3b, v119
	v_exp_f32_e32 v119, v119
	s_nop 0
	v_mul_f32_e32 v131, v119, v131
	v_mul_f32_e32 v120, 0xbfb8aa3b, v120
	v_exp_f32_e32 v120, v120
	s_nop 0
	v_mul_f32_e32 v132, v120, v132
	v_mul_f32_e32 v121, 0xbfb8aa3b, v121
	v_exp_f32_e32 v121, v121
	s_nop 0
	v_mul_f32_e32 v133, v121, v133
	v_mul_f32_e32 v122, 0xbfb8aa3b, v122
	v_exp_f32_e32 v122, v122
	s_nop 0
	v_mul_f32_e32 v134, v122, v134
	v_mul_f32_e32 v123, 0xbfb8aa3b, v123
	v_exp_f32_e32 v123, v123
	s_nop 0
	v_mul_f32_e32 v135, v123, v135
	v_cvt_pk_bf16_f32 v140, v128, v129
	v_cvt_pk_bf16_f32 v141, v130, v131
	v_cvt_pk_bf16_f32 v142, v132, v133
	v_cvt_pk_bf16_f32 v143, v134, v135
	s_lshl_b32 s48, s43, 2
	s_add_u32 s48, s48, 8
	s_add_u32 s48, s48, s41
	s_lshl_b32 s48, s48, 20
	s_lshl_b32 s57, s42, 14
	s_add_u32 s48, s48, s57
	s_add_u32 s48, s48, 0
	s_add_u32 s58, s92, s48
	s_addc_u32 s59, s93, 0
	s_add_u32 s58, s58, 0x18400000
	s_addc_u32 s59, s59, 0
	global_store_dwordx4 v2, v[140:143], s[58:59]
	ds_read_b128 v[116:119], v22 offset:49152
	ds_read_b128 v[120:123], v22 offset:49216
	ds_read_b64 v[124:125], v23 offset:24576
	ds_read_b64 v[126:127], v23 offset:24608
	s_waitcnt lgkmcnt(0)
	v_lshlrev_b32_e32 v128, 16, v124
	v_and_b32_e32 v129, 0xffff0000, v124
	v_lshlrev_b32_e32 v130, 16, v125
	v_and_b32_e32 v131, 0xffff0000, v125
	v_lshlrev_b32_e32 v132, 16, v126
	v_and_b32_e32 v133, 0xffff0000, v126
	v_lshlrev_b32_e32 v134, 16, v127
	v_and_b32_e32 v135, 0xffff0000, v127
	v_mul_f32_e32 v116, 0xbfb8aa3b, v116
	v_exp_f32_e32 v116, v116
	s_nop 0
	v_mul_f32_e32 v128, v116, v128
	v_mul_f32_e32 v117, 0xbfb8aa3b, v117
	v_exp_f32_e32 v117, v117
	s_nop 0
	v_mul_f32_e32 v129, v117, v129
	v_mul_f32_e32 v118, 0xbfb8aa3b, v118
	v_exp_f32_e32 v118, v118
	s_nop 0
	v_mul_f32_e32 v130, v118, v130
	v_mul_f32_e32 v119, 0xbfb8aa3b, v119
	v_exp_f32_e32 v119, v119
	s_nop 0
	v_mul_f32_e32 v131, v119, v131
	v_mul_f32_e32 v120, 0xbfb8aa3b, v120
	v_exp_f32_e32 v120, v120
	s_nop 0
	v_mul_f32_e32 v132, v120, v132
	v_mul_f32_e32 v121, 0xbfb8aa3b, v121
	v_exp_f32_e32 v121, v121
	s_nop 0
	v_mul_f32_e32 v133, v121, v133
	v_mul_f32_e32 v122, 0xbfb8aa3b, v122
	v_exp_f32_e32 v122, v122
	s_nop 0
	v_mul_f32_e32 v134, v122, v134
	v_mul_f32_e32 v123, 0xbfb8aa3b, v123
	v_exp_f32_e32 v123, v123
	s_nop 0
	v_mul_f32_e32 v135, v123, v135
	v_cvt_pk_bf16_f32 v140, v128, v129
	v_cvt_pk_bf16_f32 v141, v130, v131
	v_cvt_pk_bf16_f32 v142, v132, v133
	v_cvt_pk_bf16_f32 v143, v134, v135
	s_lshl_b32 s48, s43, 2
	s_add_u32 s48, s48, 8
	s_add_u32 s48, s48, s41
	s_lshl_b32 s48, s48, 20
	s_lshl_b32 s57, s42, 14
	s_add_u32 s48, s48, s57
	s_add_u32 s48, s48, 8192
	s_add_u32 s58, s92, s48
	s_addc_u32 s59, s93, 0
	s_add_u32 s58, s58, 0x18400000
	s_addc_u32 s59, s59, 0
	global_store_dwordx4 v2, v[140:143], s[58:59]
	s_barrier
	s_add_u32 s3, s3, s94
	s_branch .Lgl_unit
.Lgl_done:
.LBB0_334:
	v_readlane_b32 s0, v254, 18
	v_readlane_b32 s1, v254, 19
	s_andn2_b64 vcc, exec, s[0:1]
	s_nop 0
	v_cndmask_b32_e64 v0, 0, 1, s[0:1]
	v_cmp_ne_u32_e64 s[4:5], 1, v0
	s_cbranch_vccnz .LBB0_387
	s_add_u32 s18, s92, 0x4c00000
	s_addc_u32 s19, s93, 0
	s_add_u32 s22, s92, 0x1f520000
	s_addc_u32 s23, s93, 0
	s_add_u32 s24, s92, 0x1f540000
	s_addc_u32 s25, s93, 0
	s_add_u32 s36, s92, 0xf400000
	s_addc_u32 s37, s93, 0
	s_add_u32 s38, s92, 0x1c500000
	s_addc_u32 s39, s93, 0
	s_add_u32 s70, s92, 0x1d500000
	s_addc_u32 s71, s93, 0
	s_add_u32 s72, s90, 0x1000
	s_addc_u32 s73, s91, 0
	s_add_u32 s78, s90, 0x2000
	s_addc_u32 s79, s91, 0
	s_lshl_b32 s3, s2, 5
	s_lshl_b32 s42, s94, 5
	s_mov_b32 s43, 0x66666667
	s_movk_i32 s44, 0xfff
	s_movk_i32 s45, 0x2a00
	s_movk_i32 s46, 0x3000
	s_movk_i32 s47, 0x7f
	s_movk_i32 s48, 0xbf
	v_mov_b32_e32 v97, 0
	s_movk_i32 s49, 0x5400
	s_mov_b32 s50, 0xf800000
	v_mov_b32_e32 v179, 0x260
	s_mov_b32 s51, s2

; DEVINL u16 f2bf(float a) { return (u16)(pk2(a, 0.f) & 0xffffu); }
; DEVINL float sigm(float x) { return 1.f / (1.f + __expf(-x)); }
; DEVINL void rw_prep_unit(const Params& p, int unit) {
;     ...
;         const unsigned reco = ((unsigned)((b * 16 + head) * 4096 + s)) * 1024u;
;         const unsigned tco = (unsigned)t * 2048u + c0 * 2u;
;         unsigned hwf[4], hwb[4], ha[4], hb[4], hk[4], hr[4], hv[4], bg[4], bbn[4];
; #pragma unroll
;         for (int n = 0; n < 4; ++n) {
;           float wf = __expf(-0.606531f * sigm(w0f[n] + sel4(awf[n], j)));
;           float wb = __expf(-0.606531f * sigm(w0b[n] + sel4(awb[n], j)));
;           float kkn = kkv[n] * inv;
;           hwf[n] = f2h(wf); hwb[n] = f2h(wb); ha[n] = f2h(-kkn); hb[n] = f2h(kkn * av[n]);
;           hk[n] = f2h(pk[n]); hr[n] = f2h(pr[n]); hv[n] = f2h(pv[n]);
;           bg[n] = f2bf(sel4(ag[n], j)); bbn[n] = f2bf(dot * pv[n]);
;         }
;         char* rb = ws + O_REC + (reco + (unsigned)l15 * 64u);
.LBB0_380:
	s_or_b64 exec, exec, s[6:7]
	v_bfe_u32 v0, v2, 4, 2
	v_and_b32_e32 v180, 15, v2
	v_ashrrev_i32_e32 v1, 5, v2
	v_lshlrev_b32_e32 v182, 4, v0
	v_and_b32_e32 v181, -2, v1
	v_add_u32_e32 v183, 16, v182
	v_lshlrev_b32_e32 v184, 2, v180
	v_lshl_or_b32 v185, v0, 2, s52
	v_lshlrev_b32_e32 v186, 4, v180
	v_or_b32_e32 v187, 64, v182
	v_or_b32_e32 v188, 0x80, v182
	v_or_b32_e32 v190, 0xc0, v182
	s_mov_b32 s6, 0
	s_mov_b64 s[0:1], -1
	s_waitcnt lgkmcnt(0)
	s_barrier

; DEVINL float bflo(unsigned u) { return __uint_as_float(u << 16); }
; DEVINL float bfhi(unsigned u) { return __uint_as_float(u & 0xffff0000u); }
; DEVINL void rw_shift4(const char* colsb, float4 mu, unsigned o, int s, float (&out)[4]) {
;   const unsigned op = (s > 0) ? o - (unsigned)(NCP * 2) : o;
;   const unsigned on = (s < S_ - 1) ? o + (unsigned)(NCP * 2) : o;
;   const uint2 c = *(const uint2*)(colsb + o);
;   uint2 pv = *(const uint2*)(colsb + op);
;   uint2 nx = *(const uint2*)(colsb + on);
;   if (s == 0) pv = make_uint2(0u, 0u);
;   if (s == S_ - 1) nx = make_uint2(0u, 0u);
;   const float cu[4] = {bflo(c.x), bfhi(c.x), bflo(c.y), bfhi(c.y)};
;   const float pr[4] = {bflo(pv.x), bfhi(pv.x), bflo(pv.y), bfhi(pv.y)};
;   const float nn[4] = {bflo(nx.x), bfhi(nx.x), bflo(nx.y), bfhi(nx.y)};
;   const float m[4] = {mu.x, mu.y, mu.z, mu.w};
; #pragma unroll
;   for (int e = 0; e < 4; ++e) out[e] = cu[e] + m[e] * (0.5f * (pr[e] + nn[e]) - cu[e]);
; }
; DEVINL void rw_prep_unit(const Params& p, int unit) {
;     ...
;         const int t = tok0 + mt * 16 + 4 * g + jo;
;         const int s = t & (S_ - 1), b = t >> 12;
;         const unsigned c0 = (unsigned)(head * 64 + l15 * 4 + zo);
;         const unsigned rowo = (unsigned)t * (unsigned)(NCP * 2) + (unsigned)(C_RW * 2) + c0 * 2u;
;         float pr[4], pkr[4], pv[4];
;         rw_shift4(colsb, *(const float4*)(p.rw_mu + c0), rowo, s, pr);
;         rw_shift4(colsb, *(const float4*)(p.rw_mu + 1024u + c0), rowo + 2048u, s, pkr);
;         rw_shift4(colsb, *(const float4*)(p.rw_mu + 2048u + c0), rowo + 4096u, s, pv);
;         const float4 a0q = *(const float4*)(p.rw_a0 + c0), kkq = *(const float4*)(p.rw_k_k + c0);
;         const float4 kaq = *(const float4*)(p.rw_k_a + c0), rkq = *(const float4*)(p.rw_r_k + c0);
.LBB0_383:
	s_nop 0
	v_mov_b32_e32 v64, s40
	v_mov_b32_e32 v65, 0
	s_cmp_eq_u32 s40, 2
	v_add_u32_e32 v96, v65, v192
	v_add_u32_e32 v194, v193, v64
	v_lshlrev_b32_e32 v178, 1, v96
	v_and_b32_e32 v212, 0xfff, v194
	v_mad_u64_u32 v[72:73], s[0:1], v194, s49, v[178:179]
	v_add_u32_e32 v68, 0x1840, v72
	v_lshlrev_b64 v[74:75], 2, v[96:97]
	v_cmp_eq_u32_e32 vcc, 0, v212
	v_add_u32_e32 v69, 0xffffc440, v72
	v_lshl_add_u64 v[64:65], s[90:91], 0, v[74:75]
	v_cndmask_b32_e32 v70, v69, v68, vcc
	v_cmp_eq_u32_e64 s[0:1], s44, v212
	v_add_u32_e32 v69, 0x6c40, v72
	global_load_dwordx4 v[64:67], v[64:65], off
	v_cndmask_b32_e64 v73, v69, v68, s[0:1]
	global_load_dwordx2 v[68:69], v68, s[18:19]
	s_nop 0
	global_load_dwordx2 v[70:71], v70, s[18:19]
	s_nop 0
	global_load_dwordx2 v[76:77], v73, s[18:19]
	s_cselect_b64 s[6:7], -1, 0
	s_cmp_eq_u32 s40, 0
	s_cselect_b64 s[8:9], -1, 0
	v_cndmask_b32_e64 v223, v11, v10, s[6:7]
	v_cndmask_b32_e64 v223, v223, v8, s[8:9]
	s_waitcnt vmcnt(2)
	v_lshlrev_b32_e32 v209, 16, v68
	s_waitcnt vmcnt(1)
	v_cndmask_b32_e64 v70, v70, 0, vcc
	s_waitcnt vmcnt(0)
	v_cndmask_b32_e64 v73, v76, 0, s[0:1]
	v_cndmask_b32_e64 v76, v77, 0, s[0:1]
	v_and_b32_e32 v203, 0xffff0000, v68
	v_lshlrev_b32_e32 v68, 16, v70
	v_lshlrev_b32_e32 v77, 16, v73
	v_cndmask_b32_e64 v71, v71, 0, vcc
	v_lshlrev_b32_e32 v197, 16, v69
	v_and_b32_e32 v96, 0xffff0000, v69
	v_and_b32_e32 v69, 0xffff0000, v70
	v_and_b32_e32 v73, 0xffff0000, v73
	v_add_f32_e32 v68, v68, v77
	v_lshlrev_b32_e32 v70, 16, v71
	v_lshlrev_b32_e32 v78, 16, v76
	v_fma_f32 v210, v68, 0.5, -v209
	v_add_f32_e32 v68, v69, v73
	v_and_b32_e32 v71, 0xffff0000, v71
	v_and_b32_e32 v76, 0xffff0000, v76
	v_fma_f32 v204, v68, 0.5, -v203
	v_add_f32_e32 v68, v70, v78
	v_fma_f32 v198, v68, 0.5, -v197
	v_add_f32_e32 v68, v71, v76
	v_add_u32_e32 v73, 0x2040, v72
	v_add_u32_e32 v76, 0xffffcc40, v72
	v_cndmask_b32_e32 v78, v76, v73, vcc
	v_add_u32_e32 v76, 0x7440, v72
	v_fma_f32 v195, v68, 0.5, -v96
	v_lshl_add_u64 v[68:69], s[72:73], 0, v[74:75]
	v_cndmask_b32_e64 v80, v76, v73, s[0:1]
	global_load_dwordx4 v[68:71], v[68:69], off
	s_nop 0
	global_load_dwordx2 v[76:77], v73, s[18:19]
	s_nop 0
	global_load_dwordx2 v[78:79], v78, s[18:19]
	s_nop 0
	global_load_dwordx2 v[80:81], v80, s[18:19]
	v_fma_f32 v222, v64, v210, v209
	v_fma_f32 v221, v65, v204, v203
	v_fma_f32 v220, v66, v198, v197
	v_fma_f32 v219, v67, v195, v96
	s_waitcnt vmcnt(2)
	v_lshlrev_b32_e32 v215, 16, v76
	s_waitcnt vmcnt(1)
	v_cndmask_b32_e64 v73, v78, 0, vcc
	v_cndmask_b32_e64 v78, v79, 0, vcc
	s_waitcnt vmcnt(0)
	v_cndmask_b32_e64 v79, v80, 0, s[0:1]
	v_cndmask_b32_e64 v80, v81, 0, s[0:1]
	v_and_b32_e32 v208, 0xffff0000, v76
	v_lshlrev_b32_e32 v76, 16, v73
	v_lshlrev_b32_e32 v81, 16, v79
	v_add_f32_e32 v76, v76, v81
	v_and_b32_e32 v73, 0xffff0000, v73
	v_and_b32_e32 v79, 0xffff0000, v79
	v_fma_f32 v76, v76, 0.5, -v215
	v_fmac_f32_e32 v215, v68, v76
	v_add_f32_e32 v68, v73, v79
	v_lshlrev_b32_e32 v201, 16, v77
	v_and_b32_e32 v196, 0xffff0000, v77
	v_lshlrev_b32_e32 v77, 16, v78
	v_lshlrev_b32_e32 v82, 16, v80
	v_fma_f32 v68, v68, 0.5, -v208
	v_fmac_f32_e32 v208, v69, v68
	v_add_f32_e32 v68, v77, v82
	v_and_b32_e32 v78, 0xffff0000, v78
	v_and_b32_e32 v80, 0xffff0000, v80
	v_fma_f32 v68, v68, 0.5, -v201
	v_fmac_f32_e32 v201, v70, v68
	v_add_f32_e32 v68, v78, v80
	v_fma_f32 v68, v68, 0.5, -v196
	v_add_u32_e32 v73, 0x2840, v72
	v_add_u32_e32 v76, 0xffffd440, v72
	v_add_u32_e32 v72, 0x7c40, v72
	v_fmac_f32_e32 v196, v71, v68
	v_lshl_add_u64 v[68:69], s[78:79], 0, v[74:75]
	v_cndmask_b32_e32 v76, v76, v73, vcc
	v_cndmask_b32_e64 v78, v72, v73, s[0:1]
	global_load_dwordx4 v[68:71], v[68:69], off
	s_nop 0
	global_load_dwordx2 v[72:73], v73, s[18:19]
	s_nop 0
	global_load_dwordx2 v[76:77], v76, s[18:19]
	s_nop 0
	global_load_dwordx2 v[78:79], v78, s[18:19]
	s_waitcnt vmcnt(2)
	v_lshlrev_b32_e32 v216, 16, v72
	s_waitcnt vmcnt(1)
	v_cndmask_b32_e64 v76, v76, 0, vcc
	s_waitcnt vmcnt(0)
	v_cndmask_b32_e64 v78, v78, 0, s[0:1]
	v_and_b32_e32 v211, 0xffff0000, v72
	v_lshlrev_b32_e32 v72, 16, v76
	v_lshlrev_b32_e32 v80, 16, v78
	v_cndmask_b32_e64 v77, v77, 0, vcc
	v_cndmask_b32_e64 v79, v79, 0, s[0:1]
	v_lshlrev_b32_e32 v205, 16, v73
	v_and_b32_e32 v199, 0xffff0000, v73
	v_and_b32_e32 v73, 0xffff0000, v76
	v_and_b32_e32 v78, 0xffff0000, v78
	v_add_f32_e32 v72, v72, v80
	v_lshlrev_b32_e32 v76, 16, v77
	v_lshlrev_b32_e32 v81, 16, v79
	v_fma_f32 v218, v72, 0.5, -v216
	v_add_f32_e32 v72, v73, v78
	v_and_b32_e32 v77, 0xffff0000, v77
	v_and_b32_e32 v79, 0xffff0000, v79
	v_fma_f32 v214, v72, 0.5, -v211
	v_add_f32_e32 v72, v76, v81
	v_fma_f32 v207, v72, 0.5, -v205
	v_add_f32_e32 v72, v77, v79
	v_fma_f32 v202, v72, 0.5, -v199
	v_lshl_add_u64 v[72:73], s[20:21], 0, v[74:75]
	global_load_dwordx4 v[92:95], v[72:73], off
	v_lshl_add_u64 v[72:73], s[26:27], 0, v[74:75]
	global_load_dwordx4 v[88:91], v[72:73], off
	v_lshl_add_u64 v[72:73], s[60:61], 0, v[74:75]
	global_load_dwordx4 v[84:87], v[72:73], off
	v_lshl_add_u64 v[72:73], s[62:63], 0, v[74:75]
	global_load_dwordx4 v[80:83], v[72:73], off
	v_lshl_add_u64 v[72:73], s[12:13], 0, v[74:75]
	global_load_dwordx4 v[76:79], v[72:73], off
	v_lshl_add_u64 v[72:73], s[16:17], 0, v[74:75]
	global_load_dwordx4 v[72:75], v[72:73], off
	v_fma_f32 v217, v68, v218, v216
	v_fma_mixlo_f16 v68, v68, v218, v216
	v_fma_f32 v213, v69, v214, v211
	v_fma_mixlo_f16 v69, v69, v214, v211
	v_fma_f32 v206, v70, v207, v205
	v_fma_mixlo_f16 v70, v70, v207, v205
	v_fma_f32 v200, v71, v202, v199
	v_fma_mixlo_f16 v71, v71, v202, v199
	s_waitcnt vmcnt(5)
	v_add_f32_e32 v92, v92, v223
	v_mul_f32_e32 v92, 0xbfb8aa3b, v92
	v_exp_f32_e32 v92, v92
	s_waitcnt vmcnt(4)
; DEVINL float sigm(float x) { return 1.f / (1.f + __expf(-x)); }
; DEVINL void rw_prep_unit(const Params& p, int unit) {
;     ...
;         float pk[4], av[4], kkv[4];
;         float n2 = 0.f, dot = 0.f;
; #pragma unroll
;         for (int n = 0; n < 4; ++n) {
;           const float kraw = pkr[n];
;           float a = sigm(a0v[n] + sel4(aa[n], j));
;           av[n] = a;
;           float kk = kraw * kkp[n];
;           kkv[n] = kk;
;           n2 += kk * kk;
;           float k2 = kraw * (1.f + (a - 1.f) * kap[n]);
;           pk[n] = k2;
;           dot += pr[n] * k2 * rkp[n];
;         }
;         n2 = allred16(n2);
;         dot = allred16(dot);
;         const float inv = 1.f / fmaxf(sqrtf(n2), 1e-12f);
	v_mul_f32_e32 v89, v208, v89
	v_mul_f32_e32 v88, v215, v88
	v_mul_f32_e32 v90, v201, v90
	v_add_f32_e32 v92, 1.0, v92
	v_div_scale_f32 v223, s[0:1], v92, v92, 1.0
	v_rcp_f32_e32 v224, v223
	v_mul_f32_e32 v91, v196, v91
	v_fma_f32 v225, -v223, v224, 1.0
	v_fmac_f32_e32 v224, v225, v224
	v_div_scale_f32 v225, vcc, 1.0, v92, 1.0
	v_mul_f32_e32 v226, v225, v224
	v_fma_f32 v227, -v223, v226, v225
	v_fmac_f32_e32 v226, v227, v224
	v_fma_f32 v223, -v223, v226, v225
	v_div_fmas_f32 v223, v223, v224, v226
	v_div_fixup_f32 v92, v223, v92, 1.0
	v_add_f32_e32 v223, -1.0, v92
	s_waitcnt vmcnt(3)
	v_fma_f32 v84, v84, v223, 1.0
	v_mul_f32_e32 v223, v215, v84
	v_mul_f32_e32 v222, v222, v223
	s_waitcnt vmcnt(2)
	v_fma_f32 v80, v80, v222, 0
	v_cndmask_b32_e64 v222, v23, v22, s[6:7]
	v_cndmask_b32_e64 v222, v222, v20, s[8:9]
	v_add_f32_e32 v93, v93, v222
	v_mul_f32_e32 v93, 0xbfb8aa3b, v93
	v_exp_f32_e32 v93, v93
	v_fma_mixlo_f16 v84, v215, v84, 0
	v_add_f32_e32 v93, 1.0, v93
	v_div_scale_f32 v222, s[0:1], v93, v93, 1.0
	v_rcp_f32_e32 v223, v222
	s_nop 0
	v_fma_f32 v224, -v222, v223, 1.0
	v_fmac_f32_e32 v223, v224, v223
	v_div_scale_f32 v224, vcc, 1.0, v93, 1.0
	v_mul_f32_e32 v225, v224, v223
	v_fma_f32 v226, -v222, v225, v224
	v_fmac_f32_e32 v225, v226, v223
	v_fma_f32 v222, -v222, v225, v224
	v_div_fmas_f32 v222, v222, v223, v225
	v_div_fixup_f32 v93, v222, v93, 1.0
	v_add_f32_e32 v223, -1.0, v93
	v_fma_f32 v85, v85, v223, 1.0
	v_mul_f32_e32 v223, v208, v85
	v_mul_f32_e32 v221, v221, v223
	v_fmac_f32_e32 v80, v81, v221
	v_cndmask_b32_e64 v81, v35, v34, s[6:7]
	v_cndmask_b32_e64 v81, v81, v32, s[8:9]
	v_add_f32_e32 v81, v94, v81
	v_mul_f32_e32 v81, 0xbfb8aa3b, v81
	v_exp_f32_e32 v81, v81
	v_mul_f32_e32 v222, v89, v89
	v_fmac_f32_e32 v222, v88, v88
	v_fmac_f32_e32 v222, v90, v90
	v_add_f32_e32 v81, 1.0, v81
	v_div_scale_f32 v94, s[0:1], v81, v81, 1.0
	v_rcp_f32_e32 v221, v94
	v_fmac_f32_e32 v222, v91, v91
	v_fma_mixlo_f16 v85, v208, v85, 0
	v_fma_f32 v223, -v94, v221, 1.0
	v_fmac_f32_e32 v221, v223, v221
	v_div_scale_f32 v223, vcc, 1.0, v81, 1.0
	v_mul_f32_e32 v224, v223, v221
	v_fma_f32 v225, -v94, v224, v223
	v_fmac_f32_e32 v224, v225, v221
	v_fma_f32 v94, -v94, v224, v223
	v_div_fmas_f32 v94, v94, v221, v224
	v_div_fixup_f32 v81, v94, v81, 1.0
	v_add_f32_e32 v94, -1.0, v81
	v_fma_f32 v86, v86, v94, 1.0
	v_mul_f32_e32 v94, v201, v86
	v_mul_f32_e32 v94, v220, v94
	v_fmac_f32_e32 v80, v82, v94
	v_cndmask_b32_e64 v82, v47, v46, s[6:7]
	v_cndmask_b32_e64 v82, v82, v44, s[8:9]
	v_add_f32_e32 v82, v95, v82
	v_mul_f32_e32 v82, 0xbfb8aa3b, v82
	v_exp_f32_e32 v82, v82
	s_nop 0
	v_add_f32_e32 v82, 1.0, v82
	v_div_scale_f32 v94, s[0:1], v82, v82, 1.0
	v_rcp_f32_e32 v95, v94
	s_nop 0
	v_fma_f32 v220, -v94, v95, 1.0
	v_fmac_f32_e32 v95, v220, v95
	v_div_scale_f32 v220, vcc, 1.0, v82, 1.0
	v_mul_f32_e32 v221, v220, v95
	v_fma_f32 v223, -v94, v221, v220
	v_fmac_f32_e32 v221, v223, v95
	v_fma_f32 v94, -v94, v221, v220
	v_div_fmas_f32 v94, v94, v95, v221
	v_div_fixup_f32 v82, v94, v82, 1.0
	v_add_f32_e32 v94, -1.0, v82
	v_fma_f32 v87, v87, v94, 1.0
	v_mul_f32_e32 v94, v196, v87
	v_mul_f32_e32 v94, v219, v94
	v_fmac_f32_e32 v80, v83, v94
	v_add_f32_dpp v83, v222, v222 quad_perm:[1,0,3,2] row_mask:0xf bank_mask:0xf bound_ctrl:1
	s_nop 0
	v_add_f32_dpp v80, v80, v80 quad_perm:[1,0,3,2] row_mask:0xf bank_mask:0xf bound_ctrl:1
	v_add_f32_dpp v83, v83, v83 quad_perm:[2,3,0,1] row_mask:0xf bank_mask:0xf bound_ctrl:1
	s_nop 0
	v_add_f32_dpp v80, v80, v80 quad_perm:[2,3,0,1] row_mask:0xf bank_mask:0xf bound_ctrl:1
	v_add_f32_dpp v83, v83, v83 row_half_mirror row_mask:0xf bank_mask:0xf bound_ctrl:1
	s_nop 0
	v_add_f32_dpp v80, v80, v80 row_half_mirror row_mask:0xf bank_mask:0xf bound_ctrl:1
	v_add_f32_dpp v83, v83, v83 row_mirror row_mask:0xf bank_mask:0xf bound_ctrl:1
	v_cmp_gt_f32_e32 vcc, s50, v83
	v_mul_f32_e32 v94, 0x4f800000, v83
	v_add_f32_dpp v80, v80, v80 row_mirror row_mask:0xf bank_mask:0xf bound_ctrl:1
	v_cndmask_b32_e32 v83, v83, v94, vcc
	v_sqrt_f32_e32 v94, v83
	s_nop 0
	v_add_u32_e32 v95, -1, v94
	v_fma_f32 v219, -v95, v94, v83
	v_cmp_ge_f32_e64 s[0:1], 0, v219
	v_add_u32_e32 v219, 1, v94
	s_nop 0
	v_cndmask_b32_e64 v95, v94, v95, s[0:1]
	v_fma_f32 v94, -v219, v94, v83
	v_cmp_lt_f32_e64 s[0:1], 0, v94
	s_nop 1
	v_cndmask_b32_e64 v94, v95, v219, s[0:1]
	v_mul_f32_e32 v95, 0x37800000, v94
	v_cndmask_b32_e32 v94, v94, v95, vcc
	v_cmp_class_f32_e32 vcc, v83, v179
	s_nop 1
	v_cndmask_b32_e32 v83, v94, v83, vcc
	v_max_f32_e32 v83, 0x2b8cbccc, v83
	v_div_scale_f32 v94, s[0:1], v83, v83, 1.0
	v_rcp_f32_e32 v95, v94
	s_nop 0
	v_fma_f32 v219, -v94, v95, 1.0
	v_fmac_f32_e32 v95, v219, v95
	v_div_scale_f32 v219, vcc, 1.0, v83, 1.0
	v_mul_f32_e32 v220, v219, v95
	v_fma_f32 v221, -v94, v220, v219
	v_fmac_f32_e32 v220, v221, v95
	v_fma_f32 v94, -v94, v220, v219
	v_div_fmas_f32 v94, v94, v95, v220
	v_lshlrev_b32_e32 v95, 10, v212
	v_cndmask_b32_e64 v212, v3, v2, s[6:7]
	v_cndmask_b32_e64 v212, v212, v0, s[8:9]
	s_waitcnt vmcnt(1)
	v_add_f32_e32 v76, v76, v212
	v_mul_f32_e32 v76, 0xbfb8aa3b, v76
	v_exp_f32_e32 v76, v76
	v_div_fixup_f32 v83, v94, v83, 1.0
	v_mul_f32_e32 v88, v88, v83
	v_lshrrev_b32_e32 v94, 8, v194
	v_add_f32_e32 v76, 1.0, v76
	v_div_scale_f32 v212, s[0:1], v76, v76, 1.0
	v_rcp_f32_e32 v219, v212
	v_and_b32_e32 v94, 0x3f0, v94
	v_fma_f32 v220, -v212, v219, 1.0
	v_fmac_f32_e32 v219, v220, v219
	v_div_scale_f32 v220, vcc, 1.0, v76, 1.0
	v_mul_f32_e32 v221, v220, v219
	v_fma_f32 v222, -v212, v221, v220
	v_fmac_f32_e32 v221, v222, v219
	v_fma_f32 v212, -v212, v221, v220
	v_div_fmas_f32 v212, v212, v219, v221
	v_div_fixup_f32 v76, v212, v76, 1.0
	v_cndmask_b32_e64 v212, v7, v6, s[6:7]
	v_cndmask_b32_e64 v212, v212, v4, s[8:9]
	s_waitcnt vmcnt(0)
; DEVINL u16 f2bf(float a) { return (u16)(pk2(a, 0.f) & 0xffffu); }
; DEVINL float sigm(float x) { return 1.f / (1.f + __expf(-x)); }
; DEVINL void rw_prep_unit(const Params& p, int unit) {
;     ...
; #pragma unroll
;         for (int n = 0; n < 4; ++n) {
;           float wf = __expf(-0.606531f * sigm(w0f[n] + sel4(awf[n], j)));
;           float wb = __expf(-0.606531f * sigm(w0b[n] + sel4(awb[n], j)));
;           float kkn = kkv[n] * inv;
;           hwf[n] = f2h(wf); hwb[n] = f2h(wb); ha[n] = f2h(-kkn); hb[n] = f2h(kkn * av[n]);
;           hk[n] = f2h(pk[n]); hr[n] = f2h(pr[n]); hv[n] = f2h(pv[n]);
;           bg[n] = f2bf(sel4(ag[n], j)); bbn[n] = f2bf(dot * pv[n]);
;         }
	v_add_f32_e32 v72, v72, v212
	v_mul_f32_e32 v72, 0xbfb8aa3b, v72
	v_exp_f32_e32 v72, v72
	v_mul_f32_e32 v76, 0xbf1b459e, v76
	v_mul_f32_e32 v76, 0x3fb8aa3b, v76
	v_exp_f32_e32 v76, v76
	v_add_f32_e32 v72, 1.0, v72
	v_div_scale_f32 v212, s[0:1], v72, v72, 1.0
	v_rcp_f32_e32 v219, v212
	v_cvt_f16_f32_e32 v76, v76
	v_fma_f32 v220, -v212, v219, 1.0
	v_fmac_f32_e32 v219, v220, v219
	v_div_scale_f32 v220, vcc, 1.0, v72, 1.0
	v_mul_f32_e32 v221, v220, v219
	v_fma_f32 v222, -v212, v221, v220
	v_fmac_f32_e32 v221, v222, v219
	v_fma_f32 v212, -v212, v221, v220
	v_div_fmas_f32 v212, v212, v219, v221
	v_div_fixup_f32 v72, v212, v72, 1.0
	v_cvt_f16_f32_e64 v212, -v88
	v_fma_mixlo_f16 v88, v92, v88, 0
	v_fma_mixlo_f16 v92, v64, v210, v209
	v_cndmask_b32_e64 v64, v51, v50, s[6:7]
	v_cndmask_b32_e64 v64, v64, v48, s[8:9]
	v_cvt_pk_bf16_f32 v209, v64, s0
	v_mul_f32_e32 v64, v217, v80
	v_cvt_pk_bf16_f32 v210, v64, s0
	v_cndmask_b32_e64 v64, v15, v14, s[6:7]
	v_cndmask_b32_e64 v64, v64, v12, s[8:9]
	v_add_f32_e32 v64, v77, v64
	v_mul_f32_e32 v64, 0xbfb8aa3b, v64
	v_exp_f32_e32 v64, v64
	v_mul_f32_e32 v72, 0xbf1b459e, v72
	v_mul_f32_e32 v72, 0x3fb8aa3b, v72
	v_exp_f32_e32 v72, v72
	v_add_f32_e32 v64, 1.0, v64
	v_div_scale_f32 v77, s[0:1], v64, v64, 1.0
	v_rcp_f32_e32 v215, v77
	v_cvt_f16_f32_e32 v72, v72
	v_fma_f32 v216, -v77, v215, 1.0
	v_fmac_f32_e32 v215, v216, v215
	v_div_scale_f32 v216, vcc, 1.0, v64, 1.0
	v_mul_f32_e32 v217, v216, v215
	v_fma_f32 v218, -v77, v217, v216
	v_fmac_f32_e32 v217, v218, v215
	v_fma_f32 v77, -v77, v217, v216
	v_div_fmas_f32 v77, v77, v215, v217
	v_div_fixup_f32 v64, v77, v64, 1.0
	v_cndmask_b32_e64 v77, v19, v18, s[6:7]
	v_cndmask_b32_e64 v77, v77, v16, s[8:9]
	v_add_f32_e32 v73, v73, v77
	v_mul_f32_e32 v73, 0xbfb8aa3b, v73
	v_exp_f32_e32 v73, v73
	v_mul_f32_e32 v64, 0xbf1b459e, v64
	v_mul_f32_e32 v64, 0x3fb8aa3b, v64
	v_exp_f32_e32 v64, v64
	v_add_f32_e32 v73, 1.0, v73
	v_div_scale_f32 v77, s[0:1], v73, v73, 1.0
	v_rcp_f32_e32 v215, v77
	v_cvt_f16_f32_sdwa v64, v64 dst_sel:WORD_1 dst_unused:UNUSED_PAD src0_sel:DWORD
	v_fma_f32 v216, -v77, v215, 1.0
	v_fmac_f32_e32 v215, v216, v215
	v_div_scale_f32 v216, vcc, 1.0, v73, 1.0
	v_mul_f32_e32 v217, v216, v215
	v_fma_f32 v218, -v77, v217, v216
	v_fmac_f32_e32 v217, v218, v215
	v_fma_f32 v77, -v77, v217, v216
	v_div_fmas_f32 v77, v77, v215, v217
	v_div_fixup_f32 v73, v77, v73, 1.0
	v_mul_f32_e32 v77, v89, v83
	v_cvt_f16_f32_sdwa v89, -v77 dst_sel:WORD_1 dst_unused:UNUSED_PAD src0_sel:DWORD
	v_fma_mixlo_f16 v77, v93, v77, 0
	v_fma_mixlo_f16 v93, v65, v204, v203
	v_cndmask_b32_e64 v65, v55, v54, s[6:7]
	v_cndmask_b32_e64 v65, v65, v52, s[8:9]
	v_cvt_pk_bf16_f32 v203, v65, s0
	v_mul_f32_e32 v65, v213, v80
	v_cvt_pk_bf16_f32 v204, v65, s0
	v_cndmask_b32_e64 v65, v27, v26, s[6:7]
	v_cndmask_b32_e64 v65, v65, v24, s[8:9]
	v_add_f32_e32 v65, v78, v65
	v_mul_f32_e32 v65, 0xbfb8aa3b, v65
	v_exp_f32_e32 v65, v65
	v_mul_f32_e32 v73, 0xbf1b459e, v73
	v_mul_f32_e32 v73, 0x3fb8aa3b, v73
	v_exp_f32_e32 v73, v73
	v_add_f32_e32 v65, 1.0, v65
	v_div_scale_f32 v78, s[0:1], v65, v65, 1.0
	v_rcp_f32_e32 v208, v78
	v_cvt_f16_f32_sdwa v73, v73 dst_sel:WORD_1 dst_unused:UNUSED_PAD src0_sel:DWORD
	v_or_b32_e32 v64, v64, v76
	v_fma_f32 v211, -v78, v208, 1.0
	v_fmac_f32_e32 v208, v211, v208
	v_div_scale_f32 v211, vcc, 1.0, v65, 1.0
	v_mul_f32_e32 v213, v211, v208
	v_fma_f32 v214, -v78, v213, v211
	v_fmac_f32_e32 v213, v214, v208
	v_fma_f32 v78, -v78, v213, v211
	v_div_fmas_f32 v78, v78, v208, v213
	v_div_fixup_f32 v65, v78, v65, 1.0
	v_cndmask_b32_e64 v78, v31, v30, s[6:7]
	v_cndmask_b32_e64 v78, v78, v28, s[8:9]
	v_add_f32_e32 v74, v74, v78
	v_mul_f32_e32 v74, 0xbfb8aa3b, v74
	v_exp_f32_e32 v74, v74
	v_mul_f32_e32 v65, 0xbf1b459e, v65
	v_mul_f32_e32 v65, 0x3fb8aa3b, v65
	v_exp_f32_e32 v65, v65
	v_add_f32_e32 v74, 1.0, v74
	v_div_scale_f32 v78, s[0:1], v74, v74, 1.0
	v_rcp_f32_e32 v208, v78
	v_cvt_f16_f32_e32 v65, v65
	v_fma_f32 v211, -v78, v208, 1.0
	v_fmac_f32_e32 v208, v211, v208
	v_div_scale_f32 v211, vcc, 1.0, v74, 1.0
	v_mul_f32_e32 v213, v211, v208
	v_fma_f32 v214, -v78, v213, v211
	v_fmac_f32_e32 v213, v214, v208
	v_fma_f32 v78, -v78, v213, v211
	v_div_fmas_f32 v78, v78, v208, v213
	v_div_fixup_f32 v74, v78, v74, 1.0
	v_mul_f32_e32 v78, v90, v83
	v_cvt_f16_f32_e64 v90, -v78
	v_fma_mixlo_f16 v78, v81, v78, 0
	v_fma_mixlo_f16 v81, v201, v86, 0
	v_fma_mixlo_f16 v86, v66, v198, v197
	v_cndmask_b32_e64 v66, v59, v58, s[6:7]
	v_cndmask_b32_e64 v66, v66, v56, s[8:9]
	v_cvt_pk_bf16_f32 v197, v66, s0
	v_mul_f32_e32 v66, v206, v80
	v_cvt_pk_bf16_f32 v198, v66, s0
	v_cndmask_b32_e64 v66, v39, v38, s[6:7]
	v_cndmask_b32_e64 v66, v66, v36, s[8:9]
	v_add_f32_e32 v66, v79, v66
	v_mul_f32_e32 v66, 0xbfb8aa3b, v66
	v_exp_f32_e32 v66, v66
	v_mul_f32_e32 v74, 0xbf1b459e, v74
	v_mul_f32_e32 v74, 0x3fb8aa3b, v74
	v_exp_f32_e32 v74, v74
	v_add_f32_e32 v66, 1.0, v66
	v_div_scale_f32 v79, s[0:1], v66, v66, 1.0
	v_rcp_f32_e32 v201, v79
	v_cvt_f16_f32_e32 v74, v74
	v_fma_f32 v205, -v79, v201, 1.0
	v_fmac_f32_e32 v201, v205, v201
	v_div_scale_f32 v205, vcc, 1.0, v66, 1.0
	v_mul_f32_e32 v206, v205, v201
	v_fma_f32 v207, -v79, v206, v205
	v_fmac_f32_e32 v206, v207, v201
	v_fma_f32 v79, -v79, v206, v205
	v_div_fmas_f32 v79, v79, v201, v206
	v_div_fixup_f32 v66, v79, v66, 1.0
	v_cndmask_b32_e64 v79, v43, v42, s[6:7]
	v_cndmask_b32_e64 v79, v79, v40, s[8:9]
	v_add_f32_e32 v75, v75, v79
	v_mul_f32_e32 v75, 0xbfb8aa3b, v75
	v_exp_f32_e32 v75, v75
	v_mul_f32_e32 v66, 0xbf1b459e, v66
	v_mul_f32_e32 v66, 0x3fb8aa3b, v66
	v_exp_f32_e32 v66, v66
	v_add_f32_e32 v75, 1.0, v75
	v_div_scale_f32 v79, s[0:1], v75, v75, 1.0
	v_rcp_f32_e32 v201, v79
; DEVINL void rw_prep_unit(const Params& p, int unit) {
;     ...
;         const int t = tok0 + mt * 16 + 4 * g + jo;
;         const int s = t & (S_ - 1), b = t >> 12;
;         const unsigned c0 = (unsigned)(head * 64 + l15 * 4 + zo);
;         const unsigned rowo = (unsigned)t * (unsigned)(NCP * 2) + (unsigned)(C_RW * 2) + c0 * 2u;
;         float pr[4], pkr[4], pv[4];
;         rw_shift4(colsb, *(const float4*)(p.rw_mu + c0), rowo, s, pr);
;         rw_shift4(colsb, *(const float4*)(p.rw_mu + 1024u + c0), rowo + 2048u, s, pkr);
;         rw_shift4(colsb, *(const float4*)(p.rw_mu + 2048u + c0), rowo + 4096u, s, pv);
;     ...
;         char* rb = ws + O_REC + (reco + (unsigned)l15 * 64u);
;         *(uint4*)(rb) = make_uint4(hwf[0] | (hwf[1] << 16), hwf[2] | (hwf[3] << 16), hwb[0] | (hwb[1] << 16), hwb[2] | (hwb[3] << 16));
;         *(uint4*)(rb + 16) = make_uint4(ha[0] | (ha[1] << 16), ha[2] | (ha[3] << 16), hb[0] | (hb[1] << 16), hb[2] | (hb[3] << 16));
;         *(uint4*)(rb + 32) = make_uint4(hk[0] | (hk[1] << 16), hk[2] | (hk[3] << 16), hr[0] | (hr[1] << 16), hr[2] | (hr[3] << 16));
;         *(uint2*)(rb + 48) = make_uint2(hv[0] | (hv[1] << 16), hv[2] | (hv[3] << 16));
;         *(uint2*)(ws + O_GRW + tco) = make_uint2(bg[0] | (bg[1] << 16), bg[2] | (bg[3] << 16));
;         *(uint2*)(ws + O_BONUS + tco) = make_uint2(bbn[0] | (bbn[1] << 16), bbn[2] | (bbn[3] << 16));
	v_cvt_f16_f32_sdwa v66, v66 dst_sel:WORD_1 dst_unused:UNUSED_PAD src0_sel:DWORD
	v_fma_f32 v205, -v79, v201, 1.0
	v_fmac_f32_e32 v201, v205, v201
	v_div_scale_f32 v205, vcc, 1.0, v75, 1.0
	v_mul_f32_e32 v206, v205, v201
	v_fma_f32 v207, -v79, v206, v205
	v_fmac_f32_e32 v206, v207, v201
	v_fma_f32 v79, -v79, v206, v205
	v_div_fmas_f32 v79, v79, v201, v206
	v_div_fixup_f32 v75, v79, v75, 1.0
	v_mul_f32_e32 v75, 0xbf1b459e, v75
	v_mul_f32_e32 v75, 0x3fb8aa3b, v75
	v_exp_f32_e32 v75, v75
	v_mul_f32_e32 v79, v91, v83
	v_cvt_f16_f32_sdwa v83, -v79 dst_sel:WORD_1 dst_unused:UNUSED_PAD src0_sel:DWORD
	v_fma_mixlo_f16 v79, v82, v79, 0
	v_cvt_f16_f32_sdwa v75, v75 dst_sel:WORD_1 dst_unused:UNUSED_PAD src0_sel:DWORD
	v_fma_mixlo_f16 v82, v196, v87, 0
	v_fma_mixlo_f16 v87, v67, v195, v96
	v_cndmask_b32_e64 v67, v63, v62, s[6:7]
	v_cndmask_b32_e64 v67, v67, v60, s[8:9]
	v_cvt_pk_bf16_f32 v91, v67, s0
	v_mul_f32_e32 v67, v200, v80
	v_cvt_pk_bf16_f32 v80, v67, s0
	v_add_lshl_u32 v67, v94, v191, 22
	v_or3_b32 v95, v67, v95, v186
	v_or_b32_e32 v65, v66, v65
	v_or_b32_e32 v67, v75, v74
	v_or_b32_e32 v66, v73, v72
	global_store_dwordx4 v95, v[64:67], s[36:37]
	v_lshlrev_b32_e32 v72, 16, v77
	v_lshl_add_u32 v94, v194, 11, v178
	v_lshlrev_b32_e32 v66, 16, v79
	v_or_b32_e32 v65, v83, v90
	v_or_b32_e32 v64, v89, v212
	v_or_b32_sdwa v67, v66, v78 dst_sel:DWORD dst_unused:UNUSED_PAD src0_sel:DWORD src1_sel:WORD_0
	v_or_b32_sdwa v66, v72, v88 dst_sel:DWORD dst_unused:UNUSED_PAD src0_sel:DWORD src1_sel:WORD_0
	global_store_dwordx4 v95, v[64:67], s[36:37] offset:256
	v_lshlrev_b32_e32 v72, 16, v93
	s_add_i32 s6, s40, 1
	v_lshlrev_b32_e32 v64, 16, v82
	v_lshlrev_b32_e32 v66, 16, v85
	v_lshlrev_b32_e32 v67, 16, v87
	v_or_b32_sdwa v65, v64, v81 dst_sel:DWORD dst_unused:UNUSED_PAD src0_sel:DWORD src1_sel:WORD_0
	v_or_b32_sdwa v64, v66, v84 dst_sel:DWORD dst_unused:UNUSED_PAD src0_sel:DWORD src1_sel:WORD_0
	v_or_b32_sdwa v67, v67, v86 dst_sel:DWORD dst_unused:UNUSED_PAD src0_sel:DWORD src1_sel:WORD_0
	v_or_b32_sdwa v66, v72, v92 dst_sel:DWORD dst_unused:UNUSED_PAD src0_sel:DWORD src1_sel:WORD_0
	global_store_dwordx4 v95, v[64:67], s[36:37] offset:512
	s_cmp_eq_u32 s6, 1
	s_nop 0
	v_lshlrev_b32_e32 v64, 16, v71
	v_lshlrev_b32_e32 v66, 16, v69
	v_or_b32_sdwa v65, v64, v70 dst_sel:DWORD dst_unused:UNUSED_PAD src0_sel:DWORD src1_sel:WORD_0
	v_or_b32_sdwa v64, v66, v68 dst_sel:DWORD dst_unused:UNUSED_PAD src0_sel:DWORD src1_sel:WORD_0
	global_store_dwordx2 v95, v[64:65], s[36:37] offset:768
	v_lshlrev_b32_e32 v64, 16, v91
	v_lshlrev_b32_e32 v66, 16, v203
	v_or_b32_sdwa v65, v64, v197 dst_sel:DWORD dst_unused:UNUSED_PAD src0_sel:DWORD src1_sel:WORD_0
	v_or_b32_sdwa v64, v66, v209 dst_sel:DWORD dst_unused:UNUSED_PAD src0_sel:DWORD src1_sel:WORD_0
	global_store_dwordx2 v94, v[64:65], s[38:39]
	v_lshlrev_b32_e32 v64, 16, v80
	v_lshlrev_b32_e32 v66, 16, v204
	v_or_b32_sdwa v65, v64, v198 dst_sel:DWORD dst_unused:UNUSED_PAD src0_sel:DWORD src1_sel:WORD_0
	v_or_b32_sdwa v64, v66, v210 dst_sel:DWORD dst_unused:UNUSED_PAD src0_sel:DWORD src1_sel:WORD_0
	global_store_dwordx2 v94, v[64:65], s[70:71]
	v_mov_b32_e32 v64, s6
	v_mov_b32_e32 v65, v97
	s_cselect_b64 s[6:7], -1, 0
	v_add_u32_e32 v96, v65, v192
	v_add_u32_e32 v194, v193, v64
	v_lshlrev_b32_e32 v178, 1, v96
	v_and_b32_e32 v212, 0xfff, v194
	v_mad_u64_u32 v[72:73], s[0:1], v194, s49, v[178:179]
	v_add_u32_e32 v68, 0x1840, v72
	v_lshlrev_b64 v[74:75], 2, v[96:97]
	v_cmp_eq_u32_e32 vcc, 0, v212
	v_add_u32_e32 v69, 0xffffc440, v72
	v_lshl_add_u64 v[64:65], s[90:91], 0, v[74:75]
	v_cndmask_b32_e32 v70, v69, v68, vcc
	v_cmp_eq_u32_e64 s[0:1], s44, v212
	v_add_u32_e32 v69, 0x6c40, v72
	global_load_dwordx4 v[64:67], v[64:65], off
	v_cndmask_b32_e64 v73, v69, v68, s[0:1]
	global_load_dwordx2 v[68:69], v68, s[18:19]
	s_nop 0
	global_load_dwordx2 v[70:71], v70, s[18:19]
	s_nop 0
	global_load_dwordx2 v[76:77], v73, s[18:19]
	v_cndmask_b32_e64 v223, v11, v9, s[6:7]
	s_add_i32 s40, s40, 2
	s_cmp_eq_u32 s40, 4
	s_waitcnt vmcnt(2)
	v_lshlrev_b32_e32 v209, 16, v68
	s_waitcnt vmcnt(1)
	v_cndmask_b32_e64 v70, v70, 0, vcc
	s_waitcnt vmcnt(0)
	v_cndmask_b32_e64 v73, v76, 0, s[0:1]
	v_cndmask_b32_e64 v76, v77, 0, s[0:1]
	v_and_b32_e32 v203, 0xffff0000, v68
	v_lshlrev_b32_e32 v68, 16, v70
	v_lshlrev_b32_e32 v77, 16, v73
	v_cndmask_b32_e64 v71, v71, 0, vcc
	v_lshlrev_b32_e32 v197, 16, v69
	v_and_b32_e32 v96, 0xffff0000, v69
	v_and_b32_e32 v69, 0xffff0000, v70
	v_and_b32_e32 v73, 0xffff0000, v73
	v_add_f32_e32 v68, v68, v77
	v_lshlrev_b32_e32 v70, 16, v71
	v_lshlrev_b32_e32 v78, 16, v76
	v_fma_f32 v210, v68, 0.5, -v209
	v_add_f32_e32 v68, v69, v73
	v_and_b32_e32 v71, 0xffff0000, v71
	v_and_b32_e32 v76, 0xffff0000, v76
	v_fma_f32 v204, v68, 0.5, -v203
	v_add_f32_e32 v68, v70, v78
	v_fma_f32 v198, v68, 0.5, -v197
	v_add_f32_e32 v68, v71, v76
	v_add_u32_e32 v73, 0x2040, v72
	v_add_u32_e32 v76, 0xffffcc40, v72
	v_cndmask_b32_e32 v78, v76, v73, vcc
	v_add_u32_e32 v76, 0x7440, v72
	v_fma_f32 v195, v68, 0.5, -v96
	v_lshl_add_u64 v[68:69], s[72:73], 0, v[74:75]
	v_cndmask_b32_e64 v80, v76, v73, s[0:1]
	global_load_dwordx4 v[68:71], v[68:69], off
	s_nop 0
	global_load_dwordx2 v[76:77], v73, s[18:19]
	s_nop 0
	global_load_dwordx2 v[78:79], v78, s[18:19]
	s_nop 0
	global_load_dwordx2 v[80:81], v80, s[18:19]
	v_fma_f32 v222, v64, v210, v209
	v_fma_f32 v221, v65, v204, v203
	v_fma_f32 v220, v66, v198, v197
	v_fma_f32 v219, v67, v195, v96
	s_waitcnt vmcnt(2)
	v_lshlrev_b32_e32 v214, 16, v76
	s_waitcnt vmcnt(1)
	v_cndmask_b32_e64 v73, v78, 0, vcc
	v_cndmask_b32_e64 v78, v79, 0, vcc
	s_waitcnt vmcnt(0)
; DEVINL float bflo(unsigned u) { return __uint_as_float(u << 16); }
; DEVINL float bfhi(unsigned u) { return __uint_as_float(u & 0xffff0000u); }
; DEVINL void rw_shift4(const char* colsb, float4 mu, unsigned o, int s, float (&out)[4]) {
;   const unsigned op = (s > 0) ? o - (unsigned)(NCP * 2) : o;
;   const unsigned on = (s < S_ - 1) ? o + (unsigned)(NCP * 2) : o;
;   const uint2 c = *(const uint2*)(colsb + o);
;   uint2 pv = *(const uint2*)(colsb + op);
;   uint2 nx = *(const uint2*)(colsb + on);
;   if (s == 0) pv = make_uint2(0u, 0u);
;   if (s == S_ - 1) nx = make_uint2(0u, 0u);
;   const float cu[4] = {bflo(c.x), bfhi(c.x), bflo(c.y), bfhi(c.y)};
;   const float pr[4] = {bflo(pv.x), bfhi(pv.x), bflo(pv.y), bfhi(pv.y)};
;   const float nn[4] = {bflo(nx.x), bfhi(nx.x), bflo(nx.y), bfhi(nx.y)};
;   const float m[4] = {mu.x, mu.y, mu.z, mu.w};
; #pragma unroll
;   for (int e = 0; e < 4; ++e) out[e] = cu[e] + m[e] * (0.5f * (pr[e] + nn[e]) - cu[e]);
; DEVINL void rw_prep_unit(const Params& p, int unit) {
;     ...
;         rw_shift4(colsb, *(const float4*)(p.rw_mu + c0), rowo, s, pr);
;         rw_shift4(colsb, *(const float4*)(p.rw_mu + 1024u + c0), rowo + 2048u, s, pkr);
;         rw_shift4(colsb, *(const float4*)(p.rw_mu + 2048u + c0), rowo + 4096u, s, pv);
;         const float4 a0q = *(const float4*)(p.rw_a0 + c0), kkq = *(const float4*)(p.rw_k_k + c0);
;         const float4 kaq = *(const float4*)(p.rw_k_a + c0), rkq = *(const float4*)(p.rw_r_k + c0);
;         const float4 w0fq = *(const float4*)(p.rw_w0_f + c0), w0bq = *(const float4*)(p.rw_w0_b + c0);
;         const float a0v[4] = {a0q.x, a0q.y, a0q.z, a0q.w}, kkp[4] = {kkq.x, kkq.y, kkq.z, kkq.w};
;         const float kap[4] = {kaq.x, kaq.y, kaq.z, kaq.w}, rkp[4] = {rkq.x, rkq.y, rkq.z, rkq.w};
;         const float w0f[4] = {w0fq.x, w0fq.y, w0fq.z, w0fq.w}, w0b[4] = {w0bq.x, w0bq.y, w0bq.z, w0bq.w};
;         float pk[4], av[4], kkv[4];
;         float n2 = 0.f, dot = 0.f;
; #pragma unroll
;         for (int n = 0; n < 4; ++n) {
;           const float kraw = pkr[n];
;           float a = sigm(a0v[n] + sel4(aa[n], j));
;           av[n] = a;
;           float kk = kraw * kkp[n];
;           kkv[n] = kk;
;           n2 += kk * kk;
;           float k2 = kraw * (1.f + (a - 1.f) * kap[n]);
;           pk[n] = k2;
;           dot += pr[n] * k2 * rkp[n];
;         }
	v_cndmask_b32_e64 v79, v80, 0, s[0:1]
	v_cndmask_b32_e64 v80, v81, 0, s[0:1]
	v_and_b32_e32 v206, 0xffff0000, v76
	v_lshlrev_b32_e32 v76, 16, v73
	v_lshlrev_b32_e32 v81, 16, v79
	v_add_f32_e32 v76, v76, v81
	v_and_b32_e32 v73, 0xffff0000, v73
	v_and_b32_e32 v79, 0xffff0000, v79
	v_fma_f32 v76, v76, 0.5, -v214
	v_fmac_f32_e32 v214, v68, v76
	v_add_f32_e32 v68, v73, v79
	v_lshlrev_b32_e32 v200, 16, v77
	v_and_b32_e32 v196, 0xffff0000, v77
	v_lshlrev_b32_e32 v77, 16, v78
	v_lshlrev_b32_e32 v82, 16, v80
	v_fma_f32 v68, v68, 0.5, -v206
	v_fmac_f32_e32 v206, v69, v68
	v_add_f32_e32 v68, v77, v82
	v_and_b32_e32 v78, 0xffff0000, v78
	v_and_b32_e32 v80, 0xffff0000, v80
	v_fma_f32 v68, v68, 0.5, -v200
	v_fmac_f32_e32 v200, v70, v68
	v_add_f32_e32 v68, v78, v80
	v_fma_f32 v68, v68, 0.5, -v196
	v_add_u32_e32 v73, 0x2840, v72
	v_add_u32_e32 v76, 0xffffd440, v72
	v_add_u32_e32 v72, 0x7c40, v72
	v_fmac_f32_e32 v196, v71, v68
	v_lshl_add_u64 v[68:69], s[78:79], 0, v[74:75]
	v_cndmask_b32_e32 v76, v76, v73, vcc
	v_cndmask_b32_e64 v78, v72, v73, s[0:1]
	global_load_dwordx4 v[68:71], v[68:69], off
	s_nop 0
	global_load_dwordx2 v[72:73], v73, s[18:19]
	s_nop 0
	global_load_dwordx2 v[76:77], v76, s[18:19]
	s_nop 0
	global_load_dwordx2 v[78:79], v78, s[18:19]
	s_waitcnt vmcnt(2)
	v_lshlrev_b32_e32 v216, 16, v72
	s_waitcnt vmcnt(1)
	v_cndmask_b32_e64 v76, v76, 0, vcc
	s_waitcnt vmcnt(0)
	v_cndmask_b32_e64 v78, v78, 0, s[0:1]
	v_and_b32_e32 v211, 0xffff0000, v72
	v_lshlrev_b32_e32 v72, 16, v76
	v_lshlrev_b32_e32 v80, 16, v78
	v_cndmask_b32_e64 v77, v77, 0, vcc
	v_cndmask_b32_e64 v79, v79, 0, s[0:1]
	v_lshlrev_b32_e32 v205, 16, v73
	v_and_b32_e32 v199, 0xffff0000, v73
	v_and_b32_e32 v73, 0xffff0000, v76
	v_and_b32_e32 v78, 0xffff0000, v78
	v_add_f32_e32 v72, v72, v80
	v_lshlrev_b32_e32 v76, 16, v77
	v_lshlrev_b32_e32 v81, 16, v79
	v_fma_f32 v218, v72, 0.5, -v216
	v_add_f32_e32 v72, v73, v78
	v_and_b32_e32 v77, 0xffff0000, v77
	v_and_b32_e32 v79, 0xffff0000, v79
	v_fma_f32 v215, v72, 0.5, -v211
	v_add_f32_e32 v72, v76, v81
	v_fma_f32 v208, v72, 0.5, -v205
	v_add_f32_e32 v72, v77, v79
	v_fma_f32 v202, v72, 0.5, -v199
	v_lshl_add_u64 v[72:73], s[20:21], 0, v[74:75]
	global_load_dwordx4 v[92:95], v[72:73], off
	v_lshl_add_u64 v[72:73], s[26:27], 0, v[74:75]
	global_load_dwordx4 v[88:91], v[72:73], off
	v_lshl_add_u64 v[72:73], s[60:61], 0, v[74:75]
	global_load_dwordx4 v[84:87], v[72:73], off
	v_lshl_add_u64 v[72:73], s[62:63], 0, v[74:75]
	global_load_dwordx4 v[80:83], v[72:73], off
	v_lshl_add_u64 v[72:73], s[12:13], 0, v[74:75]
	global_load_dwordx4 v[76:79], v[72:73], off
	v_lshl_add_u64 v[72:73], s[16:17], 0, v[74:75]
	global_load_dwordx4 v[72:75], v[72:73], off
	v_fma_f32 v217, v68, v218, v216
	v_fma_mixlo_f16 v68, v68, v218, v216
	v_fma_f32 v213, v69, v215, v211
	v_fma_mixlo_f16 v69, v69, v215, v211
	v_fma_f32 v207, v70, v208, v205
	v_fma_mixlo_f16 v70, v70, v208, v205
	v_fma_f32 v201, v71, v202, v199
	v_fma_mixlo_f16 v71, v71, v202, v199
	s_waitcnt vmcnt(5)
	v_add_f32_e32 v92, v92, v223
	v_mul_f32_e32 v92, 0xbfb8aa3b, v92
	v_exp_f32_e32 v92, v92
	s_waitcnt vmcnt(4)
	v_mul_f32_e32 v89, v206, v89
	v_mul_f32_e32 v88, v214, v88
	v_mul_f32_e32 v90, v200, v90
	v_add_f32_e32 v92, 1.0, v92
	v_div_scale_f32 v223, s[0:1], v92, v92, 1.0
	v_rcp_f32_e32 v224, v223
	v_mul_f32_e32 v91, v196, v91
	v_fma_f32 v225, -v223, v224, 1.0
	v_fmac_f32_e32 v224, v225, v224
	v_div_scale_f32 v225, vcc, 1.0, v92, 1.0
	v_mul_f32_e32 v226, v225, v224
	v_fma_f32 v227, -v223, v226, v225
	v_fmac_f32_e32 v226, v227, v224
	v_fma_f32 v223, -v223, v226, v225
	v_div_fmas_f32 v223, v223, v224, v226
	v_div_fixup_f32 v92, v223, v92, 1.0
	v_add_f32_e32 v223, -1.0, v92
	s_waitcnt vmcnt(3)
	v_fma_f32 v84, v84, v223, 1.0
	v_mul_f32_e32 v223, v214, v84
	v_mul_f32_e32 v222, v222, v223
	s_waitcnt vmcnt(2)
	v_fma_f32 v80, v80, v222, 0
	v_cndmask_b32_e64 v222, v23, v21, s[6:7]
	v_add_f32_e32 v93, v93, v222
	v_mul_f32_e32 v93, 0xbfb8aa3b, v93
	v_exp_f32_e32 v93, v93
	v_fma_mixlo_f16 v84, v214, v84, 0
	v_add_f32_e32 v93, 1.0, v93
	v_div_scale_f32 v222, s[0:1], v93, v93, 1.0
	v_rcp_f32_e32 v223, v222
	s_nop 0
	v_fma_f32 v224, -v222, v223, 1.0
	v_fmac_f32_e32 v223, v224, v223
	v_div_scale_f32 v224, vcc, 1.0, v93, 1.0
	v_mul_f32_e32 v225, v224, v223
	v_fma_f32 v226, -v222, v225, v224
	v_fmac_f32_e32 v225, v226, v223
	v_fma_f32 v222, -v222, v225, v224
	v_div_fmas_f32 v222, v222, v223, v225
	v_div_fixup_f32 v93, v222, v93, 1.0
	v_add_f32_e32 v223, -1.0, v93
	v_fma_f32 v85, v85, v223, 1.0
	v_mul_f32_e32 v223, v206, v85
	v_mul_f32_e32 v221, v221, v223
	v_fmac_f32_e32 v80, v81, v221
	v_cndmask_b32_e64 v81, v35, v33, s[6:7]
	v_add_f32_e32 v81, v94, v81
	v_mul_f32_e32 v81, 0xbfb8aa3b, v81
	v_exp_f32_e32 v81, v81
	v_mul_f32_e32 v222, v89, v89
	v_fmac_f32_e32 v222, v88, v88
	v_fmac_f32_e32 v222, v90, v90
	v_add_f32_e32 v81, 1.0, v81
	v_div_scale_f32 v94, s[0:1], v81, v81, 1.0
	v_rcp_f32_e32 v221, v94
	v_fmac_f32_e32 v222, v91, v91
	v_fma_mixlo_f16 v85, v206, v85, 0
	v_fma_f32 v223, -v94, v221, 1.0
	v_fmac_f32_e32 v221, v223, v221
	v_div_scale_f32 v223, vcc, 1.0, v81, 1.0
	v_mul_f32_e32 v224, v223, v221
	v_fma_f32 v225, -v94, v224, v223
	v_fmac_f32_e32 v224, v225, v221
	v_fma_f32 v94, -v94, v224, v223
	v_div_fmas_f32 v94, v94, v221, v224
	v_div_fixup_f32 v81, v94, v81, 1.0
	v_add_f32_e32 v94, -1.0, v81
	v_fma_f32 v86, v86, v94, 1.0
	v_mul_f32_e32 v94, v200, v86
	v_mul_f32_e32 v94, v220, v94
	v_fmac_f32_e32 v80, v82, v94
	v_cndmask_b32_e64 v82, v47, v45, s[6:7]
	v_add_f32_e32 v82, v95, v82
	v_mul_f32_e32 v82, 0xbfb8aa3b, v82
	v_exp_f32_e32 v82, v82
	s_nop 0
	v_add_f32_e32 v82, 1.0, v82
	v_div_scale_f32 v94, s[0:1], v82, v82, 1.0
; DEVINL u16 f2bf(float a) { return (u16)(pk2(a, 0.f) & 0xffffu); }
; DEVINL float sigm(float x) { return 1.f / (1.f + __expf(-x)); }
; DEVINL void rw_prep_unit(const Params& p, int unit) {
;     ...
;         for (int n = 0; n < 4; ++n) {
;           const float kraw = pkr[n];
;           float a = sigm(a0v[n] + sel4(aa[n], j));
;           av[n] = a;
;           float kk = kraw * kkp[n];
;           kkv[n] = kk;
;           n2 += kk * kk;
;           float k2 = kraw * (1.f + (a - 1.f) * kap[n]);
;           pk[n] = k2;
;           dot += pr[n] * k2 * rkp[n];
;         }
;         n2 = allred16(n2);
;         dot = allred16(dot);
;         const float inv = 1.f / fmaxf(sqrtf(n2), 1e-12f);
;         const unsigned reco = ((unsigned)((b * 16 + head) * 4096 + s)) * 1024u;
;         const unsigned tco = (unsigned)t * 2048u + c0 * 2u;
;         unsigned hwf[4], hwb[4], ha[4], hb[4], hk[4], hr[4], hv[4], bg[4], bbn[4];
; #pragma unroll
;         for (int n = 0; n < 4; ++n) {
;           float wf = __expf(-0.606531f * sigm(w0f[n] + sel4(awf[n], j)));
;           float wb = __expf(-0.606531f * sigm(w0b[n] + sel4(awb[n], j)));
;           float kkn = kkv[n] * inv;
;           hwf[n] = f2h(wf); hwb[n] = f2h(wb); ha[n] = f2h(-kkn); hb[n] = f2h(kkn * av[n]);
;           hk[n] = f2h(pk[n]); hr[n] = f2h(pr[n]); hv[n] = f2h(pv[n]);
;           bg[n] = f2bf(sel4(ag[n], j)); bbn[n] = f2bf(dot * pv[n]);
	v_rcp_f32_e32 v95, v94
	s_nop 0
	v_fma_f32 v220, -v94, v95, 1.0
	v_fmac_f32_e32 v95, v220, v95
	v_div_scale_f32 v220, vcc, 1.0, v82, 1.0
	v_mul_f32_e32 v221, v220, v95
	v_fma_f32 v223, -v94, v221, v220
	v_fmac_f32_e32 v221, v223, v95
	v_fma_f32 v94, -v94, v221, v220
	v_div_fmas_f32 v94, v94, v95, v221
	v_div_fixup_f32 v82, v94, v82, 1.0
	v_add_f32_e32 v94, -1.0, v82
	v_fma_f32 v87, v87, v94, 1.0
	v_mul_f32_e32 v94, v196, v87
	v_mul_f32_e32 v94, v219, v94
	v_fmac_f32_e32 v80, v83, v94
	v_add_f32_dpp v83, v222, v222 quad_perm:[1,0,3,2] row_mask:0xf bank_mask:0xf bound_ctrl:1
	s_nop 0
	v_add_f32_dpp v80, v80, v80 quad_perm:[1,0,3,2] row_mask:0xf bank_mask:0xf bound_ctrl:1
	v_add_f32_dpp v83, v83, v83 quad_perm:[2,3,0,1] row_mask:0xf bank_mask:0xf bound_ctrl:1
	s_nop 0
	v_add_f32_dpp v80, v80, v80 quad_perm:[2,3,0,1] row_mask:0xf bank_mask:0xf bound_ctrl:1
	v_add_f32_dpp v83, v83, v83 row_half_mirror row_mask:0xf bank_mask:0xf bound_ctrl:1
	s_nop 0
	v_add_f32_dpp v80, v80, v80 row_half_mirror row_mask:0xf bank_mask:0xf bound_ctrl:1
	v_add_f32_dpp v83, v83, v83 row_mirror row_mask:0xf bank_mask:0xf bound_ctrl:1
	v_cmp_gt_f32_e32 vcc, s50, v83
	v_mul_f32_e32 v94, 0x4f800000, v83
	v_add_f32_dpp v80, v80, v80 row_mirror row_mask:0xf bank_mask:0xf bound_ctrl:1
	v_cndmask_b32_e32 v83, v83, v94, vcc
	v_sqrt_f32_e32 v94, v83
	s_nop 0
	v_add_u32_e32 v95, -1, v94
	v_fma_f32 v219, -v95, v94, v83
	v_cmp_ge_f32_e64 s[0:1], 0, v219
	v_add_u32_e32 v219, 1, v94
	s_nop 0
	v_cndmask_b32_e64 v95, v94, v95, s[0:1]
	v_fma_f32 v94, -v219, v94, v83
	v_cmp_lt_f32_e64 s[0:1], 0, v94
	s_nop 1
	v_cndmask_b32_e64 v94, v95, v219, s[0:1]
	v_mul_f32_e32 v95, 0x37800000, v94
	v_cndmask_b32_e32 v94, v94, v95, vcc
	v_cmp_class_f32_e32 vcc, v83, v179
	s_nop 1
	v_cndmask_b32_e32 v83, v94, v83, vcc
	v_max_f32_e32 v83, 0x2b8cbccc, v83
	v_div_scale_f32 v94, s[0:1], v83, v83, 1.0
	v_rcp_f32_e32 v95, v94
	s_nop 0
	v_fma_f32 v219, -v94, v95, 1.0
	v_fmac_f32_e32 v95, v219, v95
	v_div_scale_f32 v219, vcc, 1.0, v83, 1.0
	v_mul_f32_e32 v220, v219, v95
	v_fma_f32 v221, -v94, v220, v219
	v_fmac_f32_e32 v220, v221, v95
	v_fma_f32 v94, -v94, v220, v219
	v_div_fmas_f32 v94, v94, v95, v220
	v_lshlrev_b32_e32 v95, 10, v212
	v_cndmask_b32_e64 v212, v3, v1, s[6:7]
	s_waitcnt vmcnt(1)
	v_add_f32_e32 v76, v76, v212
	v_mul_f32_e32 v76, 0xbfb8aa3b, v76
	v_exp_f32_e32 v76, v76
	v_div_fixup_f32 v83, v94, v83, 1.0
	v_mul_f32_e32 v88, v88, v83
	v_lshrrev_b32_e32 v94, 8, v194
	v_add_f32_e32 v76, 1.0, v76
	v_div_scale_f32 v212, s[0:1], v76, v76, 1.0
	v_rcp_f32_e32 v219, v212
	v_and_b32_e32 v94, 0x3f0, v94
	v_fma_f32 v220, -v212, v219, 1.0
	v_fmac_f32_e32 v219, v220, v219
	v_div_scale_f32 v220, vcc, 1.0, v76, 1.0
	v_mul_f32_e32 v221, v220, v219
	v_fma_f32 v222, -v212, v221, v220
	v_fmac_f32_e32 v221, v222, v219
	v_fma_f32 v212, -v212, v221, v220
	v_div_fmas_f32 v212, v212, v219, v221
	v_div_fixup_f32 v76, v212, v76, 1.0
	v_cndmask_b32_e64 v212, v7, v5, s[6:7]
	s_waitcnt vmcnt(0)
	v_add_f32_e32 v72, v72, v212
	v_mul_f32_e32 v72, 0xbfb8aa3b, v72
	v_exp_f32_e32 v72, v72
	v_mul_f32_e32 v76, 0xbf1b459e, v76
	v_mul_f32_e32 v76, 0x3fb8aa3b, v76
	v_exp_f32_e32 v76, v76
	v_add_f32_e32 v72, 1.0, v72
	v_div_scale_f32 v212, s[0:1], v72, v72, 1.0
	v_rcp_f32_e32 v219, v212
	v_cvt_f16_f32_e32 v76, v76
	v_fma_f32 v220, -v212, v219, 1.0
	v_fmac_f32_e32 v219, v220, v219
	v_div_scale_f32 v220, vcc, 1.0, v72, 1.0
	v_mul_f32_e32 v221, v220, v219
	v_fma_f32 v222, -v212, v221, v220
	v_fmac_f32_e32 v221, v222, v219
	v_fma_f32 v212, -v212, v221, v220
	v_div_fmas_f32 v212, v212, v219, v221
	v_div_fixup_f32 v72, v212, v72, 1.0
	v_cvt_f16_f32_e64 v212, -v88
	v_fma_mixlo_f16 v88, v92, v88, 0
	v_fma_mixlo_f16 v92, v64, v210, v209
	v_cndmask_b32_e64 v64, v51, v49, s[6:7]
	v_cvt_pk_bf16_f32 v209, v64, s0
	v_mul_f32_e32 v64, v217, v80
	v_cvt_pk_bf16_f32 v210, v64, s0
	v_cndmask_b32_e64 v64, v15, v13, s[6:7]
	v_add_f32_e32 v64, v77, v64
	v_mul_f32_e32 v64, 0xbfb8aa3b, v64
	v_exp_f32_e32 v64, v64
	v_mul_f32_e32 v72, 0xbf1b459e, v72
	v_mul_f32_e32 v72, 0x3fb8aa3b, v72
	v_exp_f32_e32 v72, v72
	v_add_f32_e32 v64, 1.0, v64
	v_div_scale_f32 v77, s[0:1], v64, v64, 1.0
	v_rcp_f32_e32 v214, v77
	v_cvt_f16_f32_e32 v72, v72
	v_fma_f32 v216, -v77, v214, 1.0
	v_fmac_f32_e32 v214, v216, v214
	v_div_scale_f32 v216, vcc, 1.0, v64, 1.0
	v_mul_f32_e32 v217, v216, v214
	v_fma_f32 v218, -v77, v217, v216
	v_fmac_f32_e32 v217, v218, v214
	v_fma_f32 v77, -v77, v217, v216
	v_div_fmas_f32 v77, v77, v214, v217
	v_div_fixup_f32 v64, v77, v64, 1.0
	v_cndmask_b32_e64 v77, v19, v17, s[6:7]
	v_add_f32_e32 v73, v73, v77
	v_mul_f32_e32 v73, 0xbfb8aa3b, v73
	v_exp_f32_e32 v73, v73
	v_mul_f32_e32 v64, 0xbf1b459e, v64
	v_mul_f32_e32 v64, 0x3fb8aa3b, v64
	v_exp_f32_e32 v64, v64
	v_add_f32_e32 v73, 1.0, v73
	v_div_scale_f32 v77, s[0:1], v73, v73, 1.0
	v_rcp_f32_e32 v214, v77
	v_cvt_f16_f32_sdwa v64, v64 dst_sel:WORD_1 dst_unused:UNUSED_PAD src0_sel:DWORD
	v_fma_f32 v216, -v77, v214, 1.0
	v_fmac_f32_e32 v214, v216, v214
	v_div_scale_f32 v216, vcc, 1.0, v73, 1.0
	v_mul_f32_e32 v217, v216, v214
	v_fma_f32 v218, -v77, v217, v216
	v_fmac_f32_e32 v217, v218, v214
	v_fma_f32 v77, -v77, v217, v216
	v_div_fmas_f32 v77, v77, v214, v217
	v_div_fixup_f32 v73, v77, v73, 1.0
	v_mul_f32_e32 v77, v89, v83
	v_cvt_f16_f32_sdwa v89, -v77 dst_sel:WORD_1 dst_unused:UNUSED_PAD src0_sel:DWORD
	v_fma_mixlo_f16 v77, v93, v77, 0
	v_fma_mixlo_f16 v93, v65, v204, v203
	v_cndmask_b32_e64 v65, v55, v53, s[6:7]
	v_cvt_pk_bf16_f32 v203, v65, s0
	v_mul_f32_e32 v65, v213, v80
	v_cvt_pk_bf16_f32 v204, v65, s0
	v_cndmask_b32_e64 v65, v27, v25, s[6:7]
	v_add_f32_e32 v65, v78, v65
	v_mul_f32_e32 v65, 0xbfb8aa3b, v65
; DEVINL u16 f2bf(float a) { return (u16)(pk2(a, 0.f) & 0xffffu); }
; DEVINL float sigm(float x) { return 1.f / (1.f + __expf(-x)); }
; DEVINL void rw_prep_unit(const Params& p, int unit) {
;     ...
;         for (int n = 0; n < 4; ++n) {
;           float wf = __expf(-0.606531f * sigm(w0f[n] + sel4(awf[n], j)));
;           float wb = __expf(-0.606531f * sigm(w0b[n] + sel4(awb[n], j)));
;           float kkn = kkv[n] * inv;
;           hwf[n] = f2h(wf); hwb[n] = f2h(wb); ha[n] = f2h(-kkn); hb[n] = f2h(kkn * av[n]);
;           hk[n] = f2h(pk[n]); hr[n] = f2h(pr[n]); hv[n] = f2h(pv[n]);
;           bg[n] = f2bf(sel4(ag[n], j)); bbn[n] = f2bf(dot * pv[n]);
;         }
;         char* rb = ws + O_REC + (reco + (unsigned)l15 * 64u);
;         *(uint4*)(rb) = make_uint4(hwf[0] | (hwf[1] << 16), hwf[2] | (hwf[3] << 16), hwb[0] | (hwb[1] << 16), hwb[2] | (hwb[3] << 16));
;         *(uint4*)(rb + 16) = make_uint4(ha[0] | (ha[1] << 16), ha[2] | (ha[3] << 16), hb[0] | (hb[1] << 16), hb[2] | (hb[3] << 16));
;         *(uint4*)(rb + 32) = make_uint4(hk[0] | (hk[1] << 16), hk[2] | (hk[3] << 16), hr[0] | (hr[1] << 16), hr[2] | (hr[3] << 16));
;         *(uint2*)(rb + 48) = make_uint2(hv[0] | (hv[1] << 16), hv[2] | (hv[3] << 16));
;         *(uint2*)(ws + O_GRW + tco) = make_uint2(bg[0] | (bg[1] << 16), bg[2] | (bg[3] << 16));
;         *(uint2*)(ws + O_BONUS + tco) = make_uint2(bbn[0] | (bbn[1] << 16), bbn[2] | (bbn[3] << 16));
	v_exp_f32_e32 v65, v65
	v_mul_f32_e32 v73, 0xbf1b459e, v73
	v_mul_f32_e32 v73, 0x3fb8aa3b, v73
	v_exp_f32_e32 v73, v73
	v_add_f32_e32 v65, 1.0, v65
	v_div_scale_f32 v78, s[0:1], v65, v65, 1.0
	v_rcp_f32_e32 v206, v78
	v_cvt_f16_f32_sdwa v73, v73 dst_sel:WORD_1 dst_unused:UNUSED_PAD src0_sel:DWORD
	v_or_b32_e32 v64, v64, v76
	v_fma_f32 v211, -v78, v206, 1.0
	v_fmac_f32_e32 v206, v211, v206
	v_div_scale_f32 v211, vcc, 1.0, v65, 1.0
	v_mul_f32_e32 v213, v211, v206
	v_fma_f32 v214, -v78, v213, v211
	v_fmac_f32_e32 v213, v214, v206
	v_fma_f32 v78, -v78, v213, v211
	v_div_fmas_f32 v78, v78, v206, v213
	v_div_fixup_f32 v65, v78, v65, 1.0
	v_cndmask_b32_e64 v78, v31, v29, s[6:7]
	v_add_f32_e32 v74, v74, v78
	v_mul_f32_e32 v74, 0xbfb8aa3b, v74
	v_exp_f32_e32 v74, v74
	v_mul_f32_e32 v65, 0xbf1b459e, v65
	v_mul_f32_e32 v65, 0x3fb8aa3b, v65
	v_exp_f32_e32 v65, v65
	v_add_f32_e32 v74, 1.0, v74
	v_div_scale_f32 v78, s[0:1], v74, v74, 1.0
	v_rcp_f32_e32 v206, v78
	v_cvt_f16_f32_e32 v65, v65
	v_fma_f32 v211, -v78, v206, 1.0
	v_fmac_f32_e32 v206, v211, v206
	v_div_scale_f32 v211, vcc, 1.0, v74, 1.0
	v_mul_f32_e32 v213, v211, v206
	v_fma_f32 v214, -v78, v213, v211
	v_fmac_f32_e32 v213, v214, v206
	v_fma_f32 v78, -v78, v213, v211
	v_div_fmas_f32 v78, v78, v206, v213
	v_div_fixup_f32 v74, v78, v74, 1.0
	v_mul_f32_e32 v78, v90, v83
	v_cvt_f16_f32_e64 v90, -v78
	v_fma_mixlo_f16 v78, v81, v78, 0
	v_fma_mixlo_f16 v81, v200, v86, 0
	v_fma_mixlo_f16 v86, v66, v198, v197
	v_cndmask_b32_e64 v66, v59, v57, s[6:7]
	v_cvt_pk_bf16_f32 v197, v66, s0
	v_mul_f32_e32 v66, v207, v80
	v_cvt_pk_bf16_f32 v198, v66, s0
	v_cndmask_b32_e64 v66, v39, v37, s[6:7]
	v_add_f32_e32 v66, v79, v66
	v_mul_f32_e32 v66, 0xbfb8aa3b, v66
	v_exp_f32_e32 v66, v66
	v_mul_f32_e32 v74, 0xbf1b459e, v74
	v_mul_f32_e32 v74, 0x3fb8aa3b, v74
	v_exp_f32_e32 v74, v74
	v_add_f32_e32 v66, 1.0, v66
	v_div_scale_f32 v79, s[0:1], v66, v66, 1.0
	v_rcp_f32_e32 v200, v79
	v_cvt_f16_f32_e32 v74, v74
	v_fma_f32 v205, -v79, v200, 1.0
	v_fmac_f32_e32 v200, v205, v200
	v_div_scale_f32 v205, vcc, 1.0, v66, 1.0
	v_mul_f32_e32 v206, v205, v200
	v_fma_f32 v207, -v79, v206, v205
	v_fmac_f32_e32 v206, v207, v200
	v_fma_f32 v79, -v79, v206, v205
	v_div_fmas_f32 v79, v79, v200, v206
	v_div_fixup_f32 v66, v79, v66, 1.0
	v_cndmask_b32_e64 v79, v43, v41, s[6:7]
	v_add_f32_e32 v75, v75, v79
	v_mul_f32_e32 v75, 0xbfb8aa3b, v75
	v_exp_f32_e32 v75, v75
	v_mul_f32_e32 v66, 0xbf1b459e, v66
	v_mul_f32_e32 v66, 0x3fb8aa3b, v66
	v_exp_f32_e32 v66, v66
	v_add_f32_e32 v75, 1.0, v75
	v_div_scale_f32 v79, s[0:1], v75, v75, 1.0
	v_rcp_f32_e32 v200, v79
	v_cvt_f16_f32_sdwa v66, v66 dst_sel:WORD_1 dst_unused:UNUSED_PAD src0_sel:DWORD
	v_fma_f32 v205, -v79, v200, 1.0
	v_fmac_f32_e32 v200, v205, v200
	v_div_scale_f32 v205, vcc, 1.0, v75, 1.0
	v_mul_f32_e32 v206, v205, v200
	v_fma_f32 v207, -v79, v206, v205
	v_fmac_f32_e32 v206, v207, v200
	v_fma_f32 v79, -v79, v206, v205
	v_div_fmas_f32 v79, v79, v200, v206
	v_div_fixup_f32 v75, v79, v75, 1.0
	v_mul_f32_e32 v75, 0xbf1b459e, v75
	v_mul_f32_e32 v75, 0x3fb8aa3b, v75
	v_exp_f32_e32 v75, v75
	v_mul_f32_e32 v79, v91, v83
	v_cvt_f16_f32_sdwa v83, -v79 dst_sel:WORD_1 dst_unused:UNUSED_PAD src0_sel:DWORD
	v_fma_mixlo_f16 v79, v82, v79, 0
	v_cvt_f16_f32_sdwa v75, v75 dst_sel:WORD_1 dst_unused:UNUSED_PAD src0_sel:DWORD
	v_fma_mixlo_f16 v82, v196, v87, 0
	v_fma_mixlo_f16 v87, v67, v195, v96
	v_cndmask_b32_e64 v67, v63, v61, s[6:7]
	v_cvt_pk_bf16_f32 v91, v67, s0
	v_mul_f32_e32 v67, v201, v80
	v_cvt_pk_bf16_f32 v80, v67, s0
	v_add_lshl_u32 v67, v94, v191, 22
	v_or3_b32 v95, v67, v95, v186
	v_or_b32_e32 v65, v66, v65
	v_or_b32_e32 v67, v75, v74
	v_or_b32_e32 v66, v73, v72
	global_store_dwordx4 v95, v[64:67], s[36:37]
	v_lshlrev_b32_e32 v72, 16, v77
	v_lshl_add_u32 v94, v194, 11, v178
	v_lshlrev_b32_e32 v66, 16, v79
	v_or_b32_e32 v65, v83, v90
	v_or_b32_e32 v64, v89, v212
	v_or_b32_sdwa v67, v66, v78 dst_sel:DWORD dst_unused:UNUSED_PAD src0_sel:DWORD src1_sel:WORD_0
	v_or_b32_sdwa v66, v72, v88 dst_sel:DWORD dst_unused:UNUSED_PAD src0_sel:DWORD src1_sel:WORD_0
	global_store_dwordx4 v95, v[64:67], s[36:37] offset:256
	v_lshlrev_b32_e32 v72, 16, v93
	s_nop 0
	v_lshlrev_b32_e32 v64, 16, v82
	v_lshlrev_b32_e32 v66, 16, v85
	v_lshlrev_b32_e32 v67, 16, v87
	v_or_b32_sdwa v65, v64, v81 dst_sel:DWORD dst_unused:UNUSED_PAD src0_sel:DWORD src1_sel:WORD_0
	v_or_b32_sdwa v64, v66, v84 dst_sel:DWORD dst_unused:UNUSED_PAD src0_sel:DWORD src1_sel:WORD_0
	v_or_b32_sdwa v67, v67, v86 dst_sel:DWORD dst_unused:UNUSED_PAD src0_sel:DWORD src1_sel:WORD_0
	v_or_b32_sdwa v66, v72, v92 dst_sel:DWORD dst_unused:UNUSED_PAD src0_sel:DWORD src1_sel:WORD_0
	global_store_dwordx4 v95, v[64:67], s[36:37] offset:512
	s_nop 1
	v_lshlrev_b32_e32 v64, 16, v71
	v_lshlrev_b32_e32 v66, 16, v69
	v_or_b32_sdwa v65, v64, v70 dst_sel:DWORD dst_unused:UNUSED_PAD src0_sel:DWORD src1_sel:WORD_0
	v_or_b32_sdwa v64, v66, v68 dst_sel:DWORD dst_unused:UNUSED_PAD src0_sel:DWORD src1_sel:WORD_0
	global_store_dwordx2 v95, v[64:65], s[36:37] offset:768
	v_lshlrev_b32_e32 v64, 16, v91
	v_lshlrev_b32_e32 v66, 16, v203
	v_or_b32_sdwa v65, v64, v197 dst_sel:DWORD dst_unused:UNUSED_PAD src0_sel:DWORD src1_sel:WORD_0
	v_or_b32_sdwa v64, v66, v209 dst_sel:DWORD dst_unused:UNUSED_PAD src0_sel:DWORD src1_sel:WORD_0
	global_store_dwordx2 v94, v[64:65], s[38:39]
	v_lshlrev_b32_e32 v64, 16, v80
	v_lshlrev_b32_e32 v66, 16, v204
	v_or_b32_sdwa v65, v64, v198 dst_sel:DWORD dst_unused:UNUSED_PAD src0_sel:DWORD src1_sel:WORD_0
	v_or_b32_sdwa v64, v66, v210 dst_sel:DWORD dst_unused:UNUSED_PAD src0_sel:DWORD src1_sel:WORD_0
	global_store_dwordx2 v94, v[64:65], s[70:71]
	s_cbranch_scc0 .LBB0_383
	s_mov_b32 s6, 16
	s_mov_b64 s[0:1], 0
	s_and_b64 vcc, exec, s[82:83]
	s_cbranch_vccz .LBB0_382
	s_mov_b32 s6, 1
	s_and_b64 vcc, exec, s[80:81]
	s_cbranch_vccz .LBB0_381
	s_add_i32 s51, s51, s94
	s_add_i32 s3, s3, s42
	s_cmpk_lt_i32 s51, 0x100
	s_barrier
	s_cbranch_scc1 .LBB0_336

; template <int DIR>
; DEVINL void rwkv_scan_dir(const Params& p, int task, int lane, int wave) {
;   const int b = (task >> 8) & 1, head = (task >> 4) & 15, rg = task & 15;
;   const int seg = lane & 15, rl = lane >> 4, row = rg * 4 + rl;
;   constexpr int DIST = 24;
;   constexpr int WOFS = DIR ? 8 : 0;
;   const char* recbase = p.ws + O_REC + ((long)(b * 16 + head) * 4096) * 1024 + lane * 16;
;   const unsigned ring_lds = (unsigned)(unsigned long)(__attribute__((address_space(3))) char*)(dynsmem + wave * 32768);
;   const unsigned ring_u = __builtin_amdgcn_readfirstlane(ring_lds);
;   const unsigned a_seg = ring_lds + seg * 64;
;   const unsigned a_v = ring_lds + (row >> 2) * 64 + 48 + (row & 3) * 2;
;   u16* yo = (u16*)(p.ws + (DIR ? O_YB : O_YSUM)) + ((long)b * 4096) * 1024 + head * 64 + row;
.LBB0_481:
	s_andn2_saveexec_b64 s[0:1], s[20:21]
	s_cbranch_execz .LBB0_498
	v_and_b32_e32 v3, 15, v0
	v_lshrrev_b32_e32 v4, 4, v0
	v_lshlrev_b32_e32 v5, 4, v0
	v_readfirstlane_b32 s6, v2
	s_nop 3
	s_lshl_b32 s7, s38, 2
	s_add_u32 s7, s7, s6
	s_lshl_b32 s8, s94, 2
	s_mov_b32 s48, 0xaaaaaaaa
	s_mov_b32 s49, 0xaaaaaaaa
	s_mov_b32 s50, 0xcccccccc
	s_mov_b32 s51, 0xcccccccc
	v_mov_b32_e32 v9, 0x20010
	s_lshl_b32 s3, s6, 2
	s_add_u32 s3, s3, 0x20010
	v_mov_b32_e32 v23, s3
	v_add_u32_e32 v68, 16, v23
	s_mov_b32 s15, 0
